# on top of v23: s_setprio 0 issued before the last MFMA of each compute interval instead of after it
# baseline (speedup 1.0000x reference)
; #define PG8_STAGE(bufoff, gbase) do { _Pragma("unroll") for (int _i = 0; _i < 2; ++_i) \
;         __builtin_amdgcn_global_load_lds((const unsigned*)((const char*)(gbase) + voff[_i]), (LAS unsigned*)(lds + (bufoff) + ldsw + _i * 8192), 16, 0, 0); } while (0)
; #define PG8_LDA(dst, b, h) do { _Pragma("unroll") for (int m = 0; m < 4; ++m) _Pragma("unroll") for (int k = 0; k < 2; ++k) dst[m][k] = *(const LAS bf16x8*)(lds + PG8_SA(b, h) + aoff + m * 2048 + k * 1024); } while (0)
; #define PG8_LDB(dst, b, h) do { _Pragma("unroll") for (int n = 0; n < 2; ++n) _Pragma("unroll") for (int k = 0; k < 2; ++k) dst[n][k] = *(const LAS bf16x8*)(lds + PG8_SB(b, h) + boff + n * 2048 + k * 1024); } while (0)
; #define PG8_MMA(ai, bj, At, Bt) do { __builtin_amdgcn_s_setprio(1); _Pragma("unroll") for (int m = 0; m < 4; ++m) _Pragma("unroll") for (int n = 0; n < 2; ++n) _Pragma("unroll") for (int k = 0; k < 2; ++k) \
;         acc[ai][bj][m][n] = __builtin_amdgcn_mfma_f32_16x16x32_bf16(Bt[n][k], At[m][k], acc[ai][bj][m][n], 0, 0, 0); __builtin_amdgcn_s_setprio(0); } while (0)
; #define PG8_WAIT_L(n) asm volatile("s_waitcnt lgkmcnt(" #n ")" ::: "memory")
; #define PG8_BAR __builtin_amdgcn_s_barrier()
; #define PG8_SCHED __builtin_amdgcn_sched_barrier(0)
; template <class Epi>
; DI void gemm_phase(LAS unsigned char* lds, const Gemm g, const StaticOrder& S, const Epi& E) {
;     ...
;         for (int t = 0; t < nt; t += 2) {
;             const bool last = (t == nt - 2);
;             const char* a1 = cA + (size_t)(t + 1) * kstep;
;             const char* a2 = last ? nA : cA + (size_t)(t + 2) * kstep; const char* b2 = last ? nB : cB + (size_t)(t + 2) * kstep;
;             const char* a3 = a2 + kstep; const char* b3 = b2 + kstep;
;             PG8_LDB(B0, 0, 0); PG8_SCHED; PG8_LDA(At, 0, 0); PG8_STAGE(PG8_SA(1, 1), a1 + hstep);
;             PG8_WAIT_L(8); PG8_BAR; PG8_WAIT_L(0); PG8_MMA(0, 0, At, B0); PG8_BAR; PG8_SCHED;
;             PG8_LDB(B1, 0, 1); PG8_STAGE(PG8_SB(0, 0), b2);
;             PG8_BAR; PG8_WAIT_L(0); PG8_MMA(0, 1, At, B1); PG8_BAR;
;             PG8_LDA(At, 0, 1); PG8_STAGE(PG8_SA(0, 0), a2);
;             PG8_BAR; PG8_WAIT_L(0); PG8_MMA(1, 0, At, B0); PG8_BAR; PG8_SCHED;
.LBB0_37:
	s_add_u32 s20, s18, 0xfff80080
	s_addc_u32 s21, s19, -1
	s_add_i32 s39, 0, 0x10000
	ds_read_b128 v[138:141], v135
	ds_read_b128 v[142:145], v135 offset:1024
	ds_read_b128 v[146:149], v135 offset:2048
	ds_read_b128 v[150:153], v135 offset:3072
	s_cmp_eq_u32 s38, 28
	s_cselect_b32 s23, s4, s21
	s_cselect_b32 s22, s5, s20
	s_cselect_b32 s21, s9, s37
	s_cselect_b32 s20, s11, s33
	v_lshl_add_u64 v[154:155], s[18:19], 0, v[130:131]
	s_add_i32 m0, s28, 0xc000
	ds_read_b128 v[186:189], v137
	ds_read_b128 v[190:193], v137 offset:1024
	ds_read_b128 v[194:197], v137 offset:2048
	ds_read_b128 v[198:201], v137 offset:3072
	ds_read_b128 v[202:205], v137 offset:4096
	ds_read_b128 v[206:209], v137 offset:5120
	ds_read_b128 v[210:213], v137 offset:6144
	ds_read_b128 v[214:217], v137 offset:7168
	global_load_lds_dwordx4 v[154:155], off
	v_lshl_add_u64 v[154:155], s[18:19], 0, v[132:133]
	s_add_i32 m0, s28, 0xe000
	s_nop 0
	global_load_lds_dwordx4 v[154:155], off
	s_waitcnt lgkmcnt(8)
	s_setprio 1
	s_barrier
	s_waitcnt lgkmcnt(0)
	v_mfma_f32_16x16x32_bf16 v[124:127], v[138:141], v[186:189], v[124:127]
	v_mfma_f32_16x16x32_bf16 v[120:123], v[146:149], v[186:189], v[120:123]
	v_mfma_f32_16x16x32_bf16 v[108:111], v[138:141], v[194:197], v[108:111]
	v_mfma_f32_16x16x32_bf16 v[104:107], v[146:149], v[194:197], v[104:107]
	v_mfma_f32_16x16x32_bf16 v[92:95], v[138:141], v[202:205], v[92:95]
	v_mfma_f32_16x16x32_bf16 v[88:91], v[146:149], v[202:205], v[88:91]
	v_mfma_f32_16x16x32_bf16 v[76:79], v[138:141], v[210:213], v[76:79]
	v_mfma_f32_16x16x32_bf16 v[72:75], v[146:149], v[210:213], v[72:75]
	v_mfma_f32_16x16x32_bf16 v[124:127], v[142:145], v[190:193], v[124:127]
	v_mfma_f32_16x16x32_bf16 v[120:123], v[150:153], v[190:193], v[120:123]
	v_mfma_f32_16x16x32_bf16 v[108:111], v[142:145], v[198:201], v[108:111]
	v_mfma_f32_16x16x32_bf16 v[104:107], v[150:153], v[198:201], v[104:107]
	v_mfma_f32_16x16x32_bf16 v[92:95], v[142:145], v[206:209], v[92:95]
	v_mfma_f32_16x16x32_bf16 v[88:91], v[150:153], v[206:209], v[88:91]
	v_mfma_f32_16x16x32_bf16 v[76:79], v[142:145], v[214:217], v[76:79]
	s_setprio 0
	v_mfma_f32_16x16x32_bf16 v[72:75], v[150:153], v[214:217], v[72:75]
	s_barrier
	s_add_i32 s42, 0, 0x14000
	s_add_i32 s39, s39, s27
	ds_read_b128 v[226:229], v135 offset:16384
	ds_read_b128 v[230:233], v135 offset:17408
	ds_read_b128 v[234:237], v135 offset:18432
	ds_read_b128 v[238:241], v135 offset:19456
	v_lshl_add_u64 v[154:155], s[20:21], 0, v[158:159]
	s_mov_b32 m0, s39
	v_lshl_add_u64 v[218:219], s[20:21], 0, v[128:129]
	global_load_lds_dwordx4 v[154:155], off
	s_add_i32 m0, s39, 0x2000
	s_nop 0
	global_load_lds_dwordx4 v[218:219], off
	s_waitcnt lgkmcnt(0)
	s_setprio 1
	s_barrier
	v_mfma_f32_16x16x32_bf16 v[116:119], v[226:229], v[186:189], v[116:119]
	v_mfma_f32_16x16x32_bf16 v[112:115], v[234:237], v[186:189], v[112:115]
	v_mfma_f32_16x16x32_bf16 v[100:103], v[226:229], v[194:197], v[100:103]
	v_mfma_f32_16x16x32_bf16 v[96:99], v[234:237], v[194:197], v[96:99]
	v_mfma_f32_16x16x32_bf16 v[84:87], v[226:229], v[202:205], v[84:87]
	v_mfma_f32_16x16x32_bf16 v[80:83], v[234:237], v[202:205], v[80:83]
	v_mfma_f32_16x16x32_bf16 v[68:71], v[226:229], v[210:213], v[68:71]
	v_mfma_f32_16x16x32_bf16 v[64:67], v[234:237], v[210:213], v[64:67]
	v_mfma_f32_16x16x32_bf16 v[116:119], v[230:233], v[190:193], v[116:119]
	s_mov_b32 m0, s28
	v_mfma_f32_16x16x32_bf16 v[112:115], v[238:241], v[190:193], v[112:115]
	v_lshl_add_u64 v[220:221], s[22:23], 0, v[158:159]
	v_mfma_f32_16x16x32_bf16 v[100:103], v[230:233], v[198:201], v[100:103]
	v_mfma_f32_16x16x32_bf16 v[96:99], v[238:241], v[198:201], v[96:99]
	v_mfma_f32_16x16x32_bf16 v[84:87], v[230:233], v[206:209], v[84:87]
	v_mfma_f32_16x16x32_bf16 v[80:83], v[238:241], v[206:209], v[80:83]
	v_mfma_f32_16x16x32_bf16 v[68:71], v[230:233], v[214:217], v[68:71]
	s_setprio 0
	v_mfma_f32_16x16x32_bf16 v[64:67], v[238:241], v[214:217], v[64:67]
	s_barrier
	ds_read_b128 v[186:189], v137 offset:16384
	ds_read_b128 v[190:193], v137 offset:17408
	ds_read_b128 v[194:197], v137 offset:18432
	ds_read_b128 v[198:201], v137 offset:19456
	ds_read_b128 v[202:205], v137 offset:20480
	ds_read_b128 v[206:209], v137 offset:21504
	ds_read_b128 v[210:213], v137 offset:22528
	ds_read_b128 v[214:217], v137 offset:23552
	global_load_lds_dwordx4 v[220:221], off
	v_lshl_add_u64 v[242:243], s[22:23], 0, v[128:129]
	s_mov_b32 m0, s29
	s_nop 0
	global_load_lds_dwordx4 v[242:243], off
	s_waitcnt lgkmcnt(0)
	s_setprio 1
	s_barrier
	v_mfma_f32_16x16x32_bf16 v[60:63], v[138:141], v[186:189], v[60:63]
	v_mfma_f32_16x16x32_bf16 v[56:59], v[146:149], v[186:189], v[56:59]
	v_mfma_f32_16x16x32_bf16 v[44:47], v[138:141], v[194:197], v[44:47]
	v_mfma_f32_16x16x32_bf16 v[40:43], v[146:149], v[194:197], v[40:43]
	v_mfma_f32_16x16x32_bf16 v[28:31], v[138:141], v[202:205], v[28:31]
	v_mfma_f32_16x16x32_bf16 v[24:27], v[146:149], v[202:205], v[24:27]
	v_mfma_f32_16x16x32_bf16 v[12:15], v[138:141], v[210:213], v[12:15]
	v_mfma_f32_16x16x32_bf16 v[8:11], v[146:149], v[210:213], v[8:11]
	v_mfma_f32_16x16x32_bf16 v[60:63], v[142:145], v[190:193], v[60:63]
	v_mfma_f32_16x16x32_bf16 v[56:59], v[150:153], v[190:193], v[56:59]
	v_mfma_f32_16x16x32_bf16 v[44:47], v[142:145], v[198:201], v[44:47]
	v_mfma_f32_16x16x32_bf16 v[40:43], v[150:153], v[198:201], v[40:43]
	v_mfma_f32_16x16x32_bf16 v[28:31], v[142:145], v[206:209], v[28:31]
	v_mfma_f32_16x16x32_bf16 v[24:27], v[150:153], v[206:209], v[24:27]
	v_mfma_f32_16x16x32_bf16 v[12:15], v[142:145], v[214:217], v[12:15]
	s_setprio 0
	v_mfma_f32_16x16x32_bf16 v[8:11], v[150:153], v[214:217], v[8:11]
	s_barrier
; #define PG8_STAGE(bufoff, gbase) do { _Pragma("unroll") for (int _i = 0; _i < 2; ++_i) \
;         __builtin_amdgcn_global_load_lds((const unsigned*)((const char*)(gbase) + voff[_i]), (LAS unsigned*)(lds + (bufoff) + ldsw + _i * 8192), 16, 0, 0); } while (0)
; #define PG8_LDA(dst, b, h) do { _Pragma("unroll") for (int m = 0; m < 4; ++m) _Pragma("unroll") for (int k = 0; k < 2; ++k) dst[m][k] = *(const LAS bf16x8*)(lds + PG8_SA(b, h) + aoff + m * 2048 + k * 1024); } while (0)
; #define PG8_LDB(dst, b, h) do { _Pragma("unroll") for (int n = 0; n < 2; ++n) _Pragma("unroll") for (int k = 0; k < 2; ++k) dst[n][k] = *(const LAS bf16x8*)(lds + PG8_SB(b, h) + boff + n * 2048 + k * 1024); } while (0)
; #define PG8_MMA(ai, bj, At, Bt) do { __builtin_amdgcn_s_setprio(1); _Pragma("unroll") for (int m = 0; m < 4; ++m) _Pragma("unroll") for (int n = 0; n < 2; ++n) _Pragma("unroll") for (int k = 0; k < 2; ++k) \
;         acc[ai][bj][m][n] = __builtin_amdgcn_mfma_f32_16x16x32_bf16(Bt[n][k], At[m][k], acc[ai][bj][m][n], 0, 0, 0); __builtin_amdgcn_s_setprio(0); } while (0)
; #define PG8_WAIT_V(n) asm volatile("s_waitcnt vmcnt(" #n ")" ::: "memory")
; #define PG8_WAIT_L(n) asm volatile("s_waitcnt lgkmcnt(" #n ")" ::: "memory")
; #define PG8_BAR __builtin_amdgcn_s_barrier()
; #define PG8_SCHED __builtin_amdgcn_sched_barrier(0)
; template <class Epi>
; DI void gemm_phase(LAS unsigned char* lds, const Gemm g, const StaticOrder& S, const Epi& E) {
;     ...
;             PG8_STAGE(PG8_SB(0, 1), b2 + hstep);
;             PG8_WAIT_V(6); PG8_BAR; PG8_MMA(1, 1, At, B1); PG8_BAR;
;             PG8_LDB(B0, 1, 0); PG8_SCHED; PG8_LDA(At, 1, 0); PG8_STAGE(PG8_SA(0, 1), a2 + hstep);
;             PG8_WAIT_L(8); PG8_BAR; PG8_WAIT_L(0); PG8_MMA(0, 0, At, B0); PG8_BAR; PG8_SCHED;
;             PG8_LDB(B1, 1, 1); PG8_STAGE(PG8_SB(1, 0), b3);
	s_add_u32 s40, s20, 0x80000
	s_addc_u32 s41, s21, 0
	s_add_i32 s39, s42, s27
	v_lshl_add_u64 v[138:139], s[40:41], 0, v[158:159]
	s_mov_b32 m0, s39
	s_nop 0
	global_load_lds_dwordx4 v[138:139], off
	v_lshl_add_u64 v[138:139], s[40:41], 0, v[128:129]
	s_add_i32 m0, s39, 0x2000
	s_nop 0
	global_load_lds_dwordx4 v[138:139], off
	s_waitcnt vmcnt(6)
	s_setprio 1
	s_barrier
	v_mfma_f32_16x16x32_bf16 v[52:55], v[226:229], v[186:189], v[52:55]
	v_mfma_f32_16x16x32_bf16 v[48:51], v[234:237], v[186:189], v[48:51]
	v_mfma_f32_16x16x32_bf16 v[36:39], v[226:229], v[194:197], v[36:39]
	v_mfma_f32_16x16x32_bf16 v[32:35], v[234:237], v[194:197], v[32:35]
	v_mfma_f32_16x16x32_bf16 v[20:23], v[226:229], v[202:205], v[20:23]
	v_mfma_f32_16x16x32_bf16 v[16:19], v[234:237], v[202:205], v[16:19]
	v_mfma_f32_16x16x32_bf16 v[4:7], v[226:229], v[210:213], v[4:7]
	v_mfma_f32_16x16x32_bf16 v[0:3], v[234:237], v[210:213], v[0:3]
	v_mfma_f32_16x16x32_bf16 v[52:55], v[230:233], v[190:193], v[52:55]
	s_add_i32 s39, 0, 0x18000
	v_mfma_f32_16x16x32_bf16 v[48:51], v[238:241], v[190:193], v[48:51]
	v_mfma_f32_16x16x32_bf16 v[36:39], v[230:233], v[198:201], v[36:39]
	v_mfma_f32_16x16x32_bf16 v[32:35], v[238:241], v[198:201], v[32:35]
	v_mfma_f32_16x16x32_bf16 v[20:23], v[230:233], v[206:209], v[20:23]
	v_mfma_f32_16x16x32_bf16 v[16:19], v[238:241], v[206:209], v[16:19]
	v_mfma_f32_16x16x32_bf16 v[4:7], v[230:233], v[214:217], v[4:7]
	s_setprio 0
	v_mfma_f32_16x16x32_bf16 v[0:3], v[238:241], v[214:217], v[0:3]
	s_barrier
	ds_read_b128 v[138:141], v135 offset:32768
	ds_read_b128 v[142:145], v135 offset:33792
	ds_read_b128 v[146:149], v135 offset:34816
	ds_read_b128 v[150:153], v135 offset:35840
	s_add_u32 s22, s22, 0x80000
	s_addc_u32 s23, s23, 0
	s_mov_b32 m0, s30
	v_lshl_add_u64 v[226:227], s[22:23], 0, v[158:159]
	ds_read_b128 v[186:189], v137 offset:32768
	ds_read_b128 v[190:193], v137 offset:33792
	ds_read_b128 v[194:197], v137 offset:34816
	ds_read_b128 v[198:201], v137 offset:35840
	ds_read_b128 v[202:205], v137 offset:36864
	ds_read_b128 v[206:209], v137 offset:37888
	ds_read_b128 v[210:213], v137 offset:38912
	ds_read_b128 v[214:217], v137 offset:39936
	global_load_lds_dwordx4 v[226:227], off
	v_lshl_add_u64 v[226:227], s[22:23], 0, v[128:129]
	s_mov_b32 m0, s31
	s_nop 0
	global_load_lds_dwordx4 v[226:227], off
	s_waitcnt lgkmcnt(8)
	s_setprio 1
	s_barrier
	s_waitcnt lgkmcnt(0)
	v_mfma_f32_16x16x32_bf16 v[124:127], v[138:141], v[186:189], v[124:127]
	v_mfma_f32_16x16x32_bf16 v[120:123], v[146:149], v[186:189], v[120:123]
	v_mfma_f32_16x16x32_bf16 v[108:111], v[138:141], v[194:197], v[108:111]
	v_mfma_f32_16x16x32_bf16 v[104:107], v[146:149], v[194:197], v[104:107]
	v_mfma_f32_16x16x32_bf16 v[92:95], v[138:141], v[202:205], v[92:95]
	v_mfma_f32_16x16x32_bf16 v[88:91], v[146:149], v[202:205], v[88:91]
	v_mfma_f32_16x16x32_bf16 v[76:79], v[138:141], v[210:213], v[76:79]
	v_mfma_f32_16x16x32_bf16 v[72:75], v[146:149], v[210:213], v[72:75]
	v_mfma_f32_16x16x32_bf16 v[124:127], v[142:145], v[190:193], v[124:127]
	v_mfma_f32_16x16x32_bf16 v[120:123], v[150:153], v[190:193], v[120:123]
	v_mfma_f32_16x16x32_bf16 v[108:111], v[142:145], v[198:201], v[108:111]
	v_mfma_f32_16x16x32_bf16 v[104:107], v[150:153], v[198:201], v[104:107]
	v_mfma_f32_16x16x32_bf16 v[92:95], v[142:145], v[206:209], v[92:95]
	v_mfma_f32_16x16x32_bf16 v[88:91], v[150:153], v[206:209], v[88:91]
	v_mfma_f32_16x16x32_bf16 v[76:79], v[142:145], v[214:217], v[76:79]
	s_setprio 0
	v_mfma_f32_16x16x32_bf16 v[72:75], v[150:153], v[214:217], v[72:75]
	s_barrier
	s_add_i32 s22, 0, 0x1c000
	s_add_i32 s23, s39, s27
	v_lshl_add_u64 v[154:155], v[154:155], 0, s[94:95]
	s_mov_b32 m0, s23
	ds_read_b128 v[226:229], v135 offset:49152
	ds_read_b128 v[230:233], v135 offset:50176
	ds_read_b128 v[234:237], v135 offset:51200
	ds_read_b128 v[238:241], v135 offset:52224
	global_load_lds_dwordx4 v[154:155], off
	v_lshl_add_u64 v[154:155], v[218:219], 0, s[94:95]
	s_add_i32 m0, s23, 0x2000
	s_nop 0
	global_load_lds_dwordx4 v[154:155], off
	s_waitcnt lgkmcnt(0)
	s_setprio 1
	s_barrier
	v_mfma_f32_16x16x32_bf16 v[116:119], v[226:229], v[186:189], v[116:119]
	v_mfma_f32_16x16x32_bf16 v[112:115], v[234:237], v[186:189], v[112:115]
	v_mfma_f32_16x16x32_bf16 v[100:103], v[226:229], v[194:197], v[100:103]
	v_mfma_f32_16x16x32_bf16 v[96:99], v[234:237], v[194:197], v[96:99]
	v_mfma_f32_16x16x32_bf16 v[84:87], v[226:229], v[202:205], v[84:87]
	v_mfma_f32_16x16x32_bf16 v[80:83], v[234:237], v[202:205], v[80:83]
	v_mfma_f32_16x16x32_bf16 v[68:71], v[226:229], v[210:213], v[68:71]
	v_mfma_f32_16x16x32_bf16 v[64:67], v[234:237], v[210:213], v[64:67]
	v_mfma_f32_16x16x32_bf16 v[116:119], v[230:233], v[190:193], v[116:119]
	s_mov_b32 m0, s34
	v_mfma_f32_16x16x32_bf16 v[112:115], v[238:241], v[190:193], v[112:115]
	v_lshl_add_u64 v[154:155], v[220:221], 0, s[94:95]
	v_mfma_f32_16x16x32_bf16 v[100:103], v[230:233], v[198:201], v[100:103]
	v_mfma_f32_16x16x32_bf16 v[96:99], v[238:241], v[198:201], v[96:99]
	v_mfma_f32_16x16x32_bf16 v[84:87], v[230:233], v[206:209], v[84:87]
	v_mfma_f32_16x16x32_bf16 v[80:83], v[238:241], v[206:209], v[80:83]
	v_mfma_f32_16x16x32_bf16 v[68:71], v[230:233], v[214:217], v[68:71]
	s_setprio 0
	v_mfma_f32_16x16x32_bf16 v[64:67], v[238:241], v[214:217], v[64:67]
	s_barrier
	ds_read_b128 v[186:189], v137 offset:49152
	ds_read_b128 v[190:193], v137 offset:50176
	ds_read_b128 v[194:197], v137 offset:51200
	ds_read_b128 v[198:201], v137 offset:52224
	ds_read_b128 v[202:205], v137 offset:53248
	ds_read_b128 v[206:209], v137 offset:54272
	ds_read_b128 v[210:213], v137 offset:55296
	ds_read_b128 v[214:217], v137 offset:56320
	global_load_lds_dwordx4 v[154:155], off
	v_lshl_add_u64 v[154:155], v[242:243], 0, s[94:95]
	s_mov_b32 m0, s35
	s_nop 0
	global_load_lds_dwordx4 v[154:155], off
	s_waitcnt lgkmcnt(0)
	s_setprio 1
	s_barrier
; #define PG8_STAGE(bufoff, gbase) do { _Pragma("unroll") for (int _i = 0; _i < 2; ++_i) \
;         __builtin_amdgcn_global_load_lds((const unsigned*)((const char*)(gbase) + voff[_i]), (LAS unsigned*)(lds + (bufoff) + ldsw + _i * 8192), 16, 0, 0); } while (0)
; #define PG8_LDA(dst, b, h) do { _Pragma("unroll") for (int m = 0; m < 4; ++m) _Pragma("unroll") for (int k = 0; k < 2; ++k) dst[m][k] = *(const LAS bf16x8*)(lds + PG8_SA(b, h) + aoff + m * 2048 + k * 1024); } while (0)
; #define PG8_MMA(ai, bj, At, Bt) do { __builtin_amdgcn_s_setprio(1); _Pragma("unroll") for (int m = 0; m < 4; ++m) _Pragma("unroll") for (int n = 0; n < 2; ++n) _Pragma("unroll") for (int k = 0; k < 2; ++k) \
;         acc[ai][bj][m][n] = __builtin_amdgcn_mfma_f32_16x16x32_bf16(Bt[n][k], At[m][k], acc[ai][bj][m][n], 0, 0, 0); __builtin_amdgcn_s_setprio(0); } while (0)
; #define PG8_WAIT_V(n) asm volatile("s_waitcnt vmcnt(" #n ")" ::: "memory")
; #define PG8_WAIT_L(n) asm volatile("s_waitcnt lgkmcnt(" #n ")" ::: "memory")
; #define PG8_BAR __builtin_amdgcn_s_barrier()
; #define PG8_SCHED __builtin_amdgcn_sched_barrier(0)
; template <class Epi>
; DI void gemm_phase(LAS unsigned char* lds, const Gemm g, const StaticOrder& S, const Epi& E) {
;     ...
;             PG8_BAR; PG8_WAIT_L(0); PG8_MMA(0, 1, At, B1); PG8_BAR;
;             PG8_LDA(At, 1, 1); PG8_STAGE(PG8_SA(1, 0), a3);
;             PG8_BAR; PG8_WAIT_L(0); PG8_MMA(1, 0, At, B0); PG8_BAR; PG8_SCHED;
;             PG8_STAGE(PG8_SB(1, 1), b3 + hstep);
;             PG8_WAIT_V(6); PG8_BAR; PG8_MMA(1, 1, At, B1); PG8_BAR;
;     DI void operator()(const f32x4 (&acc)[2][2][4][2], const Unit& u, int wr, int wc, int fr, int fq) const {
;         const int row0 = u.pm * BM + wr * 64 + fr, col0 = u.pn * HALF + wc * 32 + 8 * fq;
; #pragma unroll
;         for (int ai = 0; ai < 2; ++ai)
; #pragma unroll
;             for (int m = 0; m < 4; ++m) { float hv[8];
; #pragma unroll
;                 for (int n = 0; n < 2; ++n)
; #pragma unroll
;                     for (int e = 0; e < 4; ++e) { const float gt = acc[ai][0][m][n][e], up = acc[ai][1][m][n][e];
;                         hv[n * 4 + e] = gt * __builtin_amdgcn_rcpf(1.f + __builtin_amdgcn_exp2f(-1.4426950408889634f * gt)) * up; }
;                 *(u32x4*)(H + (size_t)(row0 + ai * HALF + m * 16) * DFF + col0) = (u32x4){pk(hv[0], hv[1]), pk(hv[2], hv[3]), pk(hv[4], hv[5]), pk(hv[6], hv[7])}; }
	v_mfma_f32_16x16x32_bf16 v[60:63], v[138:141], v[186:189], v[60:63]
	v_mfma_f32_16x16x32_bf16 v[56:59], v[146:149], v[186:189], v[56:59]
	v_mfma_f32_16x16x32_bf16 v[44:47], v[138:141], v[194:197], v[44:47]
	v_mfma_f32_16x16x32_bf16 v[40:43], v[146:149], v[194:197], v[40:43]
	v_mfma_f32_16x16x32_bf16 v[28:31], v[138:141], v[202:205], v[28:31]
	v_mfma_f32_16x16x32_bf16 v[24:27], v[146:149], v[202:205], v[24:27]
	v_mfma_f32_16x16x32_bf16 v[12:15], v[138:141], v[210:213], v[12:15]
	v_mfma_f32_16x16x32_bf16 v[8:11], v[146:149], v[210:213], v[8:11]
	v_mfma_f32_16x16x32_bf16 v[60:63], v[142:145], v[190:193], v[60:63]
	v_mfma_f32_16x16x32_bf16 v[56:59], v[150:153], v[190:193], v[56:59]
	v_mfma_f32_16x16x32_bf16 v[44:47], v[142:145], v[198:201], v[44:47]
	v_mfma_f32_16x16x32_bf16 v[40:43], v[150:153], v[198:201], v[40:43]
	v_mfma_f32_16x16x32_bf16 v[28:31], v[142:145], v[206:209], v[28:31]
	v_mfma_f32_16x16x32_bf16 v[24:27], v[150:153], v[206:209], v[24:27]
	v_mfma_f32_16x16x32_bf16 v[12:15], v[142:145], v[214:217], v[12:15]
	s_setprio 0
	v_mfma_f32_16x16x32_bf16 v[8:11], v[150:153], v[214:217], v[8:11]
	s_barrier
	s_add_u32 s20, s20, 0x80080
	s_addc_u32 s21, s21, 0
	s_add_i32 s22, s22, s27
	v_lshl_add_u64 v[138:139], s[20:21], 0, v[158:159]
	s_mov_b32 m0, s22
	s_nop 0
	global_load_lds_dwordx4 v[138:139], off
	v_lshl_add_u64 v[138:139], s[20:21], 0, v[128:129]
	s_add_i32 m0, s22, 0x2000
	s_nop 0
	global_load_lds_dwordx4 v[138:139], off
	s_waitcnt vmcnt(6)
	s_setprio 1
	s_barrier
	v_mfma_f32_16x16x32_bf16 v[52:55], v[226:229], v[186:189], v[52:55]
	v_mfma_f32_16x16x32_bf16 v[48:51], v[234:237], v[186:189], v[48:51]
	v_mfma_f32_16x16x32_bf16 v[36:39], v[226:229], v[194:197], v[36:39]
	v_mfma_f32_16x16x32_bf16 v[32:35], v[234:237], v[194:197], v[32:35]
	v_mfma_f32_16x16x32_bf16 v[20:23], v[226:229], v[202:205], v[20:23]
	v_mfma_f32_16x16x32_bf16 v[16:19], v[234:237], v[202:205], v[16:19]
	v_mfma_f32_16x16x32_bf16 v[4:7], v[226:229], v[210:213], v[4:7]
	v_mfma_f32_16x16x32_bf16 v[0:3], v[234:237], v[210:213], v[0:3]
	v_mfma_f32_16x16x32_bf16 v[52:55], v[230:233], v[190:193], v[52:55]
	s_add_i32 s38, s38, 2
	v_mfma_f32_16x16x32_bf16 v[48:51], v[238:241], v[190:193], v[48:51]
	s_add_u32 s18, s18, 0x100
	v_mfma_f32_16x16x32_bf16 v[36:39], v[230:233], v[198:201], v[36:39]
	s_addc_u32 s19, s19, 0
	v_mfma_f32_16x16x32_bf16 v[32:35], v[238:241], v[198:201], v[32:35]
	s_add_u32 s33, s33, 0x100
	v_mfma_f32_16x16x32_bf16 v[20:23], v[230:233], v[206:209], v[20:23]
	s_addc_u32 s37, s37, 0
	v_mfma_f32_16x16x32_bf16 v[16:19], v[238:241], v[206:209], v[16:19]
	s_cmp_gt_u32 s38, 29
	v_mfma_f32_16x16x32_bf16 v[4:7], v[230:233], v[214:217], v[4:7]
	s_setprio 0
	v_mfma_f32_16x16x32_bf16 v[0:3], v[238:241], v[214:217], v[0:3]
	s_barrier
	s_cbranch_scc0 .LBB0_37
	v_mul_f32_e32 v139, 0xbfb8aa3b, v124
	v_exp_f32_e32 v139, v139
	v_lshl_or_b32 v140, s2, 7, v136
	v_lshl_add_u32 v138, s3, 8, v134
	v_ashrrev_i32_e32 v141, 31, v140
	v_add_f32_e32 v139, 1.0, v139
	v_rcp_f32_e32 v142, v139
	v_mul_f32_e32 v139, 0xbfb8aa3b, v125
	v_exp_f32_e32 v139, v139
	s_movk_i32 s4, 0x2c00
	s_and_b64 vcc, exec, s[6:7]
	s_mov_b64 s[20:21], s[16:17]
	v_add_f32_e32 v139, 1.0, v139
	v_rcp_f32_e32 v143, v139
	v_mul_f32_e32 v139, 0xbfb8aa3b, v126
	v_exp_f32_e32 v139, v139
	s_mov_b64 s[18:19], s[14:15]
	v_pk_mul_f32 v[124:125], v[124:125], v[142:143]
	v_add_f32_e32 v139, 1.0, v139
	v_rcp_f32_e32 v144, v139
	v_mul_f32_e32 v139, 0xbfb8aa3b, v127
	v_exp_f32_e32 v139, v139
	v_pk_mul_f32 v[116:117], v[124:125], v[116:117]
	v_add_f32_e32 v139, 1.0, v139
	v_rcp_f32_e32 v145, v139
	v_mul_f32_e32 v139, 0xbfb8aa3b, v120
	v_exp_f32_e32 v139, v139
	v_cvt_pk_bf16_f32 v116, v116, v117
	v_pk_mul_f32 v[124:125], v[126:127], v[144:145]
	v_add_f32_e32 v139, 1.0, v139
	v_rcp_f32_e32 v146, v139
	v_mul_f32_e32 v139, 0xbfb8aa3b, v121
	v_exp_f32_e32 v139, v139
	v_pk_mul_f32 v[118:119], v[124:125], v[118:119]
	v_add_f32_e32 v139, 1.0, v139
	v_rcp_f32_e32 v147, v139
	v_mul_f32_e32 v139, 0xbfb8aa3b, v122
	v_exp_f32_e32 v139, v139
	v_cvt_pk_bf16_f32 v117, v118, v119
	v_pk_mul_f32 v[118:119], v[120:121], v[146:147]
	v_add_f32_e32 v139, 1.0, v139
	v_rcp_f32_e32 v148, v139
	v_mul_f32_e32 v139, 0xbfb8aa3b, v123
	v_exp_f32_e32 v139, v139
	v_pk_mul_f32 v[112:113], v[118:119], v[112:113]
	v_add_f32_e32 v139, 1.0, v139
	v_rcp_f32_e32 v149, v139
	v_cvt_pk_bf16_f32 v118, v112, v113
	v_pk_mul_f32 v[112:113], v[122:123], v[148:149]
	s_nop 0
	v_pk_mul_f32 v[112:113], v[112:113], v[114:115]
	v_lshlrev_b64 v[114:115], 1, v[140:141]
	v_cvt_pk_bf16_f32 v119, v112, v113
	v_mov_b64_e32 v[112:113], s[54:55]
	v_mad_i64_i32 v[120:121], s[2:3], v138, s4, v[112:113]
	v_lshl_add_u64 v[120:121], v[120:121], 0, v[114:115]
	global_store_dwordx4 v[120:121], v[116:119], off
	v_mul_f32_e32 v120, 0xbfb8aa3b, v104
	v_mul_f32_e32 v121, 0xbfb8aa3b, v105
	v_mul_f32_e32 v116, 0xbfb8aa3b, v108
	v_mul_f32_e32 v117, 0xbfb8aa3b, v109
	v_exp_f32_e32 v116, v116
	v_exp_f32_e32 v117, v117
	v_mul_f32_e32 v118, 0xbfb8aa3b, v110
	v_mul_f32_e32 v119, 0xbfb8aa3b, v111
	v_exp_f32_e32 v118, v118
	v_exp_f32_e32 v119, v119
	v_exp_f32_e32 v120, v120
	v_exp_f32_e32 v121, v121
	v_add_f32_e32 v116, 1.0, v116
	v_add_f32_e32 v117, 1.0, v117
	v_mul_f32_e32 v122, 0xbfb8aa3b, v106
	v_mul_f32_e32 v123, 0xbfb8aa3b, v107
	v_rcp_f32_e32 v116, v116
	v_rcp_f32_e32 v117, v117
	v_add_f32_e32 v118, 1.0, v118
	v_add_f32_e32 v119, 1.0, v119
	v_exp_f32_e32 v122, v122
	v_exp_f32_e32 v123, v123
	v_rcp_f32_e32 v118, v118
	v_rcp_f32_e32 v119, v119
	v_add_f32_e32 v120, 1.0, v120
	v_add_f32_e32 v121, 1.0, v121
	v_rcp_f32_e32 v120, v120
	v_rcp_f32_e32 v121, v121
	v_add_f32_e32 v122, 1.0, v122
;     DI void operator()(const f32x4 (&acc)[2][2][4][2], const Unit& u, int wr, int wc, int fr, int fq) const {
;     ...
;             for (int m = 0; m < 4; ++m) { float hv[8];
; #pragma unroll
;                 for (int n = 0; n < 2; ++n)
; #pragma unroll
;                     for (int e = 0; e < 4; ++e) { const float gt = acc[ai][0][m][n][e], up = acc[ai][1][m][n][e];
;                         hv[n * 4 + e] = gt * __builtin_amdgcn_rcpf(1.f + __builtin_amdgcn_exp2f(-1.4426950408889634f * gt)) * up; }
;                 *(u32x4*)(H + (size_t)(row0 + ai * HALF + m * 16) * DFF + col0) = (u32x4){pk(hv[0], hv[1]), pk(hv[2], hv[3]), pk(hv[4], hv[5]), pk(hv[6], hv[7])}; }
	v_add_f32_e32 v123, 1.0, v123
	v_pk_mul_f32 v[108:109], v[108:109], v[116:117]
	v_rcp_f32_e32 v122, v122
	v_rcp_f32_e32 v123, v123
	v_pk_mul_f32 v[100:101], v[108:109], v[100:101]
	v_pk_mul_f32 v[108:109], v[110:111], v[118:119]
	v_cvt_pk_bf16_f32 v100, v100, v101
	v_pk_mul_f32 v[102:103], v[108:109], v[102:103]
	s_nop 0
	v_cvt_pk_bf16_f32 v101, v102, v103
	v_pk_mul_f32 v[102:103], v[104:105], v[120:121]
	s_nop 0
	v_pk_mul_f32 v[96:97], v[102:103], v[96:97]
	s_nop 0
	v_cvt_pk_bf16_f32 v102, v96, v97
	v_pk_mul_f32 v[96:97], v[106:107], v[122:123]
	s_nop 0
	v_pk_mul_f32 v[96:97], v[96:97], v[98:99]
	v_mul_f32_e32 v98, 0xbfb8aa3b, v94
	v_cvt_pk_bf16_f32 v103, v96, v97
	v_or_b32_e32 v96, 16, v138
	v_mad_i64_i32 v[96:97], s[2:3], v96, s4, v[112:113]
	v_lshl_add_u64 v[96:97], v[96:97], 0, v[114:115]
	global_store_dwordx4 v[96:97], v[100:103], off
	v_mul_f32_e32 v96, 0xbfb8aa3b, v92
	v_mul_f32_e32 v97, 0xbfb8aa3b, v93
	v_exp_f32_e32 v96, v96
	v_exp_f32_e32 v97, v97
	v_mul_f32_e32 v99, 0xbfb8aa3b, v95
	v_exp_f32_e32 v98, v98
	v_exp_f32_e32 v99, v99
	v_mul_f32_e32 v100, 0xbfb8aa3b, v88
	v_mul_f32_e32 v101, 0xbfb8aa3b, v89
	v_exp_f32_e32 v100, v100
	v_exp_f32_e32 v101, v101
	v_add_f32_e32 v96, 1.0, v96
	v_add_f32_e32 v97, 1.0, v97
	v_mul_f32_e32 v102, 0xbfb8aa3b, v90
	v_mul_f32_e32 v103, 0xbfb8aa3b, v91
	v_rcp_f32_e32 v96, v96
	v_rcp_f32_e32 v97, v97
	v_add_f32_e32 v98, 1.0, v98
	v_add_f32_e32 v99, 1.0, v99
	v_exp_f32_e32 v102, v102
	v_exp_f32_e32 v103, v103
	v_rcp_f32_e32 v98, v98
	v_rcp_f32_e32 v99, v99
	v_add_f32_e32 v100, 1.0, v100
	v_add_f32_e32 v101, 1.0, v101
	v_rcp_f32_e32 v100, v100
	v_rcp_f32_e32 v101, v101
	v_add_f32_e32 v102, 1.0, v102
	v_add_f32_e32 v103, 1.0, v103
	v_pk_mul_f32 v[92:93], v[92:93], v[96:97]
	v_rcp_f32_e32 v102, v102
	v_rcp_f32_e32 v103, v103
	v_pk_mul_f32 v[84:85], v[92:93], v[84:85]
	v_pk_mul_f32 v[92:93], v[94:95], v[98:99]
	v_cvt_pk_bf16_f32 v84, v84, v85
	v_pk_mul_f32 v[86:87], v[92:93], v[86:87]
	s_nop 0
	v_cvt_pk_bf16_f32 v85, v86, v87
	v_pk_mul_f32 v[86:87], v[88:89], v[100:101]
	s_nop 0
	v_pk_mul_f32 v[80:81], v[86:87], v[80:81]
	s_nop 0
	v_cvt_pk_bf16_f32 v86, v80, v81
	v_pk_mul_f32 v[80:81], v[90:91], v[102:103]
	s_nop 0
	v_pk_mul_f32 v[80:81], v[80:81], v[82:83]
	v_mul_f32_e32 v82, 0xbfb8aa3b, v78
	v_cvt_pk_bf16_f32 v87, v80, v81
	v_or_b32_e32 v80, 32, v138
	v_mad_i64_i32 v[80:81], s[2:3], v80, s4, v[112:113]
	v_lshl_add_u64 v[80:81], v[80:81], 0, v[114:115]
	global_store_dwordx4 v[80:81], v[84:87], off
	v_mul_f32_e32 v80, 0xbfb8aa3b, v76
	v_mul_f32_e32 v81, 0xbfb8aa3b, v77
	v_exp_f32_e32 v80, v80
	v_exp_f32_e32 v81, v81
	v_mul_f32_e32 v83, 0xbfb8aa3b, v79
	v_exp_f32_e32 v82, v82
	v_exp_f32_e32 v83, v83
	v_mul_f32_e32 v84, 0xbfb8aa3b, v72
	v_mul_f32_e32 v85, 0xbfb8aa3b, v73
	v_exp_f32_e32 v84, v84
	v_exp_f32_e32 v85, v85
	v_add_f32_e32 v80, 1.0, v80
	v_add_f32_e32 v81, 1.0, v81
	v_mul_f32_e32 v86, 0xbfb8aa3b, v74
	v_mul_f32_e32 v87, 0xbfb8aa3b, v75
	v_rcp_f32_e32 v80, v80
	v_rcp_f32_e32 v81, v81
	v_add_f32_e32 v82, 1.0, v82
	v_add_f32_e32 v83, 1.0, v83
	v_exp_f32_e32 v86, v86
	v_exp_f32_e32 v87, v87
	v_rcp_f32_e32 v82, v82
	v_rcp_f32_e32 v83, v83
	v_add_f32_e32 v84, 1.0, v84
	v_add_f32_e32 v85, 1.0, v85
	v_rcp_f32_e32 v84, v84
	v_rcp_f32_e32 v85, v85
	v_add_f32_e32 v86, 1.0, v86
	v_add_f32_e32 v87, 1.0, v87
	v_pk_mul_f32 v[76:77], v[76:77], v[80:81]
	v_rcp_f32_e32 v86, v86
	v_rcp_f32_e32 v87, v87
	v_pk_mul_f32 v[68:69], v[76:77], v[68:69]
	v_pk_mul_f32 v[76:77], v[78:79], v[82:83]
	v_cvt_pk_bf16_f32 v68, v68, v69
	v_pk_mul_f32 v[70:71], v[76:77], v[70:71]
	s_nop 0
	v_cvt_pk_bf16_f32 v69, v70, v71
	v_pk_mul_f32 v[70:71], v[72:73], v[84:85]
	v_add_u32_e32 v72, 0x80, v138
	v_pk_mul_f32 v[64:65], v[70:71], v[64:65]
	s_nop 0
	v_cvt_pk_bf16_f32 v70, v64, v65
	v_pk_mul_f32 v[64:65], v[74:75], v[86:87]
	s_nop 0
	v_pk_mul_f32 v[64:65], v[64:65], v[66:67]
	v_mul_f32_e32 v66, 0xbfb8aa3b, v62
	v_cvt_pk_bf16_f32 v71, v64, v65
	v_or_b32_e32 v64, 48, v138
	v_mad_i64_i32 v[64:65], s[2:3], v64, s4, v[112:113]
	v_lshl_add_u64 v[64:65], v[64:65], 0, v[114:115]
	global_store_dwordx4 v[64:65], v[68:71], off
	v_mul_f32_e32 v64, 0xbfb8aa3b, v60
	v_mul_f32_e32 v65, 0xbfb8aa3b, v61
	v_exp_f32_e32 v64, v64
	v_exp_f32_e32 v65, v65
	v_mul_f32_e32 v67, 0xbfb8aa3b, v63
	v_exp_f32_e32 v66, v66
	v_exp_f32_e32 v67, v67
	v_mul_f32_e32 v68, 0xbfb8aa3b, v56
	v_mul_f32_e32 v69, 0xbfb8aa3b, v57
	v_exp_f32_e32 v68, v68
	v_exp_f32_e32 v69, v69
	v_add_f32_e32 v64, 1.0, v64
	v_add_f32_e32 v65, 1.0, v65
	v_mul_f32_e32 v70, 0xbfb8aa3b, v58
	v_mul_f32_e32 v71, 0xbfb8aa3b, v59
	v_rcp_f32_e32 v64, v64
	v_rcp_f32_e32 v65, v65
	v_add_f32_e32 v66, 1.0, v66
	v_add_f32_e32 v67, 1.0, v67
	v_exp_f32_e32 v70, v70
	v_exp_f32_e32 v71, v71
	v_rcp_f32_e32 v66, v66
	v_rcp_f32_e32 v67, v67
	v_add_f32_e32 v68, 1.0, v68
	v_add_f32_e32 v69, 1.0, v69
	v_rcp_f32_e32 v68, v68
	v_rcp_f32_e32 v69, v69
	v_add_f32_e32 v70, 1.0, v70
	v_add_f32_e32 v71, 1.0, v71
	v_pk_mul_f32 v[60:61], v[60:61], v[64:65]
	v_rcp_f32_e32 v70, v70
	v_rcp_f32_e32 v71, v71
	v_pk_mul_f32 v[52:53], v[60:61], v[52:53]
	v_pk_mul_f32 v[60:61], v[62:63], v[66:67]
	v_cvt_pk_bf16_f32 v52, v52, v53
	v_pk_mul_f32 v[54:55], v[60:61], v[54:55]
	s_nop 0
	v_cvt_pk_bf16_f32 v53, v54, v55
	v_pk_mul_f32 v[54:55], v[56:57], v[68:69]
; #define PG8_WAIT_V(n) asm volatile("s_waitcnt vmcnt(" #n ")" ::: "memory")
; #define PG8_BAR __builtin_amdgcn_s_barrier()
; template <class Epi>
; DI void gemm_phase(LAS unsigned char* lds, const Gemm g, const StaticOrder& S, const Epi& E) {
;     ...
;         if (!has_next) break;
; #pragma unroll
;         for (int a = 0; a < 2; ++a)
; #pragma unroll
;             for (int b = 0; b < 2; ++b)
; #pragma unroll
;                 for (int m = 0; m < 4; ++m)
; #pragma unroll
;                     for (int n = 0; n < 2; ++n) acc[a][b][m][n] = (f32x4){0.f, 0.f, 0.f, 0.f};
;         cur = nxt; cA = nA; cB = nB; ++ui;
;     }
;     PG8_WAIT_V(0);
;     if (wr == 0) PG8_BAR;
;     PG8_BAR;
;     DI void operator()(const f32x4 (&acc)[2][2][4][2], const Unit& u, int wr, int wc, int fr, int fq) const {
;     ...
;             for (int m = 0; m < 4; ++m) { float hv[8];
; #pragma unroll
;                 for (int n = 0; n < 2; ++n)
; #pragma unroll
;                     for (int e = 0; e < 4; ++e) { const float gt = acc[ai][0][m][n][e], up = acc[ai][1][m][n][e];
;                         hv[n * 4 + e] = gt * __builtin_amdgcn_rcpf(1.f + __builtin_amdgcn_exp2f(-1.4426950408889634f * gt)) * up; }
;                 *(u32x4*)(H + (size_t)(row0 + ai * HALF + m * 16) * DFF + col0) = (u32x4){pk(hv[0], hv[1]), pk(hv[2], hv[3]), pk(hv[4], hv[5]), pk(hv[6], hv[7])}; }
	s_nop 0
	v_pk_mul_f32 v[48:49], v[54:55], v[48:49]
	s_nop 0
	v_cvt_pk_bf16_f32 v54, v48, v49
	v_pk_mul_f32 v[48:49], v[58:59], v[70:71]
	s_nop 0
	v_pk_mul_f32 v[48:49], v[48:49], v[50:51]
	v_mul_f32_e32 v50, 0xbfb8aa3b, v46
	v_cvt_pk_bf16_f32 v55, v48, v49
	v_mad_i64_i32 v[48:49], s[2:3], v72, s4, v[112:113]
	v_lshl_add_u64 v[48:49], v[48:49], 0, v[114:115]
	global_store_dwordx4 v[48:49], v[52:55], off
	v_mul_f32_e32 v48, 0xbfb8aa3b, v44
	v_mul_f32_e32 v49, 0xbfb8aa3b, v45
	v_exp_f32_e32 v48, v48
	v_exp_f32_e32 v49, v49
	v_mul_f32_e32 v51, 0xbfb8aa3b, v47
	v_exp_f32_e32 v50, v50
	v_exp_f32_e32 v51, v51
	v_mul_f32_e32 v52, 0xbfb8aa3b, v40
	v_mul_f32_e32 v53, 0xbfb8aa3b, v41
	v_exp_f32_e32 v52, v52
	v_exp_f32_e32 v53, v53
	v_add_f32_e32 v48, 1.0, v48
	v_add_f32_e32 v49, 1.0, v49
	v_mul_f32_e32 v54, 0xbfb8aa3b, v42
	v_mul_f32_e32 v55, 0xbfb8aa3b, v43
	v_rcp_f32_e32 v48, v48
	v_rcp_f32_e32 v49, v49
	v_add_f32_e32 v50, 1.0, v50
	v_add_f32_e32 v51, 1.0, v51
	v_exp_f32_e32 v54, v54
	v_exp_f32_e32 v55, v55
	v_rcp_f32_e32 v50, v50
	v_rcp_f32_e32 v51, v51
	v_add_f32_e32 v52, 1.0, v52
	v_add_f32_e32 v53, 1.0, v53
	v_rcp_f32_e32 v52, v52
	v_rcp_f32_e32 v53, v53
	v_add_f32_e32 v54, 1.0, v54
	v_add_f32_e32 v55, 1.0, v55
	v_pk_mul_f32 v[44:45], v[44:45], v[48:49]
	v_rcp_f32_e32 v54, v54
	v_rcp_f32_e32 v55, v55
	v_pk_mul_f32 v[36:37], v[44:45], v[36:37]
	v_pk_mul_f32 v[44:45], v[46:47], v[50:51]
	v_cvt_pk_bf16_f32 v36, v36, v37
	v_pk_mul_f32 v[38:39], v[44:45], v[38:39]
	s_nop 0
	v_cvt_pk_bf16_f32 v37, v38, v39
	v_pk_mul_f32 v[38:39], v[40:41], v[52:53]
	s_nop 0
	v_pk_mul_f32 v[32:33], v[38:39], v[32:33]
	s_nop 0
	v_cvt_pk_bf16_f32 v38, v32, v33
	v_pk_mul_f32 v[32:33], v[42:43], v[54:55]
	s_nop 0
	v_pk_mul_f32 v[32:33], v[32:33], v[34:35]
	v_mul_f32_e32 v34, 0xbfb8aa3b, v30
	v_cvt_pk_bf16_f32 v39, v32, v33
	v_add_u32_e32 v32, 0x90, v138
	v_mad_i64_i32 v[32:33], s[2:3], v32, s4, v[112:113]
	v_lshl_add_u64 v[32:33], v[32:33], 0, v[114:115]
	global_store_dwordx4 v[32:33], v[36:39], off
	v_mul_f32_e32 v32, 0xbfb8aa3b, v28
	v_mul_f32_e32 v33, 0xbfb8aa3b, v29
	v_exp_f32_e32 v32, v32
	v_exp_f32_e32 v33, v33
	v_mul_f32_e32 v35, 0xbfb8aa3b, v31
	v_exp_f32_e32 v34, v34
	v_exp_f32_e32 v35, v35
	v_mul_f32_e32 v36, 0xbfb8aa3b, v24
	v_mul_f32_e32 v37, 0xbfb8aa3b, v25
	v_exp_f32_e32 v36, v36
	v_exp_f32_e32 v37, v37
	v_add_f32_e32 v32, 1.0, v32
	v_add_f32_e32 v33, 1.0, v33
	v_mul_f32_e32 v38, 0xbfb8aa3b, v26
	v_mul_f32_e32 v39, 0xbfb8aa3b, v27
	v_rcp_f32_e32 v32, v32
	v_rcp_f32_e32 v33, v33
	v_add_f32_e32 v34, 1.0, v34
	v_add_f32_e32 v35, 1.0, v35
	v_exp_f32_e32 v38, v38
	v_exp_f32_e32 v39, v39
	v_rcp_f32_e32 v34, v34
	v_rcp_f32_e32 v35, v35
	v_add_f32_e32 v36, 1.0, v36
	v_add_f32_e32 v37, 1.0, v37
	v_rcp_f32_e32 v36, v36
	v_rcp_f32_e32 v37, v37
	v_add_f32_e32 v38, 1.0, v38
	v_add_f32_e32 v39, 1.0, v39
	v_pk_mul_f32 v[28:29], v[28:29], v[32:33]
	v_rcp_f32_e32 v38, v38
	v_rcp_f32_e32 v39, v39
	v_pk_mul_f32 v[20:21], v[28:29], v[20:21]
	v_pk_mul_f32 v[28:29], v[30:31], v[34:35]
	v_cvt_pk_bf16_f32 v20, v20, v21
	v_pk_mul_f32 v[22:23], v[28:29], v[22:23]
	s_nop 0
	v_cvt_pk_bf16_f32 v21, v22, v23
	v_pk_mul_f32 v[22:23], v[24:25], v[36:37]
	s_nop 0
	v_pk_mul_f32 v[16:17], v[22:23], v[16:17]
	s_nop 0
	v_cvt_pk_bf16_f32 v22, v16, v17
	v_pk_mul_f32 v[16:17], v[26:27], v[38:39]
	s_nop 0
	v_pk_mul_f32 v[16:17], v[16:17], v[18:19]
	v_mul_f32_e32 v18, 0xbfb8aa3b, v14
	v_cvt_pk_bf16_f32 v23, v16, v17
	v_add_u32_e32 v16, 0xa0, v138
	v_mad_i64_i32 v[16:17], s[2:3], v16, s4, v[112:113]
	v_lshl_add_u64 v[16:17], v[16:17], 0, v[114:115]
	global_store_dwordx4 v[16:17], v[20:23], off
	v_mul_f32_e32 v16, 0xbfb8aa3b, v12
	v_mul_f32_e32 v17, 0xbfb8aa3b, v13
	v_exp_f32_e32 v16, v16
	v_exp_f32_e32 v17, v17
	v_mul_f32_e32 v19, 0xbfb8aa3b, v15
	v_exp_f32_e32 v18, v18
	v_exp_f32_e32 v19, v19
	v_mul_f32_e32 v20, 0xbfb8aa3b, v8
	v_mul_f32_e32 v21, 0xbfb8aa3b, v9
	v_exp_f32_e32 v20, v20
	v_exp_f32_e32 v21, v21
	v_add_f32_e32 v16, 1.0, v16
	v_add_f32_e32 v17, 1.0, v17
	v_mul_f32_e32 v22, 0xbfb8aa3b, v10
	v_mul_f32_e32 v23, 0xbfb8aa3b, v11
	v_rcp_f32_e32 v16, v16
	v_rcp_f32_e32 v17, v17
	v_add_f32_e32 v18, 1.0, v18
	v_add_f32_e32 v19, 1.0, v19
	v_exp_f32_e32 v22, v22
	v_exp_f32_e32 v23, v23
	v_rcp_f32_e32 v18, v18
	v_rcp_f32_e32 v19, v19
	v_add_f32_e32 v20, 1.0, v20
	v_add_f32_e32 v21, 1.0, v21
	v_rcp_f32_e32 v20, v20
	v_rcp_f32_e32 v21, v21
	v_add_f32_e32 v22, 1.0, v22
	v_add_f32_e32 v23, 1.0, v23
	v_pk_mul_f32 v[12:13], v[12:13], v[16:17]
	v_rcp_f32_e32 v22, v22
	v_rcp_f32_e32 v23, v23
	v_pk_mul_f32 v[4:5], v[12:13], v[4:5]
	v_pk_mul_f32 v[12:13], v[14:15], v[18:19]
	v_cvt_pk_bf16_f32 v4, v4, v5
	v_pk_mul_f32 v[6:7], v[12:13], v[6:7]
	s_nop 0
	v_cvt_pk_bf16_f32 v5, v6, v7
	v_pk_mul_f32 v[6:7], v[8:9], v[20:21]
	s_nop 0
	v_pk_mul_f32 v[0:1], v[6:7], v[0:1]
	s_nop 0
	v_cvt_pk_bf16_f32 v6, v0, v1
	v_pk_mul_f32 v[0:1], v[10:11], v[22:23]
	s_nop 0
	v_pk_mul_f32 v[0:1], v[0:1], v[2:3]
	s_nop 0
	v_cvt_pk_bf16_f32 v7, v0, v1
	v_add_u32_e32 v0, 0xb0, v138
	v_mad_i64_i32 v[0:1], s[2:3], v0, s4, v[112:113]
	v_lshl_add_u64 v[0:1], v[0:1], 0, v[114:115]
	s_mov_b32 s2, s8
	s_mov_b32 s3, s10
	global_store_dwordx4 v[0:1], v[4:7], off
	s_cbranch_vccz .LBB0_34
	s_waitcnt vmcnt(0)
	s_cmpk_gt_u32 s24, 0xff
	s_cbranch_scc1 .LBB0_41
	s_barrier

; #define PG8_STAGE(bufoff, gbase) do { _Pragma("unroll") for (int _i = 0; _i < 2; ++_i) \
;         __builtin_amdgcn_global_load_lds((const unsigned*)((const char*)(gbase) + voff[_i]), (LAS unsigned*)(lds + (bufoff) + ldsw + _i * 8192), 16, 0, 0); } while (0)
; #define PG8_LDA(dst, b, h) do { _Pragma("unroll") for (int m = 0; m < 4; ++m) _Pragma("unroll") for (int k = 0; k < 2; ++k) dst[m][k] = *(const LAS bf16x8*)(lds + PG8_SA(b, h) + aoff + m * 2048 + k * 1024); } while (0)
; #define PG8_LDB(dst, b, h) do { _Pragma("unroll") for (int n = 0; n < 2; ++n) _Pragma("unroll") for (int k = 0; k < 2; ++k) dst[n][k] = *(const LAS bf16x8*)(lds + PG8_SB(b, h) + boff + n * 2048 + k * 1024); } while (0)
; #define PG8_MMA(ai, bj, At, Bt) do { __builtin_amdgcn_s_setprio(1); _Pragma("unroll") for (int m = 0; m < 4; ++m) _Pragma("unroll") for (int n = 0; n < 2; ++n) _Pragma("unroll") for (int k = 0; k < 2; ++k) \
;         acc[ai][bj][m][n] = __builtin_amdgcn_mfma_f32_16x16x32_bf16(Bt[n][k], At[m][k], acc[ai][bj][m][n], 0, 0, 0); __builtin_amdgcn_s_setprio(0); } while (0)
; #define PG8_WAIT_V(n) asm volatile("s_waitcnt vmcnt(" #n ")" ::: "memory")
; #define PG8_WAIT_L(n) asm volatile("s_waitcnt lgkmcnt(" #n ")" ::: "memory")
; #define PG8_BAR __builtin_amdgcn_s_barrier()
; #define PG8_SCHED __builtin_amdgcn_sched_barrier(0)
; template <class Epi>
; DI void gemm_phase(LAS unsigned char* lds, const Gemm g, const StaticOrder& S, const Epi& E) {
;     ...
;             PG8_LDB(B0, 0, 0); PG8_SCHED; PG8_LDA(At, 0, 0); PG8_STAGE(PG8_SA(1, 1), a1 + hstep);
;             PG8_WAIT_L(8); PG8_BAR; PG8_WAIT_L(0); PG8_MMA(0, 0, At, B0); PG8_BAR; PG8_SCHED;
;             PG8_LDB(B1, 0, 1); PG8_STAGE(PG8_SB(0, 0), b2);
;             PG8_BAR; PG8_WAIT_L(0); PG8_MMA(0, 1, At, B1); PG8_BAR;
;             PG8_LDA(At, 0, 1); PG8_STAGE(PG8_SA(0, 0), a2);
;             PG8_BAR; PG8_WAIT_L(0); PG8_MMA(1, 0, At, B0); PG8_BAR; PG8_SCHED;
;             PG8_STAGE(PG8_SB(0, 1), b2 + hstep);
;             PG8_WAIT_V(6); PG8_BAR; PG8_MMA(1, 1, At, B1); PG8_BAR;
.LBB0_77:
	s_add_u32 s22, s20, 0x100
	s_addc_u32 s23, s21, 0
	s_add_i32 s43, 0, 0x10000
	ds_read_b128 v[128:131], v226
	ds_read_b128 v[132:135], v226 offset:1024
	ds_read_b128 v[136:139], v226 offset:2048
	ds_read_b128 v[140:143], v226 offset:3072
	s_cmp_eq_u32 s33, 32
	s_cselect_b32 s27, s9, s23
	s_cselect_b32 s26, s8, s22
	s_cselect_b32 s25, s11, s5
	s_cselect_b32 s24, s10, s4
	v_lshl_add_u64 v[214:215], s[20:21], 0, v[190:191]
	s_add_i32 m0, s34, 0xc000
	ds_read_b128 v[144:147], v228
	ds_read_b128 v[148:151], v228 offset:1024
	ds_read_b128 v[152:155], v228 offset:2048
	ds_read_b128 v[194:197], v228 offset:3072
	ds_read_b128 v[198:201], v228 offset:4096
	ds_read_b128 v[202:205], v228 offset:5120
	ds_read_b128 v[206:209], v228 offset:6144
	ds_read_b128 v[210:213], v228 offset:7168
	global_load_lds_dwordx4 v[214:215], off
	v_lshl_add_u64 v[214:215], s[20:21], 0, v[192:193]
	s_add_i32 m0, s34, 0xe000
	s_nop 0
	global_load_lds_dwordx4 v[214:215], off
	s_waitcnt lgkmcnt(8)
	s_setprio 1
	s_barrier
	s_waitcnt lgkmcnt(0)
	v_mfma_f32_16x16x32_bf16 v[124:127], v[128:131], v[144:147], v[124:127]
	v_mfma_f32_16x16x32_bf16 v[120:123], v[136:139], v[144:147], v[120:123]
	v_mfma_f32_16x16x32_bf16 v[116:119], v[128:131], v[152:155], v[116:119]
	v_mfma_f32_16x16x32_bf16 v[112:115], v[136:139], v[152:155], v[112:115]
	v_mfma_f32_16x16x32_bf16 v[108:111], v[128:131], v[198:201], v[108:111]
	v_mfma_f32_16x16x32_bf16 v[104:107], v[136:139], v[198:201], v[104:107]
	v_mfma_f32_16x16x32_bf16 v[100:103], v[128:131], v[206:209], v[100:103]
	v_mfma_f32_16x16x32_bf16 v[96:99], v[136:139], v[206:209], v[96:99]
	v_mfma_f32_16x16x32_bf16 v[124:127], v[132:135], v[148:151], v[124:127]
	v_mfma_f32_16x16x32_bf16 v[120:123], v[140:143], v[148:151], v[120:123]
	v_mfma_f32_16x16x32_bf16 v[116:119], v[132:135], v[194:197], v[116:119]
	v_mfma_f32_16x16x32_bf16 v[112:115], v[140:143], v[194:197], v[112:115]
	v_mfma_f32_16x16x32_bf16 v[108:111], v[132:135], v[202:205], v[108:111]
	v_mfma_f32_16x16x32_bf16 v[104:107], v[140:143], v[202:205], v[104:107]
	v_mfma_f32_16x16x32_bf16 v[100:103], v[132:135], v[210:213], v[100:103]
	s_setprio 0
	v_mfma_f32_16x16x32_bf16 v[96:99], v[140:143], v[210:213], v[96:99]
	s_barrier
	s_add_i32 s44, 0, 0x14000
	s_add_i32 s20, s43, s31
	v_lshl_add_u64 v[218:219], s[24:25], 0, v[188:189]
	s_mov_b32 m0, s20
	ds_read_b128 v[214:217], v226 offset:16384
	ds_read_b128 v[230:233], v226 offset:17408
	ds_read_b128 v[234:237], v226 offset:18432
	ds_read_b128 v[238:241], v226 offset:19456
	global_load_lds_dwordx4 v[218:219], off
	v_lshl_add_u64 v[220:221], s[24:25], 0, v[186:187]
	s_add_i32 m0, s20, 0x2000
	s_nop 0
	global_load_lds_dwordx4 v[220:221], off
	s_waitcnt lgkmcnt(0)
	s_setprio 1
	s_barrier
	v_mfma_f32_16x16x32_bf16 v[60:63], v[214:217], v[144:147], v[60:63]
	v_mfma_f32_16x16x32_bf16 v[56:59], v[234:237], v[144:147], v[56:59]
	v_mfma_f32_16x16x32_bf16 v[52:55], v[214:217], v[152:155], v[52:55]
	v_mfma_f32_16x16x32_bf16 v[48:51], v[234:237], v[152:155], v[48:51]
	v_mfma_f32_16x16x32_bf16 v[44:47], v[214:217], v[198:201], v[44:47]
	v_mfma_f32_16x16x32_bf16 v[40:43], v[234:237], v[198:201], v[40:43]
	v_mfma_f32_16x16x32_bf16 v[36:39], v[214:217], v[206:209], v[36:39]
	v_mfma_f32_16x16x32_bf16 v[32:35], v[234:237], v[206:209], v[32:35]
	v_mfma_f32_16x16x32_bf16 v[60:63], v[230:233], v[148:151], v[60:63]
	s_mov_b32 m0, s34
	v_mfma_f32_16x16x32_bf16 v[56:59], v[238:241], v[148:151], v[56:59]
	v_lshl_add_u64 v[242:243], s[26:27], 0, v[188:189]
	v_mfma_f32_16x16x32_bf16 v[52:55], v[230:233], v[194:197], v[52:55]
	v_mfma_f32_16x16x32_bf16 v[48:51], v[238:241], v[194:197], v[48:51]
	v_mfma_f32_16x16x32_bf16 v[44:47], v[230:233], v[202:205], v[44:47]
	v_mfma_f32_16x16x32_bf16 v[40:43], v[238:241], v[202:205], v[40:43]
	v_mfma_f32_16x16x32_bf16 v[36:39], v[230:233], v[210:213], v[36:39]
	s_setprio 0
	v_mfma_f32_16x16x32_bf16 v[32:35], v[238:241], v[210:213], v[32:35]
	s_barrier
	ds_read_b128 v[144:147], v228 offset:16384
	ds_read_b128 v[148:151], v228 offset:17408
	ds_read_b128 v[152:155], v228 offset:18432
	ds_read_b128 v[194:197], v228 offset:19456
	ds_read_b128 v[198:201], v228 offset:20480
	ds_read_b128 v[202:205], v228 offset:21504
	ds_read_b128 v[206:209], v228 offset:22528
	ds_read_b128 v[210:213], v228 offset:23552
	global_load_lds_dwordx4 v[242:243], off
	v_lshl_add_u64 v[244:245], s[26:27], 0, v[186:187]
	s_mov_b32 m0, s35
	s_nop 0
	global_load_lds_dwordx4 v[244:245], off
	s_waitcnt lgkmcnt(0)
	s_setprio 1
	s_barrier
	v_mfma_f32_16x16x32_bf16 v[92:95], v[128:131], v[144:147], v[92:95]
	v_mfma_f32_16x16x32_bf16 v[88:91], v[136:139], v[144:147], v[88:91]
	v_mfma_f32_16x16x32_bf16 v[84:87], v[128:131], v[152:155], v[84:87]
	v_mfma_f32_16x16x32_bf16 v[80:83], v[136:139], v[152:155], v[80:83]
	v_mfma_f32_16x16x32_bf16 v[76:79], v[128:131], v[198:201], v[76:79]
	v_mfma_f32_16x16x32_bf16 v[72:75], v[136:139], v[198:201], v[72:75]
	v_mfma_f32_16x16x32_bf16 v[68:71], v[128:131], v[206:209], v[68:71]
	v_mfma_f32_16x16x32_bf16 v[64:67], v[136:139], v[206:209], v[64:67]
	v_mfma_f32_16x16x32_bf16 v[92:95], v[132:135], v[148:151], v[92:95]
	v_mfma_f32_16x16x32_bf16 v[88:91], v[140:143], v[148:151], v[88:91]
	v_mfma_f32_16x16x32_bf16 v[84:87], v[132:135], v[194:197], v[84:87]
	v_mfma_f32_16x16x32_bf16 v[80:83], v[140:143], v[194:197], v[80:83]
	v_mfma_f32_16x16x32_bf16 v[76:79], v[132:135], v[202:205], v[76:79]
	v_mfma_f32_16x16x32_bf16 v[72:75], v[140:143], v[202:205], v[72:75]
	v_mfma_f32_16x16x32_bf16 v[68:71], v[132:135], v[210:213], v[68:71]
	s_setprio 0
	v_mfma_f32_16x16x32_bf16 v[64:67], v[140:143], v[210:213], v[64:67]
	s_barrier
; #define PG8_STAGE(bufoff, gbase) do { _Pragma("unroll") for (int _i = 0; _i < 2; ++_i) \
;         __builtin_amdgcn_global_load_lds((const unsigned*)((const char*)(gbase) + voff[_i]), (LAS unsigned*)(lds + (bufoff) + ldsw + _i * 8192), 16, 0, 0); } while (0)
; #define PG8_LDA(dst, b, h) do { _Pragma("unroll") for (int m = 0; m < 4; ++m) _Pragma("unroll") for (int k = 0; k < 2; ++k) dst[m][k] = *(const LAS bf16x8*)(lds + PG8_SA(b, h) + aoff + m * 2048 + k * 1024); } while (0)
; #define PG8_LDB(dst, b, h) do { _Pragma("unroll") for (int n = 0; n < 2; ++n) _Pragma("unroll") for (int k = 0; k < 2; ++k) dst[n][k] = *(const LAS bf16x8*)(lds + PG8_SB(b, h) + boff + n * 2048 + k * 1024); } while (0)
; #define PG8_MMA(ai, bj, At, Bt) do { __builtin_amdgcn_s_setprio(1); _Pragma("unroll") for (int m = 0; m < 4; ++m) _Pragma("unroll") for (int n = 0; n < 2; ++n) _Pragma("unroll") for (int k = 0; k < 2; ++k) \
;         acc[ai][bj][m][n] = __builtin_amdgcn_mfma_f32_16x16x32_bf16(Bt[n][k], At[m][k], acc[ai][bj][m][n], 0, 0, 0); __builtin_amdgcn_s_setprio(0); } while (0)
; #define PG8_WAIT_V(n) asm volatile("s_waitcnt vmcnt(" #n ")" ::: "memory")
; #define PG8_WAIT_L(n) asm volatile("s_waitcnt lgkmcnt(" #n ")" ::: "memory")
; #define PG8_BAR __builtin_amdgcn_s_barrier()
; #define PG8_SCHED __builtin_amdgcn_sched_barrier(0)
; template <class Epi>
; DI void gemm_phase(LAS unsigned char* lds, const Gemm g, const StaticOrder& S, const Epi& E) {
;     ...
;             PG8_STAGE(PG8_SB(0, 1), b2 + hstep);
;             PG8_WAIT_V(6); PG8_BAR; PG8_MMA(1, 1, At, B1); PG8_BAR;
;             PG8_LDB(B0, 1, 0); PG8_SCHED; PG8_LDA(At, 1, 0); PG8_STAGE(PG8_SA(0, 1), a2 + hstep);
;             PG8_WAIT_L(8); PG8_BAR; PG8_WAIT_L(0); PG8_MMA(0, 0, At, B0); PG8_BAR; PG8_SCHED;
;             PG8_LDB(B1, 1, 1); PG8_STAGE(PG8_SB(1, 0), b3);
;             PG8_BAR; PG8_WAIT_L(0); PG8_MMA(0, 1, At, B1); PG8_BAR;
;             PG8_LDA(At, 1, 1); PG8_STAGE(PG8_SA(1, 0), a3);
;             PG8_BAR; PG8_WAIT_L(0); PG8_MMA(1, 0, At, B0); PG8_BAR; PG8_SCHED;
	s_add_u32 s20, s24, 0x90000
	s_addc_u32 s21, s25, 0
	s_add_i32 s43, s44, s31
	v_lshl_add_u64 v[128:129], s[20:21], 0, v[188:189]
	s_mov_b32 m0, s43
	s_nop 0
	global_load_lds_dwordx4 v[128:129], off
	v_lshl_add_u64 v[128:129], s[20:21], 0, v[186:187]
	s_add_i32 m0, s43, 0x2000
	s_nop 0
	global_load_lds_dwordx4 v[128:129], off
	s_waitcnt vmcnt(6)
	s_setprio 1
	s_barrier
	v_mfma_f32_16x16x32_bf16 v[28:31], v[214:217], v[144:147], v[28:31]
	v_mfma_f32_16x16x32_bf16 v[24:27], v[234:237], v[144:147], v[24:27]
	v_mfma_f32_16x16x32_bf16 v[20:23], v[214:217], v[152:155], v[20:23]
	v_mfma_f32_16x16x32_bf16 v[16:19], v[234:237], v[152:155], v[16:19]
	v_mfma_f32_16x16x32_bf16 v[12:15], v[214:217], v[198:201], v[12:15]
	v_mfma_f32_16x16x32_bf16 v[8:11], v[234:237], v[198:201], v[8:11]
	v_mfma_f32_16x16x32_bf16 v[4:7], v[214:217], v[206:209], v[4:7]
	v_mfma_f32_16x16x32_bf16 v[0:3], v[234:237], v[206:209], v[0:3]
	v_mfma_f32_16x16x32_bf16 v[28:31], v[230:233], v[148:151], v[28:31]
	s_add_i32 s43, 0, 0x18000
	v_mfma_f32_16x16x32_bf16 v[24:27], v[238:241], v[148:151], v[24:27]
	v_mfma_f32_16x16x32_bf16 v[20:23], v[230:233], v[194:197], v[20:23]
	v_mfma_f32_16x16x32_bf16 v[16:19], v[238:241], v[194:197], v[16:19]
	v_mfma_f32_16x16x32_bf16 v[12:15], v[230:233], v[202:205], v[12:15]
	v_mfma_f32_16x16x32_bf16 v[8:11], v[238:241], v[202:205], v[8:11]
	v_mfma_f32_16x16x32_bf16 v[4:7], v[230:233], v[210:213], v[4:7]
	s_setprio 0
	v_mfma_f32_16x16x32_bf16 v[0:3], v[238:241], v[210:213], v[0:3]
	s_barrier
	ds_read_b128 v[128:131], v226 offset:32768
	ds_read_b128 v[132:135], v226 offset:33792
	ds_read_b128 v[136:139], v226 offset:34816
	ds_read_b128 v[140:143], v226 offset:35840
	s_add_u32 s20, s26, 0x90000
	s_addc_u32 s21, s27, 0
	s_mov_b32 m0, s36
	v_lshl_add_u64 v[214:215], s[20:21], 0, v[188:189]
	ds_read_b128 v[144:147], v228 offset:32768
	ds_read_b128 v[148:151], v228 offset:33792
	ds_read_b128 v[152:155], v228 offset:34816
	ds_read_b128 v[194:197], v228 offset:35840
	ds_read_b128 v[198:201], v228 offset:36864
	ds_read_b128 v[202:205], v228 offset:37888
	ds_read_b128 v[206:209], v228 offset:38912
	ds_read_b128 v[210:213], v228 offset:39936
	global_load_lds_dwordx4 v[214:215], off
	v_lshl_add_u64 v[214:215], s[20:21], 0, v[186:187]
	s_mov_b32 m0, s37
	s_nop 0
	global_load_lds_dwordx4 v[214:215], off
	s_waitcnt lgkmcnt(8)
	s_setprio 1
	s_barrier
	s_waitcnt lgkmcnt(0)
	v_mfma_f32_16x16x32_bf16 v[124:127], v[128:131], v[144:147], v[124:127]
	v_mfma_f32_16x16x32_bf16 v[120:123], v[136:139], v[144:147], v[120:123]
	v_mfma_f32_16x16x32_bf16 v[116:119], v[128:131], v[152:155], v[116:119]
	v_mfma_f32_16x16x32_bf16 v[112:115], v[136:139], v[152:155], v[112:115]
	v_mfma_f32_16x16x32_bf16 v[108:111], v[128:131], v[198:201], v[108:111]
	v_mfma_f32_16x16x32_bf16 v[104:107], v[136:139], v[198:201], v[104:107]
	v_mfma_f32_16x16x32_bf16 v[100:103], v[128:131], v[206:209], v[100:103]
	v_mfma_f32_16x16x32_bf16 v[96:99], v[136:139], v[206:209], v[96:99]
	v_mfma_f32_16x16x32_bf16 v[124:127], v[132:135], v[148:151], v[124:127]
	v_mfma_f32_16x16x32_bf16 v[120:123], v[140:143], v[148:151], v[120:123]
	v_mfma_f32_16x16x32_bf16 v[116:119], v[132:135], v[194:197], v[116:119]
	v_mfma_f32_16x16x32_bf16 v[112:115], v[140:143], v[194:197], v[112:115]
	v_mfma_f32_16x16x32_bf16 v[108:111], v[132:135], v[202:205], v[108:111]
	v_mfma_f32_16x16x32_bf16 v[104:107], v[140:143], v[202:205], v[104:107]
	v_mfma_f32_16x16x32_bf16 v[100:103], v[132:135], v[210:213], v[100:103]
	s_setprio 0
	v_mfma_f32_16x16x32_bf16 v[96:99], v[140:143], v[210:213], v[96:99]
	s_barrier
	s_add_i32 s26, 0, 0x1c000
	s_add_i32 s20, s43, s31
	v_lshl_add_u64 v[218:219], v[218:219], 0, s[94:95]
	s_mov_b32 m0, s20
	ds_read_b128 v[214:217], v226 offset:49152
	ds_read_b128 v[230:233], v226 offset:50176
	ds_read_b128 v[234:237], v226 offset:51200
	ds_read_b128 v[238:241], v226 offset:52224
	global_load_lds_dwordx4 v[218:219], off
	v_lshl_add_u64 v[218:219], v[220:221], 0, s[94:95]
	s_add_i32 m0, s20, 0x2000
	s_nop 0
	global_load_lds_dwordx4 v[218:219], off
	s_waitcnt lgkmcnt(0)
	s_setprio 1
	s_barrier
	v_mfma_f32_16x16x32_bf16 v[60:63], v[214:217], v[144:147], v[60:63]
	v_mfma_f32_16x16x32_bf16 v[56:59], v[234:237], v[144:147], v[56:59]
	v_mfma_f32_16x16x32_bf16 v[52:55], v[214:217], v[152:155], v[52:55]
	v_mfma_f32_16x16x32_bf16 v[48:51], v[234:237], v[152:155], v[48:51]
	v_mfma_f32_16x16x32_bf16 v[44:47], v[214:217], v[198:201], v[44:47]
	v_mfma_f32_16x16x32_bf16 v[40:43], v[234:237], v[198:201], v[40:43]
	v_mfma_f32_16x16x32_bf16 v[36:39], v[214:217], v[206:209], v[36:39]
	v_mfma_f32_16x16x32_bf16 v[32:35], v[234:237], v[206:209], v[32:35]
	v_mfma_f32_16x16x32_bf16 v[60:63], v[230:233], v[148:151], v[60:63]
	s_mov_b32 m0, s38
	v_mfma_f32_16x16x32_bf16 v[56:59], v[238:241], v[148:151], v[56:59]
	v_lshl_add_u64 v[218:219], v[242:243], 0, s[94:95]
	v_mfma_f32_16x16x32_bf16 v[52:55], v[230:233], v[194:197], v[52:55]
	v_mfma_f32_16x16x32_bf16 v[48:51], v[238:241], v[194:197], v[48:51]
	v_mfma_f32_16x16x32_bf16 v[44:47], v[230:233], v[202:205], v[44:47]
	v_mfma_f32_16x16x32_bf16 v[40:43], v[238:241], v[202:205], v[40:43]
	v_mfma_f32_16x16x32_bf16 v[36:39], v[230:233], v[210:213], v[36:39]
	s_setprio 0
	v_mfma_f32_16x16x32_bf16 v[32:35], v[238:241], v[210:213], v[32:35]
	s_barrier
	ds_read_b128 v[144:147], v228 offset:49152
	ds_read_b128 v[148:151], v228 offset:50176
	ds_read_b128 v[152:155], v228 offset:51200
	ds_read_b128 v[194:197], v228 offset:52224
	ds_read_b128 v[198:201], v228 offset:53248
	ds_read_b128 v[202:205], v228 offset:54272
	ds_read_b128 v[206:209], v228 offset:55296
	ds_read_b128 v[210:213], v228 offset:56320
	global_load_lds_dwordx4 v[218:219], off
	v_lshl_add_u64 v[218:219], v[244:245], 0, s[94:95]
	s_mov_b32 m0, s39
	s_nop 0
	global_load_lds_dwordx4 v[218:219], off
	s_waitcnt lgkmcnt(0)
	s_setprio 1
	s_barrier
; #define PG8_BAR __builtin_amdgcn_s_barrier()
; template <class Epi>
; DI void gemm_phase(LAS unsigned char* lds, const Gemm g, const StaticOrder& S, const Epi& E) {
;     ...
;             PG8_BAR; PG8_WAIT_L(0); PG8_MMA(1, 0, At, B0); PG8_BAR; PG8_SCHED;
;             PG8_STAGE(PG8_SB(1, 1), b3 + hstep);
;             PG8_WAIT_V(6); PG8_BAR; PG8_MMA(1, 1, At, B1); PG8_BAR;
;     template <bool LN, int BJ, int LO, int HI> DI void batch(const f32x4 (&acc)[2][2][4][2], unsigned row0, unsigned col0, const f32x4 (&gv)[2], const f32x4 (&bv)[2]) const {
;         f32x4 r[HI - LO]; float mean[(HI - LO) / 2], rstd[(HI - LO) / 2];
; #pragma unroll
;         for (int i = LO; i < HI; ++i) { const int ai = i >> 3, m = (i >> 1) & 3, n = i & 1; const unsigned row = row0 + ai * HALF + m * 16;
;             if (n == 0) { mean[(i - LO) >> 1] = 0.f; rstd[(i - LO) >> 1] = 1.f;
;                 if (LN) { const float2 st = *(const float2*)(stats + row * 2u); mean[(i - LO) >> 1] = st.x; rstd[(i - LO) >> 1] = st.y; } }
;             r[i - LO] = *(const f32x4*)(src + (row * (unsigned)DM + col0 + BJ * HALF + n * 16)); }
; #pragma unroll
;         for (int i = LO; i < HI; ++i) { const int ai = i >> 3, m = (i >> 1) & 3, n = i & 1; const unsigned row = row0 + ai * HALF + m * 16;
;             *(f32x4*)(Y + (row * (unsigned)DM + col0 + BJ * HALF + n * 16)) = acc[ai][BJ][m][n] + ((r[i - LO] - mean[(i - LO) >> 1]) * rstd[(i - LO) >> 1]) * gv[n] + bv[n]; }
;         __builtin_amdgcn_sched_barrier(0);
;     }
;     template <bool LN, int BJ> DI void load_gb(unsigned col0, f32x4 (&gv)[2], f32x4 (&bv)[2]) const {
; #pragma unroll
;         for (int n = 0; n < 2; ++n) {
;             if (LN) { gv[n] = *(const f32x4*)(gam + col0 + BJ * HALF + n * 16) * ALPHA; bv[n] = *(const f32x4*)(bet + col0 + BJ * HALF + n * 16) * ALPHA; }
;             else { gv[n] = (f32x4){ALPHA, ALPHA, ALPHA, ALPHA}; bv[n] = (f32x4){0.f, 0.f, 0.f, 0.f}; }
;         }
;     }
;     template <bool LN> DI void run(const f32x4 (&acc)[2][2][4][2], const Unit& u, int wr, int wc, int fr, int fq) const {
;         const unsigned row0 = u.pm * BM + wr * 64 + fr, col0 = u.pn * BM + wc * 32 + 4 * fq;
;         f32x4 gv[2], bv[2];
;         load_gb<LN, 0>(col0, gv, bv);
;         batch<LN, 0, 0, 4>(acc, row0, col0, gv, bv);
;         batch<LN, 0, 4, 8>(acc, row0, col0, gv, bv);
;         batch<LN, 0, 8, 12>(acc, row0, col0, gv, bv);
	v_mfma_f32_16x16x32_bf16 v[92:95], v[128:131], v[144:147], v[92:95]
	v_mfma_f32_16x16x32_bf16 v[88:91], v[136:139], v[144:147], v[88:91]
	v_mfma_f32_16x16x32_bf16 v[84:87], v[128:131], v[152:155], v[84:87]
	v_mfma_f32_16x16x32_bf16 v[80:83], v[136:139], v[152:155], v[80:83]
	v_mfma_f32_16x16x32_bf16 v[76:79], v[128:131], v[198:201], v[76:79]
	v_mfma_f32_16x16x32_bf16 v[72:75], v[136:139], v[198:201], v[72:75]
	v_mfma_f32_16x16x32_bf16 v[68:71], v[128:131], v[206:209], v[68:71]
	v_mfma_f32_16x16x32_bf16 v[64:67], v[136:139], v[206:209], v[64:67]
	v_mfma_f32_16x16x32_bf16 v[92:95], v[132:135], v[148:151], v[92:95]
	v_mfma_f32_16x16x32_bf16 v[88:91], v[140:143], v[148:151], v[88:91]
	v_mfma_f32_16x16x32_bf16 v[84:87], v[132:135], v[194:197], v[84:87]
	v_mfma_f32_16x16x32_bf16 v[80:83], v[140:143], v[194:197], v[80:83]
	v_mfma_f32_16x16x32_bf16 v[76:79], v[132:135], v[202:205], v[76:79]
	v_mfma_f32_16x16x32_bf16 v[72:75], v[140:143], v[202:205], v[72:75]
	v_mfma_f32_16x16x32_bf16 v[68:71], v[132:135], v[210:213], v[68:71]
	s_setprio 0
	v_mfma_f32_16x16x32_bf16 v[64:67], v[140:143], v[210:213], v[64:67]
	s_barrier
	s_add_u32 s20, s24, 0x90080
	s_addc_u32 s21, s25, 0
	s_add_i32 s24, s26, s31
	v_lshl_add_u64 v[128:129], s[20:21], 0, v[188:189]
	s_mov_b32 m0, s24
	s_nop 0
	global_load_lds_dwordx4 v[128:129], off
	v_lshl_add_u64 v[128:129], s[20:21], 0, v[186:187]
	s_add_i32 m0, s24, 0x2000
	s_nop 0
	global_load_lds_dwordx4 v[128:129], off
	s_waitcnt vmcnt(6)
	s_setprio 1
	s_barrier
	v_mfma_f32_16x16x32_bf16 v[28:31], v[214:217], v[144:147], v[28:31]
	v_mfma_f32_16x16x32_bf16 v[24:27], v[234:237], v[144:147], v[24:27]
	v_mfma_f32_16x16x32_bf16 v[20:23], v[214:217], v[152:155], v[20:23]
	v_mfma_f32_16x16x32_bf16 v[16:19], v[234:237], v[152:155], v[16:19]
	v_mfma_f32_16x16x32_bf16 v[12:15], v[214:217], v[198:201], v[12:15]
	v_mfma_f32_16x16x32_bf16 v[8:11], v[234:237], v[198:201], v[8:11]
	v_mfma_f32_16x16x32_bf16 v[4:7], v[214:217], v[206:209], v[4:7]
	v_mfma_f32_16x16x32_bf16 v[0:3], v[234:237], v[206:209], v[0:3]
	v_mfma_f32_16x16x32_bf16 v[28:31], v[230:233], v[148:151], v[28:31]
	s_add_i32 s33, s33, 2
	v_mfma_f32_16x16x32_bf16 v[24:27], v[238:241], v[148:151], v[24:27]
	s_add_u32 s4, s4, 0x100
	v_mfma_f32_16x16x32_bf16 v[20:23], v[230:233], v[194:197], v[20:23]
	s_addc_u32 s5, s5, 0
	v_mfma_f32_16x16x32_bf16 v[16:19], v[238:241], v[194:197], v[16:19]
	s_cmp_gt_u32 s33, 33
	v_mfma_f32_16x16x32_bf16 v[12:15], v[230:233], v[202:205], v[12:15]
	s_mov_b64 s[20:21], s[22:23]
	v_mfma_f32_16x16x32_bf16 v[8:11], v[238:241], v[202:205], v[8:11]
	v_mfma_f32_16x16x32_bf16 v[4:7], v[230:233], v[210:213], v[4:7]
	s_setprio 0
	v_mfma_f32_16x16x32_bf16 v[0:3], v[238:241], v[210:213], v[0:3]
	s_barrier
	s_cbranch_scc0 .LBB0_77
	v_lshl_add_u32 v206, s3, 8, v225
	v_lshl_or_b32 v158, s2, 8, v227
	v_lshlrev_b32_e32 v232, 11, v206
	s_andn2_b64 vcc, exec, s[14:15]
	v_or_b32_e32 v231, 16, v158
	v_add_u32_e32 v194, v232, v158
	v_or_b32_e32 v230, 0x80, v158
	v_or_b32_e32 v229, 0x90, v158
	s_cbranch_vccnz .LBB0_80
	v_lshlrev_b64 v[132:133], 2, v[158:159]
	v_lshl_add_u64 v[140:141], s[16:17], 0, v[132:133]
	global_load_dwordx4 v[128:131], v[140:141], off
	v_lshl_add_u64 v[142:143], s[18:19], 0, v[132:133]
	v_readlane_b32 s2, v253, 8
	v_mov_b32_e32 v195, v159
	v_lshlrev_b32_e32 v136, 1, v206
	v_mov_b32_e32 v137, v159
	v_readlane_b32 s3, v253, 9
	v_lshlrev_b64 v[212:213], 2, v[194:195]
	v_add_u32_e32 v146, v232, v231
	v_lshl_add_u64 v[144:145], v[136:137], 2, s[2:3]
	v_lshl_add_u64 v[136:137], s[88:89], 0, v[212:213]
	v_mov_b32_e32 v147, v159
	v_lshl_add_u64 v[146:147], v[146:147], 2, s[88:89]
	v_or_b32_e32 v195, 16, v206
	v_mov_b32_e32 v201, v159
	v_mov_b32_e32 v209, v159
	v_lshl_add_u64 v[212:213], s[90:91], 0, v[212:213]
	s_waitcnt vmcnt(0)
	v_pk_mul_f32 v[152:153], v[130:131], s[78:79] op_sel_hi:[1,0]
	v_pk_mul_f32 v[154:155], v[128:129], s[78:79] op_sel_hi:[1,0]
	global_load_dwordx4 v[132:135], v[142:143], off
	global_load_dwordx4 v[128:131], v[140:141], off offset:64
	global_load_dwordx2 v[204:205], v[144:145], off
	global_load_dwordx4 v[196:199], v[146:147], off
	v_lshlrev_b32_e32 v146, 1, v195
	global_load_dwordx4 v[136:139], v[136:137], off
	v_lshlrev_b32_e32 v195, 11, v195
	v_mov_b32_e32 v147, v159
	v_add_u32_e32 v200, v195, v158
	v_lshl_add_u64 v[146:147], v[146:147], 2, s[2:3]
	v_lshl_add_u64 v[200:201], v[200:201], 2, s[88:89]
	global_load_dwordx2 v[214:215], v[146:147], off
	v_add_u32_e32 v208, v195, v231
	global_load_dwordx4 v[200:203], v[200:201], off
	v_lshl_add_u64 v[208:209], v[208:209], 2, s[88:89]
	global_load_dwordx4 v[208:211], v[208:209], off
	s_waitcnt vmcnt(0)
	v_pk_mul_f32 v[148:149], v[130:131], s[78:79] op_sel_hi:[1,0]
	v_pk_mul_f32 v[150:151], v[128:129], s[78:79] op_sel_hi:[1,0]
	global_load_dwordx4 v[128:131], v[142:143], off offset:64
	v_sub_f32_e32 v137, v137, v204
	v_sub_f32_e32 v136, v136, v204
	v_sub_f32_e32 v139, v139, v204
	v_sub_f32_e32 v138, v138, v204
	v_pk_mul_f32 v[138:139], v[204:205], v[138:139] op_sel:[1,0]
	v_pk_mul_f32 v[136:137], v[204:205], v[136:137] op_sel:[1,0]
	v_pk_fma_f32 v[138:139], v[152:153], v[138:139], v[126:127]
	v_pk_fma_f32 v[136:137], v[154:155], v[136:137], v[124:125]
	v_pk_fma_f32 v[138:139], v[134:135], s[78:79], v[138:139] op_sel_hi:[1,0,1]
	v_pk_fma_f32 v[136:137], v[132:133], s[78:79], v[136:137] op_sel_hi:[1,0,1]
	global_store_dwordx4 v[212:213], v[136:139], off
	s_nop 1
	v_sub_f32_e32 v137, v197, v204
	v_sub_f32_e32 v136, v196, v204
	v_sub_f32_e32 v139, v199, v204
	v_sub_f32_e32 v138, v198, v204
	v_pk_mul_f32 v[138:139], v[204:205], v[138:139] op_sel:[1,0]
	v_pk_mul_f32 v[136:137], v[204:205], v[136:137] op_sel:[1,0]
	v_pk_fma_f32 v[138:139], v[148:149], v[138:139], v[122:123]
	v_pk_fma_f32 v[136:137], v[150:151], v[136:137], v[120:121]
	v_or_b32_e32 v196, 16, v194
	v_mov_b32_e32 v197, v159
	v_lshl_add_u64 v[196:197], v[196:197], 2, s[90:91]
	s_waitcnt vmcnt(0)
;     template <bool LN, int BJ, int LO, int HI> DI void batch(const f32x4 (&acc)[2][2][4][2], unsigned row0, unsigned col0, const f32x4 (&gv)[2], const f32x4 (&bv)[2]) const {
;         f32x4 r[HI - LO]; float mean[(HI - LO) / 2], rstd[(HI - LO) / 2];
; #pragma unroll
;         for (int i = LO; i < HI; ++i) { const int ai = i >> 3, m = (i >> 1) & 3, n = i & 1; const unsigned row = row0 + ai * HALF + m * 16;
;             if (n == 0) { mean[(i - LO) >> 1] = 0.f; rstd[(i - LO) >> 1] = 1.f;
;                 if (LN) { const float2 st = *(const float2*)(stats + row * 2u); mean[(i - LO) >> 1] = st.x; rstd[(i - LO) >> 1] = st.y; } }
;             r[i - LO] = *(const f32x4*)(src + (row * (unsigned)DM + col0 + BJ * HALF + n * 16)); }
; #pragma unroll
;         for (int i = LO; i < HI; ++i) { const int ai = i >> 3, m = (i >> 1) & 3, n = i & 1; const unsigned row = row0 + ai * HALF + m * 16;
;             *(f32x4*)(Y + (row * (unsigned)DM + col0 + BJ * HALF + n * 16)) = acc[ai][BJ][m][n] + ((r[i - LO] - mean[(i - LO) >> 1]) * rstd[(i - LO) >> 1]) * gv[n] + bv[n]; }
;         __builtin_amdgcn_sched_barrier(0);
;     }
;     template <bool LN, int BJ> DI void load_gb(unsigned col0, f32x4 (&gv)[2], f32x4 (&bv)[2]) const {
; #pragma unroll
;         for (int n = 0; n < 2; ++n) {
;             if (LN) { gv[n] = *(const f32x4*)(gam + col0 + BJ * HALF + n * 16) * ALPHA; bv[n] = *(const f32x4*)(bet + col0 + BJ * HALF + n * 16) * ALPHA; }
;             else { gv[n] = (f32x4){ALPHA, ALPHA, ALPHA, ALPHA}; bv[n] = (f32x4){0.f, 0.f, 0.f, 0.f}; }
;         }
;     }
	v_pk_fma_f32 v[138:139], v[130:131], s[78:79], v[138:139] op_sel_hi:[1,0,1]
	v_pk_fma_f32 v[136:137], v[128:129], s[78:79], v[136:137] op_sel_hi:[1,0,1]
	global_store_dwordx4 v[196:197], v[136:139], off
	v_add_u32_e32 v196, 0x8000, v194
	v_mov_b32_e32 v197, v159
	v_sub_f32_e32 v137, v201, v214
	v_sub_f32_e32 v136, v200, v214
	v_sub_f32_e32 v139, v203, v214
	v_sub_f32_e32 v138, v202, v214
	v_pk_mul_f32 v[138:139], v[214:215], v[138:139] op_sel:[1,0]
	v_pk_mul_f32 v[136:137], v[214:215], v[136:137] op_sel:[1,0]
	v_pk_fma_f32 v[138:139], v[152:153], v[138:139], v[118:119]
	v_pk_fma_f32 v[136:137], v[154:155], v[136:137], v[116:117]
	v_pk_fma_f32 v[138:139], v[134:135], s[78:79], v[138:139] op_sel_hi:[1,0,1]
	v_pk_fma_f32 v[136:137], v[132:133], s[78:79], v[136:137] op_sel_hi:[1,0,1]
	v_lshl_add_u64 v[196:197], v[196:197], 2, s[90:91]
	global_store_dwordx4 v[196:197], v[136:139], off
	v_add_u32_e32 v196, 0x8010, v194
	v_mov_b32_e32 v197, v159
	v_sub_f32_e32 v137, v209, v214
	v_sub_f32_e32 v136, v208, v214
	v_sub_f32_e32 v139, v211, v214
	v_sub_f32_e32 v138, v210, v214
	v_pk_mul_f32 v[138:139], v[214:215], v[138:139] op_sel:[1,0]
	v_pk_mul_f32 v[136:137], v[214:215], v[136:137] op_sel:[1,0]
	v_pk_fma_f32 v[138:139], v[148:149], v[138:139], v[114:115]
	v_pk_fma_f32 v[136:137], v[150:151], v[136:137], v[112:113]
	v_pk_fma_f32 v[138:139], v[130:131], s[78:79], v[138:139] op_sel_hi:[1,0,1]
	v_pk_fma_f32 v[136:137], v[128:129], s[78:79], v[136:137] op_sel_hi:[1,0,1]
	v_lshl_add_u64 v[196:197], v[196:197], 2, s[90:91]
	global_store_dwordx4 v[196:197], v[136:139], off
	s_nop 1
	v_or_b32_e32 v138, 32, v206
	v_lshlrev_b32_e32 v136, 1, v138
	v_mov_b32_e32 v137, v159
	v_lshlrev_b32_e32 v236, 11, v138
	v_lshl_add_u64 v[200:201], v[136:137], 2, s[2:3]
	v_add_u32_e32 v136, v236, v158
	v_lshl_add_u64 v[136:137], v[136:137], 2, s[88:89]
	global_load_dwordx2 v[204:205], v[200:201], off
	v_add_u32_e32 v196, v236, v231
	global_load_dwordx4 v[136:139], v[136:137], off
	v_mov_b32_e32 v197, v159
	v_lshl_add_u64 v[196:197], v[196:197], 2, s[88:89]
	global_load_dwordx4 v[196:199], v[196:197], off
	v_or_b32_e32 v207, 48, v206
	v_lshlrev_b32_e32 v235, 11, v207
	v_lshlrev_b32_e32 v202, 1, v207
	v_mov_b32_e32 v203, v159
	v_add_u32_e32 v208, v235, v158
	v_mov_b32_e32 v209, v159
	v_lshl_add_u64 v[202:203], v[202:203], 2, s[2:3]
	v_lshl_add_u64 v[208:209], v[208:209], 2, s[88:89]
	global_load_dwordx2 v[216:217], v[202:203], off
	v_add_u32_e32 v212, v235, v231
	global_load_dwordx4 v[208:211], v[208:209], off
	v_mov_b32_e32 v213, v159
	v_lshl_add_u64 v[212:213], v[212:213], 2, s[88:89]
	global_load_dwordx4 v[212:215], v[212:213], off
	v_add_u32_e32 v218, 0x10000, v194
	v_mov_b32_e32 v219, v159
	v_lshl_add_u64 v[218:219], v[218:219], 2, s[90:91]
	s_waitcnt vmcnt(0)
	v_sub_f32_e32 v137, v137, v204
	v_sub_f32_e32 v136, v136, v204
	v_sub_f32_e32 v139, v139, v204
	v_sub_f32_e32 v138, v138, v204
	v_pk_mul_f32 v[138:139], v[204:205], v[138:139] op_sel:[1,0]
	v_pk_mul_f32 v[136:137], v[204:205], v[136:137] op_sel:[1,0]
	v_pk_fma_f32 v[138:139], v[152:153], v[138:139], v[110:111]
	v_pk_fma_f32 v[136:137], v[154:155], v[136:137], v[108:109]
	v_pk_fma_f32 v[138:139], v[134:135], s[78:79], v[138:139] op_sel_hi:[1,0,1]
	v_pk_fma_f32 v[136:137], v[132:133], s[78:79], v[136:137] op_sel_hi:[1,0,1]
	global_store_dwordx4 v[218:219], v[136:139], off
	s_nop 1
	v_sub_f32_e32 v137, v197, v204
	v_sub_f32_e32 v136, v196, v204
	v_sub_f32_e32 v139, v199, v204
	v_sub_f32_e32 v138, v198, v204
	v_pk_mul_f32 v[138:139], v[204:205], v[138:139] op_sel:[1,0]
	v_pk_mul_f32 v[136:137], v[204:205], v[136:137] op_sel:[1,0]
	v_pk_fma_f32 v[138:139], v[148:149], v[138:139], v[106:107]
	v_pk_fma_f32 v[136:137], v[150:151], v[136:137], v[104:105]
	v_add_u32_e32 v196, 0x10010, v194
	v_mov_b32_e32 v197, v159
	v_pk_fma_f32 v[138:139], v[130:131], s[78:79], v[138:139] op_sel_hi:[1,0,1]
	v_pk_fma_f32 v[136:137], v[128:129], s[78:79], v[136:137] op_sel_hi:[1,0,1]
	v_lshl_add_u64 v[196:197], v[196:197], 2, s[90:91]
	global_store_dwordx4 v[196:197], v[136:139], off
	v_add_u32_e32 v196, 0x18000, v194
	v_mov_b32_e32 v197, v159
	v_sub_f32_e32 v137, v209, v216
	v_sub_f32_e32 v136, v208, v216
	v_sub_f32_e32 v139, v211, v216
	v_sub_f32_e32 v138, v210, v216
	v_pk_mul_f32 v[138:139], v[216:217], v[138:139] op_sel:[1,0]
	v_pk_mul_f32 v[136:137], v[216:217], v[136:137] op_sel:[1,0]
	v_pk_fma_f32 v[138:139], v[152:153], v[138:139], v[102:103]
	v_pk_fma_f32 v[136:137], v[154:155], v[136:137], v[100:101]
	v_pk_fma_f32 v[138:139], v[134:135], s[78:79], v[138:139] op_sel_hi:[1,0,1]
	v_pk_fma_f32 v[136:137], v[132:133], s[78:79], v[136:137] op_sel_hi:[1,0,1]
	v_lshl_add_u64 v[196:197], v[196:197], 2, s[90:91]
	global_store_dwordx4 v[196:197], v[136:139], off
	v_add_u32_e32 v196, 0x18010, v194
	v_mov_b32_e32 v197, v159
	v_sub_f32_e32 v137, v213, v216
	v_sub_f32_e32 v136, v212, v216
	v_sub_f32_e32 v139, v215, v216
	v_sub_f32_e32 v138, v214, v216
	v_pk_mul_f32 v[138:139], v[216:217], v[138:139] op_sel:[1,0]
	v_pk_mul_f32 v[136:137], v[216:217], v[136:137] op_sel:[1,0]
	v_pk_fma_f32 v[138:139], v[148:149], v[138:139], v[98:99]
	v_pk_fma_f32 v[136:137], v[150:151], v[136:137], v[96:97]
	v_pk_fma_f32 v[138:139], v[130:131], s[78:79], v[138:139] op_sel_hi:[1,0,1]
	v_pk_fma_f32 v[136:137], v[128:129], s[78:79], v[136:137] op_sel_hi:[1,0,1]
	v_lshl_add_u64 v[196:197], v[196:197], 2, s[90:91]
	global_store_dwordx4 v[196:197], v[136:139], off
	s_nop 1
	v_add_u32_e32 v138, 0x80, v206
	v_lshlrev_b32_e32 v136, 1, v138
	v_mov_b32_e32 v137, v159
	v_lshlrev_b32_e32 v233, 11, v138
	v_lshl_add_u64 v[196:197], v[136:137], 2, s[2:3]
	v_add_u32_e32 v136, v233, v158
	v_lshl_add_u64 v[136:137], v[136:137], 2, s[88:89]
	global_load_dwordx2 v[204:205], v[196:197], off
	v_add_u32_e32 v198, v233, v231
	global_load_dwordx4 v[136:139], v[136:137], off
	v_mov_b32_e32 v199, v159
	v_add_u32_e32 v207, 0x90, v206
	v_lshl_add_u64 v[198:199], v[198:199], 2, s[88:89]
	v_lshlrev_b32_e32 v234, 11, v207
	global_load_dwordx4 v[208:211], v[198:199], off
	v_add_u32_e32 v212, v234, v158
	v_mov_b32_e32 v213, v159
	v_lshl_add_u64 v[212:213], v[212:213], 2, s[88:89]
	global_load_dwordx4 v[212:215], v[212:213], off
	v_lshlrev_b32_e32 v198, 1, v207
	v_mov_b32_e32 v199, v159
	v_lshl_add_u64 v[198:199], v[198:199], 2, s[2:3]
	global_load_dwordx2 v[220:221], v[198:199], off
	v_add_u32_e32 v216, v234, v231
	v_mov_b32_e32 v217, v159
	v_lshl_add_u64 v[216:217], v[216:217], 2, s[88:89]
	global_load_dwordx4 v[216:219], v[216:217], off
	v_add_u32_e32 v238, 0x40000, v194
	v_mov_b32_e32 v239, v159
	v_lshl_add_u64 v[238:239], v[238:239], 2, s[90:91]
	s_waitcnt vmcnt(0)
;     template <bool LN, int BJ, int LO, int HI> DI void batch(const f32x4 (&acc)[2][2][4][2], unsigned row0, unsigned col0, const f32x4 (&gv)[2], const f32x4 (&bv)[2]) const {
;         f32x4 r[HI - LO]; float mean[(HI - LO) / 2], rstd[(HI - LO) / 2];
; #pragma unroll
;         for (int i = LO; i < HI; ++i) { const int ai = i >> 3, m = (i >> 1) & 3, n = i & 1; const unsigned row = row0 + ai * HALF + m * 16;
;             if (n == 0) { mean[(i - LO) >> 1] = 0.f; rstd[(i - LO) >> 1] = 1.f;
;                 if (LN) { const float2 st = *(const float2*)(stats + row * 2u); mean[(i - LO) >> 1] = st.x; rstd[(i - LO) >> 1] = st.y; } }
;             r[i - LO] = *(const f32x4*)(src + (row * (unsigned)DM + col0 + BJ * HALF + n * 16)); }
; #pragma unroll
;         for (int i = LO; i < HI; ++i) { const int ai = i >> 3, m = (i >> 1) & 3, n = i & 1; const unsigned row = row0 + ai * HALF + m * 16;
;             *(f32x4*)(Y + (row * (unsigned)DM + col0 + BJ * HALF + n * 16)) = acc[ai][BJ][m][n] + ((r[i - LO] - mean[(i - LO) >> 1]) * rstd[(i - LO) >> 1]) * gv[n] + bv[n]; }
	v_sub_f32_e32 v137, v137, v204
	v_sub_f32_e32 v136, v136, v204
	v_sub_f32_e32 v139, v139, v204
	v_sub_f32_e32 v138, v138, v204
	v_pk_mul_f32 v[138:139], v[204:205], v[138:139] op_sel:[1,0]
	v_pk_mul_f32 v[136:137], v[204:205], v[136:137] op_sel:[1,0]
	v_pk_fma_f32 v[138:139], v[152:153], v[138:139], v[94:95]
	v_pk_fma_f32 v[136:137], v[154:155], v[136:137], v[92:93]
	v_pk_fma_f32 v[138:139], v[134:135], s[78:79], v[138:139] op_sel_hi:[1,0,1]
	v_pk_fma_f32 v[136:137], v[132:133], s[78:79], v[136:137] op_sel_hi:[1,0,1]
	global_store_dwordx4 v[238:239], v[136:139], off
	s_nop 1
	v_sub_f32_e32 v137, v209, v204
	v_sub_f32_e32 v136, v208, v204
	v_sub_f32_e32 v139, v211, v204
	v_sub_f32_e32 v138, v210, v204
	v_pk_mul_f32 v[138:139], v[204:205], v[138:139] op_sel:[1,0]
	v_pk_mul_f32 v[136:137], v[204:205], v[136:137] op_sel:[1,0]
	v_pk_fma_f32 v[138:139], v[148:149], v[138:139], v[90:91]
	v_pk_fma_f32 v[136:137], v[150:151], v[136:137], v[88:89]
	v_add_u32_e32 v204, 0x40010, v194
	v_mov_b32_e32 v205, v159
	v_pk_fma_f32 v[138:139], v[130:131], s[78:79], v[138:139] op_sel_hi:[1,0,1]
	v_pk_fma_f32 v[136:137], v[128:129], s[78:79], v[136:137] op_sel_hi:[1,0,1]
	v_lshl_add_u64 v[204:205], v[204:205], 2, s[90:91]
	global_store_dwordx4 v[204:205], v[136:139], off
	v_add_u32_e32 v204, 0x48000, v194
	v_mov_b32_e32 v205, v159
	v_sub_f32_e32 v137, v213, v220
	v_sub_f32_e32 v136, v212, v220
	v_sub_f32_e32 v139, v215, v220
	v_sub_f32_e32 v138, v214, v220
	v_pk_mul_f32 v[138:139], v[220:221], v[138:139] op_sel:[1,0]
	v_pk_mul_f32 v[136:137], v[220:221], v[136:137] op_sel:[1,0]
	v_pk_fma_f32 v[138:139], v[152:153], v[138:139], v[86:87]
	v_pk_fma_f32 v[136:137], v[154:155], v[136:137], v[84:85]
	v_pk_fma_f32 v[138:139], v[134:135], s[78:79], v[138:139] op_sel_hi:[1,0,1]
	v_pk_fma_f32 v[136:137], v[132:133], s[78:79], v[136:137] op_sel_hi:[1,0,1]
	v_lshl_add_u64 v[204:205], v[204:205], 2, s[90:91]
	global_store_dwordx4 v[204:205], v[136:139], off
	v_add_u32_e32 v204, 0x48010, v194
	v_mov_b32_e32 v205, v159
	v_sub_f32_e32 v137, v217, v220
	v_sub_f32_e32 v136, v216, v220
	v_sub_f32_e32 v139, v219, v220
	v_sub_f32_e32 v138, v218, v220
	v_pk_mul_f32 v[138:139], v[220:221], v[138:139] op_sel:[1,0]
	v_pk_mul_f32 v[136:137], v[220:221], v[136:137] op_sel:[1,0]
	v_pk_fma_f32 v[138:139], v[148:149], v[138:139], v[82:83]
	v_pk_fma_f32 v[136:137], v[150:151], v[136:137], v[80:81]
	v_pk_fma_f32 v[138:139], v[130:131], s[78:79], v[138:139] op_sel_hi:[1,0,1]
	v_pk_fma_f32 v[136:137], v[128:129], s[78:79], v[136:137] op_sel_hi:[1,0,1]
	v_lshl_add_u64 v[204:205], v[204:205], 2, s[90:91]
	global_store_dwordx4 v[204:205], v[136:139], off
	s_nop 1
	v_add_u32_e32 v138, 0xa0, v206
	v_lshlrev_b32_e32 v136, 1, v138
	v_mov_b32_e32 v137, v159
	v_lshlrev_b32_e32 v237, 11, v138
	v_lshl_add_u64 v[204:205], v[136:137], 2, s[2:3]
	v_add_u32_e32 v136, v237, v158
	v_lshl_add_u64 v[136:137], v[136:137], 2, s[88:89]
	global_load_dwordx2 v[220:221], v[204:205], off
	v_add_u32_e32 v208, v237, v231
	global_load_dwordx4 v[136:139], v[136:137], off
	v_mov_b32_e32 v209, v159
	v_lshl_add_u64 v[208:209], v[208:209], 2, s[88:89]
	global_load_dwordx4 v[212:215], v[208:209], off
	v_add_u32_e32 v208, 0xb0, v206
	v_lshlrev_b32_e32 v206, 1, v208
	v_mov_b32_e32 v207, v159
	v_lshlrev_b32_e32 v238, 11, v208
	v_lshl_add_u64 v[210:211], v[206:207], 2, s[2:3]
	v_add_u32_e32 v206, v238, v158
	v_lshl_add_u64 v[206:207], v[206:207], 2, s[88:89]
	global_load_dwordx2 v[240:241], v[210:211], off
	v_add_u32_e32 v216, v238, v231
	global_load_dwordx4 v[206:209], v[206:207], off
	v_mov_b32_e32 v217, v159
	v_lshl_add_u64 v[216:217], v[216:217], 2, s[88:89]
	global_load_dwordx4 v[216:219], v[216:217], off
	v_add_u32_e32 v242, 0x50000, v194
	v_mov_b32_e32 v243, v159
	v_lshl_add_u64 v[242:243], v[242:243], 2, s[90:91]
	s_waitcnt vmcnt(0)
	v_sub_f32_e32 v137, v137, v220
	v_sub_f32_e32 v136, v136, v220
	v_sub_f32_e32 v139, v139, v220
	v_sub_f32_e32 v138, v138, v220
	v_pk_mul_f32 v[138:139], v[220:221], v[138:139] op_sel:[1,0]
	v_pk_mul_f32 v[136:137], v[220:221], v[136:137] op_sel:[1,0]
	v_pk_fma_f32 v[138:139], v[152:153], v[138:139], v[78:79]
	v_pk_fma_f32 v[136:137], v[154:155], v[136:137], v[76:77]
	v_pk_fma_f32 v[138:139], v[134:135], s[78:79], v[138:139] op_sel_hi:[1,0,1]
	v_pk_fma_f32 v[136:137], v[132:133], s[78:79], v[136:137] op_sel_hi:[1,0,1]
	global_store_dwordx4 v[242:243], v[136:139], off
	s_nop 1
	v_sub_f32_e32 v137, v213, v220
	v_sub_f32_e32 v136, v212, v220
	v_sub_f32_e32 v139, v215, v220
	v_sub_f32_e32 v138, v214, v220
	v_pk_mul_f32 v[138:139], v[220:221], v[138:139] op_sel:[1,0]
	v_pk_mul_f32 v[136:137], v[220:221], v[136:137] op_sel:[1,0]
	v_pk_fma_f32 v[138:139], v[148:149], v[138:139], v[74:75]
	v_pk_fma_f32 v[136:137], v[150:151], v[136:137], v[72:73]
	v_add_u32_e32 v212, 0x50010, v194
	v_mov_b32_e32 v213, v159
	v_pk_fma_f32 v[138:139], v[130:131], s[78:79], v[138:139] op_sel_hi:[1,0,1]
	v_pk_fma_f32 v[136:137], v[128:129], s[78:79], v[136:137] op_sel_hi:[1,0,1]
	v_lshl_add_u64 v[212:213], v[212:213], 2, s[90:91]
	global_store_dwordx4 v[212:213], v[136:139], off
	s_nop 1
	v_sub_f32_e32 v137, v207, v240
	v_sub_f32_e32 v136, v206, v240
	v_sub_f32_e32 v139, v209, v240
	v_sub_f32_e32 v138, v208, v240
	v_pk_mul_f32 v[136:137], v[240:241], v[136:137] op_sel:[1,0]
	v_pk_mul_f32 v[138:139], v[240:241], v[138:139] op_sel:[1,0]
	v_pk_fma_f32 v[136:137], v[154:155], v[136:137], v[68:69]
	v_pk_fma_f32 v[138:139], v[152:153], v[138:139], v[70:71]
	v_pk_fma_f32 v[132:133], v[132:133], s[78:79], v[136:137] op_sel_hi:[1,0,1]
	v_add_u32_e32 v136, 0x58000, v194
	v_mov_b32_e32 v137, v159
	v_pk_fma_f32 v[134:135], v[134:135], s[78:79], v[138:139] op_sel_hi:[1,0,1]
	v_lshl_add_u64 v[136:137], v[136:137], 2, s[90:91]
	global_store_dwordx4 v[136:137], v[132:135], off
	s_nop 1
	v_sub_f32_e32 v133, v217, v240
	v_sub_f32_e32 v132, v216, v240
	v_sub_f32_e32 v135, v219, v240
	v_sub_f32_e32 v134, v218, v240
	v_pk_mul_f32 v[132:133], v[240:241], v[132:133] op_sel:[1,0]
	v_pk_mul_f32 v[134:135], v[240:241], v[134:135] op_sel:[1,0]
	v_pk_fma_f32 v[132:133], v[150:151], v[132:133], v[64:65]
	v_pk_fma_f32 v[134:135], v[148:149], v[134:135], v[66:67]
	v_pk_fma_f32 v[128:129], v[128:129], s[78:79], v[132:133] op_sel_hi:[1,0,1]
	v_add_u32_e32 v132, 0x58010, v194
	v_mov_b32_e32 v133, v159
	v_pk_fma_f32 v[130:131], v[130:131], s[78:79], v[134:135] op_sel_hi:[1,0,1]
	v_lshl_add_u64 v[132:133], v[132:133], 2, s[90:91]
	global_store_dwordx4 v[132:133], v[128:131], off
	global_load_dwordx4 v[128:131], v[140:141], off offset:512
	v_add_u32_e32 v136, v232, v230
	v_mov_b32_e32 v137, v159
	v_lshl_add_u64 v[136:137], v[136:137], 2, s[88:89]
	s_waitcnt vmcnt(0)
;     template <bool LN, int BJ, int LO, int HI> DI void batch(const f32x4 (&acc)[2][2][4][2], unsigned row0, unsigned col0, const f32x4 (&gv)[2], const f32x4 (&bv)[2]) const {
;         f32x4 r[HI - LO]; float mean[(HI - LO) / 2], rstd[(HI - LO) / 2];
; #pragma unroll
;         for (int i = LO; i < HI; ++i) { const int ai = i >> 3, m = (i >> 1) & 3, n = i & 1; const unsigned row = row0 + ai * HALF + m * 16;
;             if (n == 0) { mean[(i - LO) >> 1] = 0.f; rstd[(i - LO) >> 1] = 1.f;
;                 if (LN) { const float2 st = *(const float2*)(stats + row * 2u); mean[(i - LO) >> 1] = st.x; rstd[(i - LO) >> 1] = st.y; } }
;             r[i - LO] = *(const f32x4*)(src + (row * (unsigned)DM + col0 + BJ * HALF + n * 16)); }
; #pragma unroll
;         for (int i = LO; i < HI; ++i) { const int ai = i >> 3, m = (i >> 1) & 3, n = i & 1; const unsigned row = row0 + ai * HALF + m * 16;
;             *(f32x4*)(Y + (row * (unsigned)DM + col0 + BJ * HALF + n * 16)) = acc[ai][BJ][m][n] + ((r[i - LO] - mean[(i - LO) >> 1]) * rstd[(i - LO) >> 1]) * gv[n] + bv[n]; }
;         __builtin_amdgcn_sched_barrier(0);
;     }
;     template <bool LN, int BJ> DI void load_gb(unsigned col0, f32x4 (&gv)[2], f32x4 (&bv)[2]) const {
; #pragma unroll
;         for (int n = 0; n < 2; ++n) {
;             if (LN) { gv[n] = *(const f32x4*)(gam + col0 + BJ * HALF + n * 16) * ALPHA; bv[n] = *(const f32x4*)(bet + col0 + BJ * HALF + n * 16) * ALPHA; }
;             else { gv[n] = (f32x4){ALPHA, ALPHA, ALPHA, ALPHA}; bv[n] = (f32x4){0.f, 0.f, 0.f, 0.f}; }
;         }
;     }
	v_pk_mul_f32 v[212:213], v[130:131], s[78:79] op_sel_hi:[1,0]
	v_pk_mul_f32 v[214:215], v[128:129], s[78:79] op_sel_hi:[1,0]
	global_load_dwordx4 v[132:135], v[142:143], off offset:512
	global_load_dwordx4 v[128:131], v[140:141], off offset:576
	s_waitcnt vmcnt(0)
	v_pk_mul_f32 v[206:207], v[130:131], s[78:79] op_sel_hi:[1,0]
	v_pk_mul_f32 v[208:209], v[128:129], s[78:79] op_sel_hi:[1,0]
	global_load_dwordx4 v[128:131], v[142:143], off offset:576
	global_load_dwordx2 v[220:221], v[144:145], off
	global_load_dwordx4 v[240:243], v[136:137], off
	v_add_u32_e32 v136, v232, v229
	v_mov_b32_e32 v137, v159
	v_lshl_add_u64 v[136:137], v[136:137], 2, s[88:89]
	global_load_dwordx4 v[244:247], v[136:137], off
	global_load_dwordx2 v[218:219], v[146:147], off
	v_add_u32_e32 v136, v195, v230
	v_mov_b32_e32 v137, v159
	v_lshl_add_u64 v[136:137], v[136:137], 2, s[88:89]
	global_load_dwordx4 v[248:251], v[136:137], off
	v_add_u32_e32 v136, v195, v229
	v_mov_b32_e32 v137, v159
	v_lshl_add_u64 v[136:137], v[136:137], 2, s[88:89]
	global_load_dwordx4 v[152:155], v[136:137], off
	global_load_dwordx2 v[216:217], v[200:201], off
	v_add_u32_e32 v136, v236, v230
	v_mov_b32_e32 v137, v159
	v_lshl_add_u64 v[136:137], v[136:137], 2, s[88:89]
	global_load_dwordx4 v[148:151], v[136:137], off
	v_add_u32_e32 v136, v236, v229
	v_mov_b32_e32 v137, v159
	v_lshl_add_u64 v[136:137], v[136:137], 2, s[88:89]
	global_load_dwordx4 v[144:147], v[136:137], off
	global_load_dwordx2 v[200:201], v[202:203], off
	v_add_u32_e32 v136, v235, v230
	v_mov_b32_e32 v137, v159
	v_lshl_add_u64 v[136:137], v[136:137], 2, s[88:89]
	global_load_dwordx4 v[140:143], v[136:137], off
	v_add_u32_e32 v136, v235, v229
	v_mov_b32_e32 v137, v159
	v_lshl_add_u64 v[136:137], v[136:137], 2, s[88:89]
	global_load_dwordx4 v[136:139], v[136:137], off
	v_add_u32_e32 v202, 0x80, v194
	v_mov_b32_e32 v203, v159
	v_lshl_add_u64 v[202:203], v[202:203], 2, s[90:91]
	s_waitcnt vmcnt(0)
	v_sub_f32_e32 v241, v241, v220
	v_sub_f32_e32 v240, v240, v220
	v_sub_f32_e32 v243, v243, v220
	v_sub_f32_e32 v242, v242, v220
	v_pk_mul_f32 v[242:243], v[220:221], v[242:243] op_sel:[1,0]
	v_pk_mul_f32 v[240:241], v[220:221], v[240:241] op_sel:[1,0]
	v_pk_fma_f32 v[242:243], v[212:213], v[242:243], v[62:63]
	v_pk_fma_f32 v[240:241], v[214:215], v[240:241], v[60:61]
	v_pk_fma_f32 v[242:243], v[134:135], s[78:79], v[242:243] op_sel_hi:[1,0,1]
	v_pk_fma_f32 v[240:241], v[132:133], s[78:79], v[240:241] op_sel_hi:[1,0,1]
	global_store_dwordx4 v[202:203], v[240:243], off
	v_sub_f32_e32 v203, v245, v220
	v_sub_f32_e32 v202, v244, v220
	v_sub_f32_e32 v241, v247, v220
	v_sub_f32_e32 v240, v246, v220
	v_pk_mul_f32 v[202:203], v[220:221], v[202:203] op_sel:[1,0]
	v_pk_mul_f32 v[240:241], v[220:221], v[240:241] op_sel:[1,0]
	v_pk_fma_f32 v[202:203], v[208:209], v[202:203], v[56:57]
	v_pk_fma_f32 v[220:221], v[206:207], v[240:241], v[58:59]
	v_pk_fma_f32 v[240:241], v[128:129], s[78:79], v[202:203] op_sel_hi:[1,0,1]
	v_add_u32_e32 v202, 0x90, v194
	v_mov_b32_e32 v203, v159
	v_pk_fma_f32 v[242:243], v[130:131], s[78:79], v[220:221] op_sel_hi:[1,0,1]
	v_lshl_add_u64 v[202:203], v[202:203], 2, s[90:91]
	global_store_dwordx4 v[202:203], v[240:243], off
	v_sub_f32_e32 v203, v249, v218
	v_sub_f32_e32 v202, v248, v218
	v_sub_f32_e32 v221, v251, v218
	v_sub_f32_e32 v220, v250, v218
	v_pk_mul_f32 v[202:203], v[218:219], v[202:203] op_sel:[1,0]
	v_pk_mul_f32 v[220:221], v[218:219], v[220:221] op_sel:[1,0]
	v_pk_fma_f32 v[202:203], v[214:215], v[202:203], v[52:53]
	v_pk_fma_f32 v[220:221], v[212:213], v[220:221], v[54:55]
	v_pk_fma_f32 v[240:241], v[132:133], s[78:79], v[202:203] op_sel_hi:[1,0,1]
	v_add_u32_e32 v202, 0x8080, v194
	v_mov_b32_e32 v203, v159
	v_sub_f32_e32 v153, v153, v218
	v_sub_f32_e32 v152, v152, v218
	v_sub_f32_e32 v155, v155, v218
	v_sub_f32_e32 v154, v154, v218
	v_pk_fma_f32 v[242:243], v[134:135], s[78:79], v[220:221] op_sel_hi:[1,0,1]
	v_lshl_add_u64 v[202:203], v[202:203], 2, s[90:91]
	v_pk_mul_f32 v[154:155], v[218:219], v[154:155] op_sel:[1,0]
	v_pk_mul_f32 v[152:153], v[218:219], v[152:153] op_sel:[1,0]
	global_store_dwordx4 v[202:203], v[240:243], off
	v_pk_fma_f32 v[152:153], v[208:209], v[152:153], v[48:49]
	v_pk_fma_f32 v[154:155], v[206:207], v[154:155], v[50:51]
	v_add_u32_e32 v202, 0x8090, v194
	v_mov_b32_e32 v203, v159
	v_sub_f32_e32 v149, v149, v216
	v_sub_f32_e32 v148, v148, v216
	v_sub_f32_e32 v151, v151, v216
	v_sub_f32_e32 v150, v150, v216
	v_pk_fma_f32 v[154:155], v[130:131], s[78:79], v[154:155] op_sel_hi:[1,0,1]
	v_pk_fma_f32 v[152:153], v[128:129], s[78:79], v[152:153] op_sel_hi:[1,0,1]
	v_lshl_add_u64 v[202:203], v[202:203], 2, s[90:91]
	v_pk_mul_f32 v[150:151], v[216:217], v[150:151] op_sel:[1,0]
	v_pk_mul_f32 v[148:149], v[216:217], v[148:149] op_sel:[1,0]
	global_store_dwordx4 v[202:203], v[152:155], off
	v_pk_fma_f32 v[148:149], v[214:215], v[148:149], v[44:45]
	v_pk_fma_f32 v[150:151], v[212:213], v[150:151], v[46:47]
	v_add_u32_e32 v152, 0x10080, v194
	v_mov_b32_e32 v153, v159
	v_sub_f32_e32 v145, v145, v216
	v_sub_f32_e32 v144, v144, v216
	v_sub_f32_e32 v147, v147, v216
	v_sub_f32_e32 v146, v146, v216
	v_pk_fma_f32 v[150:151], v[134:135], s[78:79], v[150:151] op_sel_hi:[1,0,1]
	v_pk_fma_f32 v[148:149], v[132:133], s[78:79], v[148:149] op_sel_hi:[1,0,1]
	v_lshl_add_u64 v[152:153], v[152:153], 2, s[90:91]
	v_pk_mul_f32 v[146:147], v[216:217], v[146:147] op_sel:[1,0]
	v_pk_mul_f32 v[144:145], v[216:217], v[144:145] op_sel:[1,0]
	global_store_dwordx4 v[152:153], v[148:151], off
	v_pk_fma_f32 v[144:145], v[208:209], v[144:145], v[40:41]
	v_pk_fma_f32 v[146:147], v[206:207], v[146:147], v[42:43]
;     template <bool LN, int BJ, int LO, int HI> DI void batch(const f32x4 (&acc)[2][2][4][2], unsigned row0, unsigned col0, const f32x4 (&gv)[2], const f32x4 (&bv)[2]) const {
;         f32x4 r[HI - LO]; float mean[(HI - LO) / 2], rstd[(HI - LO) / 2];
; #pragma unroll
;         for (int i = LO; i < HI; ++i) { const int ai = i >> 3, m = (i >> 1) & 3, n = i & 1; const unsigned row = row0 + ai * HALF + m * 16;
;             if (n == 0) { mean[(i - LO) >> 1] = 0.f; rstd[(i - LO) >> 1] = 1.f;
;                 if (LN) { const float2 st = *(const float2*)(stats + row * 2u); mean[(i - LO) >> 1] = st.x; rstd[(i - LO) >> 1] = st.y; } }
;             r[i - LO] = *(const f32x4*)(src + (row * (unsigned)DM + col0 + BJ * HALF + n * 16)); }
; #pragma unroll
;         for (int i = LO; i < HI; ++i) { const int ai = i >> 3, m = (i >> 1) & 3, n = i & 1; const unsigned row = row0 + ai * HALF + m * 16;
;             *(f32x4*)(Y + (row * (unsigned)DM + col0 + BJ * HALF + n * 16)) = acc[ai][BJ][m][n] + ((r[i - LO] - mean[(i - LO) >> 1]) * rstd[(i - LO) >> 1]) * gv[n] + bv[n]; }
	v_add_u32_e32 v148, 0x10090, v194
	v_mov_b32_e32 v149, v159
	v_sub_f32_e32 v141, v141, v200
	v_sub_f32_e32 v140, v140, v200
	v_sub_f32_e32 v143, v143, v200
	v_sub_f32_e32 v142, v142, v200
	v_pk_fma_f32 v[146:147], v[130:131], s[78:79], v[146:147] op_sel_hi:[1,0,1]
	v_pk_fma_f32 v[144:145], v[128:129], s[78:79], v[144:145] op_sel_hi:[1,0,1]
	v_lshl_add_u64 v[148:149], v[148:149], 2, s[90:91]
	v_pk_mul_f32 v[142:143], v[200:201], v[142:143] op_sel:[1,0]
	v_pk_mul_f32 v[140:141], v[200:201], v[140:141] op_sel:[1,0]
	global_store_dwordx4 v[148:149], v[144:147], off
	v_pk_fma_f32 v[140:141], v[214:215], v[140:141], v[36:37]
	v_pk_fma_f32 v[142:143], v[212:213], v[142:143], v[38:39]
	v_add_u32_e32 v144, 0x18080, v194
	v_mov_b32_e32 v145, v159
	v_sub_f32_e32 v137, v137, v200
	v_sub_f32_e32 v136, v136, v200
	v_sub_f32_e32 v139, v139, v200
	v_sub_f32_e32 v138, v138, v200
	v_pk_fma_f32 v[142:143], v[134:135], s[78:79], v[142:143] op_sel_hi:[1,0,1]
	v_pk_fma_f32 v[140:141], v[132:133], s[78:79], v[140:141] op_sel_hi:[1,0,1]
	v_lshl_add_u64 v[144:145], v[144:145], 2, s[90:91]
	v_pk_mul_f32 v[138:139], v[200:201], v[138:139] op_sel:[1,0]
	v_pk_mul_f32 v[136:137], v[200:201], v[136:137] op_sel:[1,0]
	global_store_dwordx4 v[144:145], v[140:143], off
	v_pk_fma_f32 v[136:137], v[208:209], v[136:137], v[32:33]
	v_pk_fma_f32 v[138:139], v[206:207], v[138:139], v[34:35]
	v_add_u32_e32 v140, 0x18090, v194
	v_mov_b32_e32 v141, v159
	v_pk_fma_f32 v[138:139], v[130:131], s[78:79], v[138:139] op_sel_hi:[1,0,1]
	v_pk_fma_f32 v[136:137], v[128:129], s[78:79], v[136:137] op_sel_hi:[1,0,1]
	v_lshl_add_u64 v[140:141], v[140:141], 2, s[90:91]
	global_store_dwordx4 v[140:141], v[136:139], off
	s_nop 1
	v_add_u32_e32 v136, v233, v230
	v_mov_b32_e32 v137, v159
	v_lshl_add_u64 v[136:137], v[136:137], 2, s[88:89]
	global_load_dwordx2 v[220:221], v[196:197], off
	global_load_dwordx4 v[216:219], v[136:137], off
	v_add_u32_e32 v136, v233, v229
	v_mov_b32_e32 v137, v159
	v_lshl_add_u64 v[136:137], v[136:137], 2, s[88:89]
	global_load_dwordx4 v[240:243], v[136:137], off
	global_load_dwordx2 v[200:201], v[198:199], off
	v_add_u32_e32 v136, v234, v230
	v_mov_b32_e32 v137, v159
	v_lshl_add_u64 v[136:137], v[136:137], 2, s[88:89]
	global_load_dwordx4 v[244:247], v[136:137], off
	v_add_u32_e32 v136, v234, v229
	v_mov_b32_e32 v137, v159
	v_lshl_add_u64 v[136:137], v[136:137], 2, s[88:89]
	global_load_dwordx4 v[152:155], v[136:137], off
	global_load_dwordx2 v[198:199], v[204:205], off
	v_add_u32_e32 v136, v237, v230
	v_mov_b32_e32 v137, v159
	v_lshl_add_u64 v[136:137], v[136:137], 2, s[88:89]
	global_load_dwordx4 v[148:151], v[136:137], off
	v_add_u32_e32 v136, v237, v229
	v_mov_b32_e32 v137, v159
	v_lshl_add_u64 v[136:137], v[136:137], 2, s[88:89]
	global_load_dwordx4 v[144:147], v[136:137], off
	global_load_dwordx2 v[196:197], v[210:211], off
	v_add_u32_e32 v136, v238, v230
	v_mov_b32_e32 v137, v159
	v_lshl_add_u64 v[136:137], v[136:137], 2, s[88:89]
	global_load_dwordx4 v[140:143], v[136:137], off
	v_add_u32_e32 v136, v238, v229
	v_mov_b32_e32 v137, v159
	v_lshl_add_u64 v[136:137], v[136:137], 2, s[88:89]
	global_load_dwordx4 v[136:139], v[136:137], off
	v_add_u32_e32 v210, 0x40080, v194
	v_mov_b32_e32 v211, v159
	v_lshl_add_u64 v[210:211], v[210:211], 2, s[90:91]
	s_waitcnt vmcnt(0)
;     template <bool LN, int BJ, int LO, int HI> DI void batch(const f32x4 (&acc)[2][2][4][2], unsigned row0, unsigned col0, const f32x4 (&gv)[2], const f32x4 (&bv)[2]) const {
;         f32x4 r[HI - LO]; float mean[(HI - LO) / 2], rstd[(HI - LO) / 2];
; #pragma unroll
;         for (int i = LO; i < HI; ++i) { const int ai = i >> 3, m = (i >> 1) & 3, n = i & 1; const unsigned row = row0 + ai * HALF + m * 16;
;             if (n == 0) { mean[(i - LO) >> 1] = 0.f; rstd[(i - LO) >> 1] = 1.f;
;                 if (LN) { const float2 st = *(const float2*)(stats + row * 2u); mean[(i - LO) >> 1] = st.x; rstd[(i - LO) >> 1] = st.y; } }
;             r[i - LO] = *(const f32x4*)(src + (row * (unsigned)DM + col0 + BJ * HALF + n * 16)); }
; #pragma unroll
;         for (int i = LO; i < HI; ++i) { const int ai = i >> 3, m = (i >> 1) & 3, n = i & 1; const unsigned row = row0 + ai * HALF + m * 16;
;             *(f32x4*)(Y + (row * (unsigned)DM + col0 + BJ * HALF + n * 16)) = acc[ai][BJ][m][n] + ((r[i - LO] - mean[(i - LO) >> 1]) * rstd[(i - LO) >> 1]) * gv[n] + bv[n]; }
	v_sub_f32_e32 v203, v217, v220
	v_sub_f32_e32 v202, v216, v220
	v_sub_f32_e32 v205, v219, v220
	v_sub_f32_e32 v204, v218, v220
	v_pk_mul_f32 v[204:205], v[220:221], v[204:205] op_sel:[1,0]
	v_pk_mul_f32 v[202:203], v[220:221], v[202:203] op_sel:[1,0]
	v_pk_fma_f32 v[204:205], v[212:213], v[204:205], v[30:31]
	v_pk_fma_f32 v[202:203], v[214:215], v[202:203], v[28:29]
	v_pk_fma_f32 v[204:205], v[134:135], s[78:79], v[204:205] op_sel_hi:[1,0,1]
	v_pk_fma_f32 v[202:203], v[132:133], s[78:79], v[202:203] op_sel_hi:[1,0,1]
	global_store_dwordx4 v[210:211], v[202:205], off
	v_add_u32_e32 v210, 0x40090, v194
	v_mov_b32_e32 v211, v159
	v_sub_f32_e32 v203, v241, v220
	v_sub_f32_e32 v202, v240, v220
	v_sub_f32_e32 v205, v243, v220
	v_sub_f32_e32 v204, v242, v220
	v_pk_mul_f32 v[204:205], v[220:221], v[204:205] op_sel:[1,0]
	v_pk_mul_f32 v[202:203], v[220:221], v[202:203] op_sel:[1,0]
	v_pk_fma_f32 v[204:205], v[206:207], v[204:205], v[26:27]
	v_pk_fma_f32 v[202:203], v[208:209], v[202:203], v[24:25]
	v_pk_fma_f32 v[204:205], v[130:131], s[78:79], v[204:205] op_sel_hi:[1,0,1]
	v_pk_fma_f32 v[202:203], v[128:129], s[78:79], v[202:203] op_sel_hi:[1,0,1]
	v_lshl_add_u64 v[210:211], v[210:211], 2, s[90:91]
	global_store_dwordx4 v[210:211], v[202:205], off
	v_sub_f32_e32 v149, v149, v198
	v_sub_f32_e32 v148, v148, v198
	v_sub_f32_e32 v203, v245, v200
	v_sub_f32_e32 v202, v244, v200
	v_sub_f32_e32 v141, v141, v196
	v_sub_f32_e32 v140, v140, v196
	v_sub_f32_e32 v205, v247, v200
	v_sub_f32_e32 v204, v246, v200
	v_pk_mul_f32 v[202:203], v[200:201], v[202:203] op_sel:[1,0]
	v_sub_f32_e32 v151, v151, v198
	v_sub_f32_e32 v150, v150, v198
	v_pk_mul_f32 v[148:149], v[198:199], v[148:149] op_sel:[1,0]
	v_sub_f32_e32 v143, v143, v196
	v_sub_f32_e32 v142, v142, v196
	v_pk_mul_f32 v[140:141], v[196:197], v[140:141] op_sel:[1,0]
	v_pk_mul_f32 v[204:205], v[200:201], v[204:205] op_sel:[1,0]
	v_pk_fma_f32 v[202:203], v[214:215], v[202:203], v[20:21]
	v_sub_f32_e32 v153, v153, v200
	v_sub_f32_e32 v152, v152, v200
	v_sub_f32_e32 v155, v155, v200
	v_sub_f32_e32 v154, v154, v200
	v_pk_mul_f32 v[150:151], v[198:199], v[150:151] op_sel:[1,0]
	v_pk_fma_f32 v[148:149], v[214:215], v[148:149], v[12:13]
	v_pk_mul_f32 v[142:143], v[196:197], v[142:143] op_sel:[1,0]
	v_pk_fma_f32 v[140:141], v[214:215], v[140:141], v[4:5]
	v_pk_fma_f32 v[204:205], v[212:213], v[204:205], v[22:23]
	v_pk_fma_f32 v[202:203], v[132:133], s[78:79], v[202:203] op_sel_hi:[1,0,1]
	v_pk_mul_f32 v[154:155], v[200:201], v[154:155] op_sel:[1,0]
	v_pk_mul_f32 v[152:153], v[200:201], v[152:153] op_sel:[1,0]
	v_pk_fma_f32 v[150:151], v[212:213], v[150:151], v[14:15]
	v_pk_fma_f32 v[148:149], v[132:133], s[78:79], v[148:149] op_sel_hi:[1,0,1]
	v_pk_fma_f32 v[142:143], v[212:213], v[142:143], v[6:7]
	v_pk_fma_f32 v[132:133], v[132:133], s[78:79], v[140:141] op_sel_hi:[1,0,1]
	v_add_u32_e32 v140, 0x58080, v194
	v_mov_b32_e32 v141, v159
	v_pk_fma_f32 v[204:205], v[134:135], s[78:79], v[204:205] op_sel_hi:[1,0,1]
	v_pk_fma_f32 v[152:153], v[208:209], v[152:153], v[16:17]
	v_pk_fma_f32 v[154:155], v[206:207], v[154:155], v[18:19]
	v_add_u32_e32 v200, 0x48090, v194
	v_mov_b32_e32 v201, v159
	v_pk_fma_f32 v[150:151], v[134:135], s[78:79], v[150:151] op_sel_hi:[1,0,1]
	v_pk_fma_f32 v[134:135], v[134:135], s[78:79], v[142:143] op_sel_hi:[1,0,1]
	v_lshl_add_u64 v[140:141], v[140:141], 2, s[90:91]
	v_pk_fma_f32 v[154:155], v[130:131], s[78:79], v[154:155] op_sel_hi:[1,0,1]
	v_pk_fma_f32 v[152:153], v[128:129], s[78:79], v[152:153] op_sel_hi:[1,0,1]
	v_lshl_add_u64 v[200:201], v[200:201], 2, s[90:91]
	v_sub_f32_e32 v145, v145, v198
	v_sub_f32_e32 v144, v144, v198
	global_store_dwordx4 v[140:141], v[132:135], off
	global_store_dwordx4 v[200:201], v[152:155], off
	v_sub_f32_e32 v147, v147, v198
	v_sub_f32_e32 v133, v137, v196
	v_sub_f32_e32 v132, v136, v196
	v_add_u32_e32 v152, 0x50080, v194
	v_mov_b32_e32 v153, v159
	v_sub_f32_e32 v146, v146, v198
	v_pk_mul_f32 v[144:145], v[198:199], v[144:145] op_sel:[1,0]
	v_sub_f32_e32 v135, v139, v196
	v_sub_f32_e32 v134, v138, v196
	v_pk_mul_f32 v[132:133], v[196:197], v[132:133] op_sel:[1,0]
	v_lshl_add_u64 v[152:153], v[152:153], 2, s[90:91]
	v_pk_mul_f32 v[146:147], v[198:199], v[146:147] op_sel:[1,0]
	v_pk_fma_f32 v[144:145], v[208:209], v[144:145], v[8:9]
	v_pk_mul_f32 v[134:135], v[196:197], v[134:135] op_sel:[1,0]
	v_pk_fma_f32 v[132:133], v[208:209], v[132:133], v[0:1]
	v_add_u32_e32 v210, 0x48080, v194
	v_mov_b32_e32 v211, v159
	global_store_dwordx4 v[152:153], v[148:151], off
	v_pk_fma_f32 v[146:147], v[206:207], v[146:147], v[10:11]
	v_pk_fma_f32 v[144:145], v[128:129], s[78:79], v[144:145] op_sel_hi:[1,0,1]
	v_add_u32_e32 v148, 0x50090, v194
	v_mov_b32_e32 v149, v159
	v_pk_fma_f32 v[134:135], v[206:207], v[134:135], v[2:3]
	v_pk_fma_f32 v[128:129], v[128:129], s[78:79], v[132:133] op_sel_hi:[1,0,1]
	v_add_u32_e32 v132, 0x58090, v194
	v_mov_b32_e32 v133, v159
	v_lshl_add_u64 v[210:211], v[210:211], 2, s[90:91]
	v_pk_fma_f32 v[146:147], v[130:131], s[78:79], v[146:147] op_sel_hi:[1,0,1]
	v_lshl_add_u64 v[148:149], v[148:149], 2, s[90:91]
	v_pk_fma_f32 v[130:131], v[130:131], s[78:79], v[134:135] op_sel_hi:[1,0,1]
	v_lshl_add_u64 v[132:133], v[132:133], 2, s[90:91]
	global_store_dwordx4 v[210:211], v[202:205], off
	global_store_dwordx4 v[148:149], v[144:147], off
	global_store_dwordx4 v[132:133], v[128:131], off
	s_mov_b64 s[20:21], 0
	s_branch .LBB0_81

; #define PG8_STAGE(bufoff, gbase) do { _Pragma("unroll") for (int _i = 0; _i < 2; ++_i) \
;         __builtin_amdgcn_global_load_lds((const unsigned*)((const char*)(gbase) + voff[_i]), (LAS unsigned*)(lds + (bufoff) + ldsw + _i * 8192), 16, 0, 0); } while (0)
; #define PG8_LDA(dst, b, h) do { _Pragma("unroll") for (int m = 0; m < 4; ++m) _Pragma("unroll") for (int k = 0; k < 2; ++k) dst[m][k] = *(const LAS bf16x8*)(lds + PG8_SA(b, h) + aoff + m * 2048 + k * 1024); } while (0)
; #define PG8_LDB(dst, b, h) do { _Pragma("unroll") for (int n = 0; n < 2; ++n) _Pragma("unroll") for (int k = 0; k < 2; ++k) dst[n][k] = *(const LAS bf16x8*)(lds + PG8_SB(b, h) + boff + n * 2048 + k * 1024); } while (0)
; #define PG8_MMA(ai, bj, At, Bt) do { __builtin_amdgcn_s_setprio(1); _Pragma("unroll") for (int m = 0; m < 4; ++m) _Pragma("unroll") for (int n = 0; n < 2; ++n) _Pragma("unroll") for (int k = 0; k < 2; ++k) \
;         acc[ai][bj][m][n] = __builtin_amdgcn_mfma_f32_16x16x32_bf16(Bt[n][k], At[m][k], acc[ai][bj][m][n], 0, 0, 0); __builtin_amdgcn_s_setprio(0); } while (0)
; #define PG8_WAIT_V(n) asm volatile("s_waitcnt vmcnt(" #n ")" ::: "memory")
; #define PG8_WAIT_L(n) asm volatile("s_waitcnt lgkmcnt(" #n ")" ::: "memory")
; #define PG8_BAR __builtin_amdgcn_s_barrier()
; #define PG8_SCHED __builtin_amdgcn_sched_barrier(0)
; template <class Epi>
; DI void gemm_phase(LAS unsigned char* lds, const Gemm g, const StaticOrder& S, const Epi& E) {
;     ...
;             PG8_LDB(B0, 0, 0); PG8_SCHED; PG8_LDA(At, 0, 0); PG8_STAGE(PG8_SA(1, 1), a1 + hstep);
;             PG8_WAIT_L(8); PG8_BAR; PG8_WAIT_L(0); PG8_MMA(0, 0, At, B0); PG8_BAR; PG8_SCHED;
;             PG8_LDB(B1, 0, 1); PG8_STAGE(PG8_SB(0, 0), b2);
;             PG8_BAR; PG8_WAIT_L(0); PG8_MMA(0, 1, At, B1); PG8_BAR;
;             PG8_LDA(At, 0, 1); PG8_STAGE(PG8_SA(0, 0), a2);
;             PG8_BAR; PG8_WAIT_L(0); PG8_MMA(1, 0, At, B0); PG8_BAR; PG8_SCHED;
;             PG8_STAGE(PG8_SB(0, 1), b2 + hstep);
;             PG8_WAIT_V(6); PG8_BAR; PG8_MMA(1, 1, At, B1); PG8_BAR;
.LBB0_134:
	s_add_u32 s18, s16, 0x100
	s_addc_u32 s19, s17, 0
	s_add_i32 s39, 0, 0x10000
	ds_read_b128 v[96:99], v199
	ds_read_b128 v[100:103], v199 offset:1024
	ds_read_b128 v[136:139], v199 offset:2048
	ds_read_b128 v[148:151], v199 offset:3072
	s_cmpk_eq_i32 s33, 0x54
	s_cselect_b32 s23, s9, s19
	s_cselect_b32 s22, s8, s18
	s_cselect_b32 s21, s11, s5
	s_cselect_b32 s20, s10, s4
	v_lshl_add_u64 v[218:219], s[16:17], 0, v[144:145]
	s_add_i32 m0, s28, 0xc000
	ds_read_b128 v[152:155], v201
	ds_read_b128 v[186:189], v201 offset:1024
	ds_read_b128 v[190:193], v201 offset:2048
	ds_read_b128 v[194:197], v201 offset:3072
	ds_read_b128 v[202:205], v201 offset:4096
	ds_read_b128 v[206:209], v201 offset:5120
	ds_read_b128 v[210:213], v201 offset:6144
	ds_read_b128 v[214:217], v201 offset:7168
	global_load_lds_dwordx4 v[218:219], off
	v_lshl_add_u64 v[218:219], s[16:17], 0, v[146:147]
	s_add_i32 m0, s28, 0xe000
	s_nop 0
	global_load_lds_dwordx4 v[218:219], off
	s_waitcnt lgkmcnt(8)
	s_setprio 1
	s_barrier
	s_waitcnt lgkmcnt(0)
	v_mfma_f32_16x16x32_bf16 v[132:135], v[96:99], v[152:155], v[132:135]
	v_mfma_f32_16x16x32_bf16 v[128:131], v[136:139], v[152:155], v[128:131]
	v_mfma_f32_16x16x32_bf16 v[124:127], v[96:99], v[190:193], v[124:127]
	v_mfma_f32_16x16x32_bf16 v[120:123], v[136:139], v[190:193], v[120:123]
	v_mfma_f32_16x16x32_bf16 v[116:119], v[96:99], v[202:205], v[116:119]
	v_mfma_f32_16x16x32_bf16 v[112:115], v[136:139], v[202:205], v[112:115]
	v_mfma_f32_16x16x32_bf16 v[108:111], v[96:99], v[210:213], v[108:111]
	v_mfma_f32_16x16x32_bf16 v[104:107], v[136:139], v[210:213], v[104:107]
	v_mfma_f32_16x16x32_bf16 v[132:135], v[100:103], v[186:189], v[132:135]
	v_mfma_f32_16x16x32_bf16 v[128:131], v[148:151], v[186:189], v[128:131]
	v_mfma_f32_16x16x32_bf16 v[124:127], v[100:103], v[194:197], v[124:127]
	v_mfma_f32_16x16x32_bf16 v[120:123], v[148:151], v[194:197], v[120:123]
	v_mfma_f32_16x16x32_bf16 v[116:119], v[100:103], v[206:209], v[116:119]
	v_mfma_f32_16x16x32_bf16 v[112:115], v[148:151], v[206:209], v[112:115]
	v_mfma_f32_16x16x32_bf16 v[108:111], v[100:103], v[214:217], v[108:111]
	s_setprio 0
	v_mfma_f32_16x16x32_bf16 v[104:107], v[148:151], v[214:217], v[104:107]
	s_barrier
	s_add_i32 s40, 0, 0x14000
	s_add_i32 s16, s39, s27
	v_lshl_add_u64 v[218:219], s[20:21], 0, v[142:143]
	s_mov_b32 m0, s16
	ds_read_b128 v[226:229], v199 offset:16384
	ds_read_b128 v[230:233], v199 offset:17408
	ds_read_b128 v[234:237], v199 offset:18432
	ds_read_b128 v[238:241], v199 offset:19456
	global_load_lds_dwordx4 v[218:219], off
	v_lshl_add_u64 v[220:221], s[20:21], 0, v[140:141]
	s_add_i32 m0, s16, 0x2000
	s_nop 0
	global_load_lds_dwordx4 v[220:221], off
	s_waitcnt lgkmcnt(0)
	s_setprio 1
	s_barrier
	v_mfma_f32_16x16x32_bf16 v[60:63], v[226:229], v[152:155], v[60:63]
	v_mfma_f32_16x16x32_bf16 v[56:59], v[234:237], v[152:155], v[56:59]
	v_mfma_f32_16x16x32_bf16 v[52:55], v[226:229], v[190:193], v[52:55]
	v_mfma_f32_16x16x32_bf16 v[48:51], v[234:237], v[190:193], v[48:51]
	v_mfma_f32_16x16x32_bf16 v[44:47], v[226:229], v[202:205], v[44:47]
	v_mfma_f32_16x16x32_bf16 v[40:43], v[234:237], v[202:205], v[40:43]
	v_mfma_f32_16x16x32_bf16 v[36:39], v[226:229], v[210:213], v[36:39]
	v_mfma_f32_16x16x32_bf16 v[32:35], v[234:237], v[210:213], v[32:35]
	v_mfma_f32_16x16x32_bf16 v[60:63], v[230:233], v[186:189], v[60:63]
	s_mov_b32 m0, s28
	v_mfma_f32_16x16x32_bf16 v[56:59], v[238:241], v[186:189], v[56:59]
	v_lshl_add_u64 v[242:243], s[22:23], 0, v[142:143]
	v_mfma_f32_16x16x32_bf16 v[52:55], v[230:233], v[194:197], v[52:55]
	v_mfma_f32_16x16x32_bf16 v[48:51], v[238:241], v[194:197], v[48:51]
	v_mfma_f32_16x16x32_bf16 v[44:47], v[230:233], v[206:209], v[44:47]
	v_mfma_f32_16x16x32_bf16 v[40:43], v[238:241], v[206:209], v[40:43]
	v_mfma_f32_16x16x32_bf16 v[36:39], v[230:233], v[214:217], v[36:39]
	s_setprio 0
	v_mfma_f32_16x16x32_bf16 v[32:35], v[238:241], v[214:217], v[32:35]
	s_barrier
	ds_read_b128 v[152:155], v201 offset:16384
	ds_read_b128 v[186:189], v201 offset:17408
	ds_read_b128 v[190:193], v201 offset:18432
	ds_read_b128 v[194:197], v201 offset:19456
	ds_read_b128 v[202:205], v201 offset:20480
	ds_read_b128 v[206:209], v201 offset:21504
	ds_read_b128 v[210:213], v201 offset:22528
	ds_read_b128 v[214:217], v201 offset:23552
	global_load_lds_dwordx4 v[242:243], off
	v_lshl_add_u64 v[244:245], s[22:23], 0, v[140:141]
	s_mov_b32 m0, s29
	s_nop 0
	global_load_lds_dwordx4 v[244:245], off
	s_waitcnt lgkmcnt(0)
	s_setprio 1
	s_barrier
	v_mfma_f32_16x16x32_bf16 v[92:95], v[96:99], v[152:155], v[92:95]
	v_mfma_f32_16x16x32_bf16 v[88:91], v[136:139], v[152:155], v[88:91]
	v_mfma_f32_16x16x32_bf16 v[84:87], v[96:99], v[190:193], v[84:87]
	v_mfma_f32_16x16x32_bf16 v[80:83], v[136:139], v[190:193], v[80:83]
	v_mfma_f32_16x16x32_bf16 v[76:79], v[96:99], v[202:205], v[76:79]
	v_mfma_f32_16x16x32_bf16 v[72:75], v[136:139], v[202:205], v[72:75]
	v_mfma_f32_16x16x32_bf16 v[68:71], v[96:99], v[210:213], v[68:71]
	v_mfma_f32_16x16x32_bf16 v[64:67], v[136:139], v[210:213], v[64:67]
	v_mfma_f32_16x16x32_bf16 v[92:95], v[100:103], v[186:189], v[92:95]
	v_mfma_f32_16x16x32_bf16 v[88:91], v[148:151], v[186:189], v[88:91]
	v_mfma_f32_16x16x32_bf16 v[84:87], v[100:103], v[194:197], v[84:87]
	v_mfma_f32_16x16x32_bf16 v[80:83], v[148:151], v[194:197], v[80:83]
	v_mfma_f32_16x16x32_bf16 v[76:79], v[100:103], v[206:209], v[76:79]
	v_mfma_f32_16x16x32_bf16 v[72:75], v[148:151], v[206:209], v[72:75]
	v_mfma_f32_16x16x32_bf16 v[68:71], v[100:103], v[214:217], v[68:71]
	s_setprio 0
	v_mfma_f32_16x16x32_bf16 v[64:67], v[148:151], v[214:217], v[64:67]
	s_barrier
; #define PG8_STAGE(bufoff, gbase) do { _Pragma("unroll") for (int _i = 0; _i < 2; ++_i) \
;         __builtin_amdgcn_global_load_lds((const unsigned*)((const char*)(gbase) + voff[_i]), (LAS unsigned*)(lds + (bufoff) + ldsw + _i * 8192), 16, 0, 0); } while (0)
; #define PG8_LDA(dst, b, h) do { _Pragma("unroll") for (int m = 0; m < 4; ++m) _Pragma("unroll") for (int k = 0; k < 2; ++k) dst[m][k] = *(const LAS bf16x8*)(lds + PG8_SA(b, h) + aoff + m * 2048 + k * 1024); } while (0)
; #define PG8_LDB(dst, b, h) do { _Pragma("unroll") for (int n = 0; n < 2; ++n) _Pragma("unroll") for (int k = 0; k < 2; ++k) dst[n][k] = *(const LAS bf16x8*)(lds + PG8_SB(b, h) + boff + n * 2048 + k * 1024); } while (0)
; #define PG8_MMA(ai, bj, At, Bt) do { __builtin_amdgcn_s_setprio(1); _Pragma("unroll") for (int m = 0; m < 4; ++m) _Pragma("unroll") for (int n = 0; n < 2; ++n) _Pragma("unroll") for (int k = 0; k < 2; ++k) \
;         acc[ai][bj][m][n] = __builtin_amdgcn_mfma_f32_16x16x32_bf16(Bt[n][k], At[m][k], acc[ai][bj][m][n], 0, 0, 0); __builtin_amdgcn_s_setprio(0); } while (0)
; #define PG8_WAIT_V(n) asm volatile("s_waitcnt vmcnt(" #n ")" ::: "memory")
; #define PG8_WAIT_L(n) asm volatile("s_waitcnt lgkmcnt(" #n ")" ::: "memory")
; #define PG8_BAR __builtin_amdgcn_s_barrier()
; #define PG8_SCHED __builtin_amdgcn_sched_barrier(0)
; template <class Epi>
; DI void gemm_phase(LAS unsigned char* lds, const Gemm g, const StaticOrder& S, const Epi& E) {
;     ...
;             PG8_STAGE(PG8_SB(0, 1), b2 + hstep);
;             PG8_WAIT_V(6); PG8_BAR; PG8_MMA(1, 1, At, B1); PG8_BAR;
;             PG8_LDB(B0, 1, 0); PG8_SCHED; PG8_LDA(At, 1, 0); PG8_STAGE(PG8_SA(0, 1), a2 + hstep);
;             PG8_WAIT_L(8); PG8_BAR; PG8_WAIT_L(0); PG8_MMA(0, 0, At, B0); PG8_BAR; PG8_SCHED;
;             PG8_LDB(B1, 1, 1); PG8_STAGE(PG8_SB(1, 0), b3);
;             PG8_BAR; PG8_WAIT_L(0); PG8_MMA(0, 1, At, B1); PG8_BAR;
;             PG8_LDA(At, 1, 1); PG8_STAGE(PG8_SA(1, 0), a3);
;             PG8_BAR; PG8_WAIT_L(0); PG8_MMA(1, 0, At, B0); PG8_BAR; PG8_SCHED;
	s_add_u32 s16, s20, 0x160000
	s_addc_u32 s17, s21, 0
	s_add_i32 s39, s40, s27
	v_lshl_add_u64 v[96:97], s[16:17], 0, v[142:143]
	s_mov_b32 m0, s39
	s_nop 0
	global_load_lds_dwordx4 v[96:97], off
	v_lshl_add_u64 v[96:97], s[16:17], 0, v[140:141]
	s_add_i32 m0, s39, 0x2000
	s_nop 0
	global_load_lds_dwordx4 v[96:97], off
	s_waitcnt vmcnt(6)
	s_setprio 1
	s_barrier
	v_mfma_f32_16x16x32_bf16 v[28:31], v[226:229], v[152:155], v[28:31]
	v_mfma_f32_16x16x32_bf16 v[24:27], v[234:237], v[152:155], v[24:27]
	v_mfma_f32_16x16x32_bf16 v[20:23], v[226:229], v[190:193], v[20:23]
	v_mfma_f32_16x16x32_bf16 v[16:19], v[234:237], v[190:193], v[16:19]
	v_mfma_f32_16x16x32_bf16 v[12:15], v[226:229], v[202:205], v[12:15]
	v_mfma_f32_16x16x32_bf16 v[8:11], v[234:237], v[202:205], v[8:11]
	v_mfma_f32_16x16x32_bf16 v[4:7], v[226:229], v[210:213], v[4:7]
	v_mfma_f32_16x16x32_bf16 v[0:3], v[234:237], v[210:213], v[0:3]
	v_mfma_f32_16x16x32_bf16 v[28:31], v[230:233], v[186:189], v[28:31]
	s_add_i32 s39, 0, 0x18000
	v_mfma_f32_16x16x32_bf16 v[24:27], v[238:241], v[186:189], v[24:27]
	v_mfma_f32_16x16x32_bf16 v[20:23], v[230:233], v[194:197], v[20:23]
	v_mfma_f32_16x16x32_bf16 v[16:19], v[238:241], v[194:197], v[16:19]
	v_mfma_f32_16x16x32_bf16 v[12:15], v[230:233], v[206:209], v[12:15]
	v_mfma_f32_16x16x32_bf16 v[8:11], v[238:241], v[206:209], v[8:11]
	v_mfma_f32_16x16x32_bf16 v[4:7], v[230:233], v[214:217], v[4:7]
	s_setprio 0
	v_mfma_f32_16x16x32_bf16 v[0:3], v[238:241], v[214:217], v[0:3]
	s_barrier
	ds_read_b128 v[96:99], v199 offset:32768
	ds_read_b128 v[100:103], v199 offset:33792
	ds_read_b128 v[136:139], v199 offset:34816
	ds_read_b128 v[148:151], v199 offset:35840
	s_add_u32 s16, s22, 0x160000
	s_addc_u32 s17, s23, 0
	s_mov_b32 m0, s30
	v_lshl_add_u64 v[226:227], s[16:17], 0, v[142:143]
	ds_read_b128 v[152:155], v201 offset:32768
	ds_read_b128 v[186:189], v201 offset:33792
	ds_read_b128 v[190:193], v201 offset:34816
	ds_read_b128 v[194:197], v201 offset:35840
	ds_read_b128 v[202:205], v201 offset:36864
	ds_read_b128 v[206:209], v201 offset:37888
	ds_read_b128 v[210:213], v201 offset:38912
	ds_read_b128 v[214:217], v201 offset:39936
	global_load_lds_dwordx4 v[226:227], off
	v_lshl_add_u64 v[226:227], s[16:17], 0, v[140:141]
	s_mov_b32 m0, s31
	s_nop 0
	global_load_lds_dwordx4 v[226:227], off
	s_waitcnt lgkmcnt(8)
	s_setprio 1
	s_barrier
	s_waitcnt lgkmcnt(0)
	v_mfma_f32_16x16x32_bf16 v[132:135], v[96:99], v[152:155], v[132:135]
	v_mfma_f32_16x16x32_bf16 v[128:131], v[136:139], v[152:155], v[128:131]
	v_mfma_f32_16x16x32_bf16 v[124:127], v[96:99], v[190:193], v[124:127]
	v_mfma_f32_16x16x32_bf16 v[120:123], v[136:139], v[190:193], v[120:123]
	v_mfma_f32_16x16x32_bf16 v[116:119], v[96:99], v[202:205], v[116:119]
	v_mfma_f32_16x16x32_bf16 v[112:115], v[136:139], v[202:205], v[112:115]
	v_mfma_f32_16x16x32_bf16 v[108:111], v[96:99], v[210:213], v[108:111]
	v_mfma_f32_16x16x32_bf16 v[104:107], v[136:139], v[210:213], v[104:107]
	v_mfma_f32_16x16x32_bf16 v[132:135], v[100:103], v[186:189], v[132:135]
	v_mfma_f32_16x16x32_bf16 v[128:131], v[148:151], v[186:189], v[128:131]
	v_mfma_f32_16x16x32_bf16 v[124:127], v[100:103], v[194:197], v[124:127]
	v_mfma_f32_16x16x32_bf16 v[120:123], v[148:151], v[194:197], v[120:123]
	v_mfma_f32_16x16x32_bf16 v[116:119], v[100:103], v[206:209], v[116:119]
	v_mfma_f32_16x16x32_bf16 v[112:115], v[148:151], v[206:209], v[112:115]
	v_mfma_f32_16x16x32_bf16 v[108:111], v[100:103], v[214:217], v[108:111]
	s_setprio 0
	v_mfma_f32_16x16x32_bf16 v[104:107], v[148:151], v[214:217], v[104:107]
	s_barrier
	s_add_i32 s22, 0, 0x1c000
	s_add_i32 s16, s39, s27
	v_lshl_add_u64 v[218:219], v[218:219], 0, s[94:95]
	s_mov_b32 m0, s16
	ds_read_b128 v[226:229], v199 offset:49152
	ds_read_b128 v[230:233], v199 offset:50176
	ds_read_b128 v[234:237], v199 offset:51200
	ds_read_b128 v[238:241], v199 offset:52224
	global_load_lds_dwordx4 v[218:219], off
	v_lshl_add_u64 v[218:219], v[220:221], 0, s[94:95]
	s_add_i32 m0, s16, 0x2000
	s_nop 0
	global_load_lds_dwordx4 v[218:219], off
	s_waitcnt lgkmcnt(0)
	s_setprio 1
	s_barrier
	v_mfma_f32_16x16x32_bf16 v[60:63], v[226:229], v[152:155], v[60:63]
	v_mfma_f32_16x16x32_bf16 v[56:59], v[234:237], v[152:155], v[56:59]
	v_mfma_f32_16x16x32_bf16 v[52:55], v[226:229], v[190:193], v[52:55]
	v_mfma_f32_16x16x32_bf16 v[48:51], v[234:237], v[190:193], v[48:51]
	v_mfma_f32_16x16x32_bf16 v[44:47], v[226:229], v[202:205], v[44:47]
	v_mfma_f32_16x16x32_bf16 v[40:43], v[234:237], v[202:205], v[40:43]
	v_mfma_f32_16x16x32_bf16 v[36:39], v[226:229], v[210:213], v[36:39]
	v_mfma_f32_16x16x32_bf16 v[32:35], v[234:237], v[210:213], v[32:35]
	v_mfma_f32_16x16x32_bf16 v[60:63], v[230:233], v[186:189], v[60:63]
	s_mov_b32 m0, s34
	v_mfma_f32_16x16x32_bf16 v[56:59], v[238:241], v[186:189], v[56:59]
	v_lshl_add_u64 v[218:219], v[242:243], 0, s[94:95]
	v_mfma_f32_16x16x32_bf16 v[52:55], v[230:233], v[194:197], v[52:55]
	v_mfma_f32_16x16x32_bf16 v[48:51], v[238:241], v[194:197], v[48:51]
	v_mfma_f32_16x16x32_bf16 v[44:47], v[230:233], v[206:209], v[44:47]
	v_mfma_f32_16x16x32_bf16 v[40:43], v[238:241], v[206:209], v[40:43]
	v_mfma_f32_16x16x32_bf16 v[36:39], v[230:233], v[214:217], v[36:39]
	s_setprio 0
	v_mfma_f32_16x16x32_bf16 v[32:35], v[238:241], v[214:217], v[32:35]
	s_barrier
	ds_read_b128 v[152:155], v201 offset:49152
	ds_read_b128 v[186:189], v201 offset:50176
	ds_read_b128 v[190:193], v201 offset:51200
	ds_read_b128 v[194:197], v201 offset:52224
	ds_read_b128 v[202:205], v201 offset:53248
	ds_read_b128 v[206:209], v201 offset:54272
	ds_read_b128 v[210:213], v201 offset:55296
	ds_read_b128 v[214:217], v201 offset:56320
	global_load_lds_dwordx4 v[218:219], off
	v_lshl_add_u64 v[218:219], v[244:245], 0, s[94:95]
	s_mov_b32 m0, s35
	s_nop 0
	global_load_lds_dwordx4 v[218:219], off
	s_waitcnt lgkmcnt(0)
	s_setprio 1
	s_barrier
; #define PG8_BAR __builtin_amdgcn_s_barrier()
; template <class Epi>
; DI void gemm_phase(LAS unsigned char* lds, const Gemm g, const StaticOrder& S, const Epi& E) {
;     ...
;             PG8_BAR; PG8_WAIT_L(0); PG8_MMA(1, 0, At, B0); PG8_BAR; PG8_SCHED;
;             PG8_STAGE(PG8_SB(1, 1), b3 + hstep);
;             PG8_WAIT_V(6); PG8_BAR; PG8_MMA(1, 1, At, B1); PG8_BAR;
;     template <bool LN, int BJ, int LO, int HI> DI void batch(const f32x4 (&acc)[2][2][4][2], unsigned row0, unsigned col0, const f32x4 (&gv)[2], const f32x4 (&bv)[2]) const {
;         f32x4 r[HI - LO]; float mean[(HI - LO) / 2], rstd[(HI - LO) / 2];
; #pragma unroll
;         for (int i = LO; i < HI; ++i) { const int ai = i >> 3, m = (i >> 1) & 3, n = i & 1; const unsigned row = row0 + ai * HALF + m * 16;
;             if (n == 0) { mean[(i - LO) >> 1] = 0.f; rstd[(i - LO) >> 1] = 1.f;
;                 if (LN) { const float2 st = *(const float2*)(stats + row * 2u); mean[(i - LO) >> 1] = st.x; rstd[(i - LO) >> 1] = st.y; } }
;             r[i - LO] = *(const f32x4*)(src + (row * (unsigned)DM + col0 + BJ * HALF + n * 16)); }
; #pragma unroll
;         for (int i = LO; i < HI; ++i) { const int ai = i >> 3, m = (i >> 1) & 3, n = i & 1; const unsigned row = row0 + ai * HALF + m * 16;
;             *(f32x4*)(Y + (row * (unsigned)DM + col0 + BJ * HALF + n * 16)) = acc[ai][BJ][m][n] + ((r[i - LO] - mean[(i - LO) >> 1]) * rstd[(i - LO) >> 1]) * gv[n] + bv[n]; }
;         __builtin_amdgcn_sched_barrier(0);
;     }
;     template <bool LN, int BJ> DI void load_gb(unsigned col0, f32x4 (&gv)[2], f32x4 (&bv)[2]) const {
; #pragma unroll
;         for (int n = 0; n < 2; ++n) {
;             if (LN) { gv[n] = *(const f32x4*)(gam + col0 + BJ * HALF + n * 16) * ALPHA; bv[n] = *(const f32x4*)(bet + col0 + BJ * HALF + n * 16) * ALPHA; }
;             else { gv[n] = (f32x4){ALPHA, ALPHA, ALPHA, ALPHA}; bv[n] = (f32x4){0.f, 0.f, 0.f, 0.f}; }
;         }
;     }
;     template <bool LN> DI void run(const f32x4 (&acc)[2][2][4][2], const Unit& u, int wr, int wc, int fr, int fq) const {
;         const unsigned row0 = u.pm * BM + wr * 64 + fr, col0 = u.pn * BM + wc * 32 + 4 * fq;
;         f32x4 gv[2], bv[2];
;         load_gb<LN, 0>(col0, gv, bv);
;         batch<LN, 0, 0, 4>(acc, row0, col0, gv, bv);
;         batch<LN, 0, 4, 8>(acc, row0, col0, gv, bv);
;         batch<LN, 0, 8, 12>(acc, row0, col0, gv, bv);
	v_mfma_f32_16x16x32_bf16 v[92:95], v[96:99], v[152:155], v[92:95]
	v_mfma_f32_16x16x32_bf16 v[88:91], v[136:139], v[152:155], v[88:91]
	v_mfma_f32_16x16x32_bf16 v[84:87], v[96:99], v[190:193], v[84:87]
	v_mfma_f32_16x16x32_bf16 v[80:83], v[136:139], v[190:193], v[80:83]
	v_mfma_f32_16x16x32_bf16 v[76:79], v[96:99], v[202:205], v[76:79]
	v_mfma_f32_16x16x32_bf16 v[72:75], v[136:139], v[202:205], v[72:75]
	v_mfma_f32_16x16x32_bf16 v[68:71], v[96:99], v[210:213], v[68:71]
	v_mfma_f32_16x16x32_bf16 v[64:67], v[136:139], v[210:213], v[64:67]
	v_mfma_f32_16x16x32_bf16 v[92:95], v[100:103], v[186:189], v[92:95]
	v_mfma_f32_16x16x32_bf16 v[88:91], v[148:151], v[186:189], v[88:91]
	v_mfma_f32_16x16x32_bf16 v[84:87], v[100:103], v[194:197], v[84:87]
	v_mfma_f32_16x16x32_bf16 v[80:83], v[148:151], v[194:197], v[80:83]
	v_mfma_f32_16x16x32_bf16 v[76:79], v[100:103], v[206:209], v[76:79]
	v_mfma_f32_16x16x32_bf16 v[72:75], v[148:151], v[206:209], v[72:75]
	v_mfma_f32_16x16x32_bf16 v[68:71], v[100:103], v[214:217], v[68:71]
	s_setprio 0
	v_mfma_f32_16x16x32_bf16 v[64:67], v[148:151], v[214:217], v[64:67]
	s_barrier
	s_add_u32 s16, s20, 0x160080
	s_addc_u32 s17, s21, 0
	s_add_i32 s20, s22, s27
	v_lshl_add_u64 v[96:97], s[16:17], 0, v[142:143]
	s_mov_b32 m0, s20
	s_nop 0
	global_load_lds_dwordx4 v[96:97], off
	v_lshl_add_u64 v[96:97], s[16:17], 0, v[140:141]
	s_add_i32 m0, s20, 0x2000
	s_nop 0
	global_load_lds_dwordx4 v[96:97], off
	s_waitcnt vmcnt(6)
	s_setprio 1
	s_barrier
	v_mfma_f32_16x16x32_bf16 v[28:31], v[226:229], v[152:155], v[28:31]
	v_mfma_f32_16x16x32_bf16 v[24:27], v[234:237], v[152:155], v[24:27]
	v_mfma_f32_16x16x32_bf16 v[20:23], v[226:229], v[190:193], v[20:23]
	v_mfma_f32_16x16x32_bf16 v[16:19], v[234:237], v[190:193], v[16:19]
	v_mfma_f32_16x16x32_bf16 v[12:15], v[226:229], v[202:205], v[12:15]
	v_mfma_f32_16x16x32_bf16 v[8:11], v[234:237], v[202:205], v[8:11]
	v_mfma_f32_16x16x32_bf16 v[4:7], v[226:229], v[210:213], v[4:7]
	v_mfma_f32_16x16x32_bf16 v[0:3], v[234:237], v[210:213], v[0:3]
	v_mfma_f32_16x16x32_bf16 v[28:31], v[230:233], v[186:189], v[28:31]
	s_add_i32 s33, s33, 2
	v_mfma_f32_16x16x32_bf16 v[24:27], v[238:241], v[186:189], v[24:27]
	s_add_u32 s4, s4, 0x100
	v_mfma_f32_16x16x32_bf16 v[20:23], v[230:233], v[194:197], v[20:23]
	s_addc_u32 s5, s5, 0
	v_mfma_f32_16x16x32_bf16 v[16:19], v[238:241], v[194:197], v[16:19]
	s_cmpk_gt_u32 s33, 0x55
	v_mfma_f32_16x16x32_bf16 v[12:15], v[230:233], v[206:209], v[12:15]
	s_mov_b64 s[16:17], s[18:19]
	v_mfma_f32_16x16x32_bf16 v[8:11], v[238:241], v[206:209], v[8:11]
	v_mfma_f32_16x16x32_bf16 v[4:7], v[230:233], v[214:217], v[4:7]
	s_setprio 0
	v_mfma_f32_16x16x32_bf16 v[0:3], v[238:241], v[214:217], v[0:3]
	s_barrier
	s_cbranch_scc0 .LBB0_134
	v_lshl_or_b32 v158, s2, 8, v200
	v_lshlrev_b64 v[100:101], 2, v[158:159]
	v_lshl_add_u64 v[150:151], s[12:13], 0, v[100:101]
	global_load_dwordx4 v[96:99], v[150:151], off
	v_lshl_add_u64 v[152:153], s[14:15], 0, v[100:101]
	v_lshl_add_u32 v203, s3, 8, v198
	v_lshlrev_b32_e32 v202, 11, v203
	v_add_u32_e32 v148, v202, v158
	v_mov_b32_e32 v149, v159
	v_lshlrev_b32_e32 v136, 1, v203
	v_mov_b32_e32 v137, v159
	v_lshlrev_b64 v[220:221], 2, v[148:149]
	v_lshl_add_u64 v[154:155], v[136:137], 2, s[96:97]
	v_lshl_add_u64 v[136:137], s[90:91], 0, v[220:221]
	v_or_b32_e32 v204, 16, v158
	v_or_b32_e32 v138, 16, v203
	v_lshlrev_b32_e32 v149, 11, v138
	s_waitcnt vmcnt(0)
	v_pk_mul_f32 v[192:193], v[98:99], s[78:79] op_sel_hi:[1,0]
	v_pk_mul_f32 v[194:195], v[96:97], s[78:79] op_sel_hi:[1,0]
	global_load_dwordx4 v[100:103], v[152:153], off
	global_load_dwordx4 v[96:99], v[150:151], off offset:64
	global_load_dwordx2 v[218:219], v[154:155], off
	global_load_dwordx4 v[206:209], v[136:137], off
	v_add_u32_e32 v136, v202, v204
	v_mov_b32_e32 v137, v159
	v_lshl_add_u64 v[136:137], v[136:137], 2, s[90:91]
	global_load_dwordx4 v[210:213], v[136:137], off
	v_lshlrev_b32_e32 v136, 1, v138
	v_mov_b32_e32 v137, v159
	v_lshl_add_u64 v[186:187], v[136:137], 2, s[96:97]
	v_add_u32_e32 v136, v149, v158
	v_lshl_add_u64 v[136:137], v[136:137], 2, s[90:91]
	global_load_dwordx2 v[196:197], v[186:187], off
	global_load_dwordx4 v[214:217], v[136:137], off
	v_add_u32_e32 v136, v149, v204
	v_mov_b32_e32 v137, v159
	v_lshl_add_u64 v[136:137], v[136:137], 2, s[90:91]
	global_load_dwordx4 v[136:139], v[136:137], off
	s_waitcnt vmcnt(0)
	v_pk_mul_f32 v[188:189], v[98:99], s[78:79] op_sel_hi:[1,0]
	v_pk_mul_f32 v[190:191], v[96:97], s[78:79] op_sel_hi:[1,0]
	global_load_dwordx4 v[96:99], v[152:153], off offset:64
	v_sub_f32_e32 v207, v207, v218
	v_sub_f32_e32 v206, v206, v218
	v_sub_f32_e32 v209, v209, v218
	v_sub_f32_e32 v208, v208, v218
	v_pk_mul_f32 v[208:209], v[218:219], v[208:209] op_sel:[1,0]
	v_pk_mul_f32 v[206:207], v[218:219], v[206:207] op_sel:[1,0]
	v_pk_fma_f32 v[134:135], v[192:193], v[208:209], v[134:135]
	v_pk_fma_f32 v[132:133], v[194:195], v[206:207], v[132:133]
	v_pk_fma_f32 v[134:135], v[102:103], s[78:79], v[134:135] op_sel_hi:[1,0,1]
	v_pk_fma_f32 v[132:133], v[100:101], s[78:79], v[132:133] op_sel_hi:[1,0,1]
	v_lshl_add_u64 v[206:207], s[88:89], 0, v[220:221]
	global_store_dwordx4 v[206:207], v[132:135], off
	s_nop 1
	v_sub_f32_e32 v133, v211, v218
	v_sub_f32_e32 v132, v210, v218
	v_sub_f32_e32 v135, v213, v218
	v_sub_f32_e32 v134, v212, v218
	v_pk_mul_f32 v[134:135], v[218:219], v[134:135] op_sel:[1,0]
	v_pk_mul_f32 v[132:133], v[218:219], v[132:133] op_sel:[1,0]
	v_pk_fma_f32 v[130:131], v[188:189], v[134:135], v[130:131]
	v_pk_fma_f32 v[128:129], v[190:191], v[132:133], v[128:129]
	v_or_b32_e32 v132, 16, v148
	v_mov_b32_e32 v133, v159
	v_lshl_add_u64 v[132:133], v[132:133], 2, s[88:89]
	s_waitcnt vmcnt(0)
;     template <bool LN, int BJ, int LO, int HI> DI void batch(const f32x4 (&acc)[2][2][4][2], unsigned row0, unsigned col0, const f32x4 (&gv)[2], const f32x4 (&bv)[2]) const {
;         f32x4 r[HI - LO]; float mean[(HI - LO) / 2], rstd[(HI - LO) / 2];
; #pragma unroll
;         for (int i = LO; i < HI; ++i) { const int ai = i >> 3, m = (i >> 1) & 3, n = i & 1; const unsigned row = row0 + ai * HALF + m * 16;
;             if (n == 0) { mean[(i - LO) >> 1] = 0.f; rstd[(i - LO) >> 1] = 1.f;
;                 if (LN) { const float2 st = *(const float2*)(stats + row * 2u); mean[(i - LO) >> 1] = st.x; rstd[(i - LO) >> 1] = st.y; } }
;             r[i - LO] = *(const f32x4*)(src + (row * (unsigned)DM + col0 + BJ * HALF + n * 16)); }
; #pragma unroll
;         for (int i = LO; i < HI; ++i) { const int ai = i >> 3, m = (i >> 1) & 3, n = i & 1; const unsigned row = row0 + ai * HALF + m * 16;
;             *(f32x4*)(Y + (row * (unsigned)DM + col0 + BJ * HALF + n * 16)) = acc[ai][BJ][m][n] + ((r[i - LO] - mean[(i - LO) >> 1]) * rstd[(i - LO) >> 1]) * gv[n] + bv[n]; }
;         __builtin_amdgcn_sched_barrier(0);
;     }
;     template <bool LN, int BJ> DI void load_gb(unsigned col0, f32x4 (&gv)[2], f32x4 (&bv)[2]) const {
; #pragma unroll
;         for (int n = 0; n < 2; ++n) {
;             if (LN) { gv[n] = *(const f32x4*)(gam + col0 + BJ * HALF + n * 16) * ALPHA; bv[n] = *(const f32x4*)(bet + col0 + BJ * HALF + n * 16) * ALPHA; }
;             else { gv[n] = (f32x4){ALPHA, ALPHA, ALPHA, ALPHA}; bv[n] = (f32x4){0.f, 0.f, 0.f, 0.f}; }
;         }
;     }
	v_pk_fma_f32 v[130:131], v[98:99], s[78:79], v[130:131] op_sel_hi:[1,0,1]
	v_pk_fma_f32 v[128:129], v[96:97], s[78:79], v[128:129] op_sel_hi:[1,0,1]
	global_store_dwordx4 v[132:133], v[128:131], off
	s_nop 1
	v_sub_f32_e32 v129, v215, v196
	v_sub_f32_e32 v128, v214, v196
	v_sub_f32_e32 v131, v217, v196
	v_sub_f32_e32 v130, v216, v196
	v_pk_mul_f32 v[130:131], v[196:197], v[130:131] op_sel:[1,0]
	v_pk_mul_f32 v[128:129], v[196:197], v[128:129] op_sel:[1,0]
	v_pk_fma_f32 v[126:127], v[192:193], v[130:131], v[126:127]
	v_pk_fma_f32 v[124:125], v[194:195], v[128:129], v[124:125]
	v_add_u32_e32 v128, 0x8000, v148
	v_mov_b32_e32 v129, v159
	v_pk_fma_f32 v[126:127], v[102:103], s[78:79], v[126:127] op_sel_hi:[1,0,1]
	v_pk_fma_f32 v[124:125], v[100:101], s[78:79], v[124:125] op_sel_hi:[1,0,1]
	v_lshl_add_u64 v[128:129], v[128:129], 2, s[88:89]
	global_store_dwordx4 v[128:129], v[124:127], off
	s_nop 1
	v_sub_f32_e32 v125, v137, v196
	v_sub_f32_e32 v124, v136, v196
	v_sub_f32_e32 v127, v139, v196
	v_sub_f32_e32 v126, v138, v196
	v_pk_mul_f32 v[126:127], v[196:197], v[126:127] op_sel:[1,0]
	v_pk_mul_f32 v[124:125], v[196:197], v[124:125] op_sel:[1,0]
	v_pk_fma_f32 v[122:123], v[188:189], v[126:127], v[122:123]
	v_pk_fma_f32 v[120:121], v[190:191], v[124:125], v[120:121]
	v_add_u32_e32 v124, 0x8010, v148
	v_mov_b32_e32 v125, v159
	v_pk_fma_f32 v[122:123], v[98:99], s[78:79], v[122:123] op_sel_hi:[1,0,1]
	v_pk_fma_f32 v[120:121], v[96:97], s[78:79], v[120:121] op_sel_hi:[1,0,1]
	v_lshl_add_u64 v[124:125], v[124:125], 2, s[88:89]
	global_store_dwordx4 v[124:125], v[120:123], off
	s_nop 1
	v_or_b32_e32 v122, 32, v203
	v_lshlrev_b32_e32 v124, 11, v122
	v_lshlrev_b32_e32 v120, 1, v122
	v_mov_b32_e32 v121, v159
	v_add_u32_e32 v122, v124, v158
	v_mov_b32_e32 v123, v159
	v_lshl_add_u64 v[120:121], v[120:121], 2, s[96:97]
	v_lshl_add_u64 v[122:123], v[122:123], 2, s[90:91]
	global_load_dwordx2 v[138:139], v[120:121], off
	global_load_dwordx4 v[126:129], v[122:123], off
	v_add_u32_e32 v122, v124, v204
	v_mov_b32_e32 v123, v159
	v_lshl_add_u64 v[122:123], v[122:123], 2, s[90:91]
	global_load_dwordx4 v[130:133], v[122:123], off
	v_or_b32_e32 v125, 48, v203
	v_lshlrev_b32_e32 v122, 1, v125
	v_lshlrev_b32_e32 v125, 11, v125
	v_mov_b32_e32 v123, v159
	v_add_u32_e32 v134, v125, v158
	v_mov_b32_e32 v135, v159
	v_lshl_add_u64 v[122:123], v[122:123], 2, s[96:97]
	v_lshl_add_u64 v[134:135], v[134:135], 2, s[90:91]
	global_load_dwordx2 v[196:197], v[122:123], off
	v_add_u32_e32 v206, v125, v204
	global_load_dwordx4 v[134:137], v[134:135], off
	v_mov_b32_e32 v207, v159
	v_lshl_add_u64 v[206:207], v[206:207], 2, s[90:91]
	global_load_dwordx4 v[206:209], v[206:207], off
	s_waitcnt vmcnt(0)
	v_sub_f32_e32 v127, v127, v138
	v_sub_f32_e32 v126, v126, v138
	v_sub_f32_e32 v129, v129, v138
	v_sub_f32_e32 v128, v128, v138
	v_pk_mul_f32 v[128:129], v[138:139], v[128:129] op_sel:[1,0]
	v_pk_mul_f32 v[126:127], v[138:139], v[126:127] op_sel:[1,0]
	v_pk_fma_f32 v[118:119], v[192:193], v[128:129], v[118:119]
	v_pk_fma_f32 v[116:117], v[194:195], v[126:127], v[116:117]
	v_add_u32_e32 v126, 0x10000, v148
	v_mov_b32_e32 v127, v159
	v_pk_fma_f32 v[118:119], v[102:103], s[78:79], v[118:119] op_sel_hi:[1,0,1]
	v_pk_fma_f32 v[116:117], v[100:101], s[78:79], v[116:117] op_sel_hi:[1,0,1]
	v_lshl_add_u64 v[126:127], v[126:127], 2, s[88:89]
	global_store_dwordx4 v[126:127], v[116:119], off
	s_nop 1
	v_sub_f32_e32 v117, v131, v138
	v_sub_f32_e32 v116, v130, v138
	v_sub_f32_e32 v119, v133, v138
	v_sub_f32_e32 v118, v132, v138
	v_pk_mul_f32 v[118:119], v[138:139], v[118:119] op_sel:[1,0]
	v_pk_mul_f32 v[116:117], v[138:139], v[116:117] op_sel:[1,0]
	v_pk_fma_f32 v[114:115], v[188:189], v[118:119], v[114:115]
	v_pk_fma_f32 v[112:113], v[190:191], v[116:117], v[112:113]
	v_add_u32_e32 v116, 0x10010, v148
	v_mov_b32_e32 v117, v159
	v_pk_fma_f32 v[114:115], v[98:99], s[78:79], v[114:115] op_sel_hi:[1,0,1]
	v_pk_fma_f32 v[112:113], v[96:97], s[78:79], v[112:113] op_sel_hi:[1,0,1]
	v_lshl_add_u64 v[116:117], v[116:117], 2, s[88:89]
	global_store_dwordx4 v[116:117], v[112:115], off
	s_nop 1
	v_sub_f32_e32 v113, v135, v196
	v_sub_f32_e32 v112, v134, v196
	v_sub_f32_e32 v115, v137, v196
	v_sub_f32_e32 v114, v136, v196
	v_pk_mul_f32 v[114:115], v[196:197], v[114:115] op_sel:[1,0]
	v_pk_mul_f32 v[112:113], v[196:197], v[112:113] op_sel:[1,0]
	v_pk_fma_f32 v[110:111], v[192:193], v[114:115], v[110:111]
	v_pk_fma_f32 v[108:109], v[194:195], v[112:113], v[108:109]
	v_add_u32_e32 v112, 0x18000, v148
	v_mov_b32_e32 v113, v159
	v_pk_fma_f32 v[110:111], v[102:103], s[78:79], v[110:111] op_sel_hi:[1,0,1]
	v_pk_fma_f32 v[108:109], v[100:101], s[78:79], v[108:109] op_sel_hi:[1,0,1]
	v_lshl_add_u64 v[112:113], v[112:113], 2, s[88:89]
	global_store_dwordx4 v[112:113], v[108:111], off
	s_nop 1
	v_sub_f32_e32 v109, v207, v196
	v_sub_f32_e32 v108, v206, v196
	v_sub_f32_e32 v111, v209, v196
	v_sub_f32_e32 v110, v208, v196
	v_pk_mul_f32 v[110:111], v[196:197], v[110:111] op_sel:[1,0]
	v_pk_mul_f32 v[108:109], v[196:197], v[108:109] op_sel:[1,0]
	v_pk_fma_f32 v[106:107], v[188:189], v[110:111], v[106:107]
	v_pk_fma_f32 v[104:105], v[190:191], v[108:109], v[104:105]
	v_add_u32_e32 v108, 0x18010, v148
	v_mov_b32_e32 v109, v159
	v_pk_fma_f32 v[106:107], v[98:99], s[78:79], v[106:107] op_sel_hi:[1,0,1]
	v_pk_fma_f32 v[104:105], v[96:97], s[78:79], v[104:105] op_sel_hi:[1,0,1]
	v_lshl_add_u64 v[108:109], v[108:109], 2, s[88:89]
	global_store_dwordx4 v[108:109], v[104:107], off
	s_nop 1
	v_add_u32_e32 v106, 0x80, v203
	v_lshlrev_b32_e32 v114, 11, v106
	v_lshlrev_b32_e32 v104, 1, v106
	v_mov_b32_e32 v105, v159
	v_add_u32_e32 v106, v114, v158
	v_mov_b32_e32 v107, v159
	v_lshl_add_u64 v[104:105], v[104:105], 2, s[96:97]
	v_lshl_add_u64 v[106:107], v[106:107], 2, s[90:91]
	global_load_dwordx2 v[112:113], v[104:105], off
	global_load_dwordx4 v[108:111], v[106:107], off
	v_add_u32_e32 v106, v114, v204
	v_mov_b32_e32 v107, v159
	v_lshl_add_u64 v[106:107], v[106:107], 2, s[90:91]
	global_load_dwordx4 v[116:119], v[106:107], off
	v_add_u32_e32 v115, 0x90, v203
	v_lshlrev_b32_e32 v106, 1, v115
	v_lshlrev_b32_e32 v115, 11, v115
	v_mov_b32_e32 v107, v159
	v_add_u32_e32 v126, v115, v158
	v_mov_b32_e32 v127, v159
	v_lshl_add_u64 v[106:107], v[106:107], 2, s[96:97]
	v_lshl_add_u64 v[126:127], v[126:127], 2, s[90:91]
	global_load_dwordx2 v[134:135], v[106:107], off
	v_add_u32_e32 v130, v115, v204
	global_load_dwordx4 v[126:129], v[126:127], off
	v_mov_b32_e32 v131, v159
	v_lshl_add_u64 v[130:131], v[130:131], 2, s[90:91]
	global_load_dwordx4 v[130:133], v[130:131], off
	s_waitcnt vmcnt(0)
;     template <bool LN, int BJ, int LO, int HI> DI void batch(const f32x4 (&acc)[2][2][4][2], unsigned row0, unsigned col0, const f32x4 (&gv)[2], const f32x4 (&bv)[2]) const {
;         f32x4 r[HI - LO]; float mean[(HI - LO) / 2], rstd[(HI - LO) / 2];
; #pragma unroll
;         for (int i = LO; i < HI; ++i) { const int ai = i >> 3, m = (i >> 1) & 3, n = i & 1; const unsigned row = row0 + ai * HALF + m * 16;
;             if (n == 0) { mean[(i - LO) >> 1] = 0.f; rstd[(i - LO) >> 1] = 1.f;
;                 if (LN) { const float2 st = *(const float2*)(stats + row * 2u); mean[(i - LO) >> 1] = st.x; rstd[(i - LO) >> 1] = st.y; } }
;             r[i - LO] = *(const f32x4*)(src + (row * (unsigned)DM + col0 + BJ * HALF + n * 16)); }
; #pragma unroll
;         for (int i = LO; i < HI; ++i) { const int ai = i >> 3, m = (i >> 1) & 3, n = i & 1; const unsigned row = row0 + ai * HALF + m * 16;
;             *(f32x4*)(Y + (row * (unsigned)DM + col0 + BJ * HALF + n * 16)) = acc[ai][BJ][m][n] + ((r[i - LO] - mean[(i - LO) >> 1]) * rstd[(i - LO) >> 1]) * gv[n] + bv[n]; }
	v_sub_f32_e32 v109, v109, v112
	v_sub_f32_e32 v108, v108, v112
	v_sub_f32_e32 v111, v111, v112
	v_sub_f32_e32 v110, v110, v112
	v_pk_mul_f32 v[110:111], v[112:113], v[110:111] op_sel:[1,0]
	v_pk_mul_f32 v[108:109], v[112:113], v[108:109] op_sel:[1,0]
	v_pk_fma_f32 v[94:95], v[192:193], v[110:111], v[94:95]
	v_pk_fma_f32 v[92:93], v[194:195], v[108:109], v[92:93]
	v_add_u32_e32 v108, 0x40000, v148
	v_mov_b32_e32 v109, v159
	v_pk_fma_f32 v[94:95], v[102:103], s[78:79], v[94:95] op_sel_hi:[1,0,1]
	v_pk_fma_f32 v[92:93], v[100:101], s[78:79], v[92:93] op_sel_hi:[1,0,1]
	v_lshl_add_u64 v[108:109], v[108:109], 2, s[88:89]
	global_store_dwordx4 v[108:109], v[92:95], off
	s_nop 1
	v_sub_f32_e32 v93, v117, v112
	v_sub_f32_e32 v92, v116, v112
	v_sub_f32_e32 v95, v119, v112
	v_sub_f32_e32 v94, v118, v112
	v_pk_mul_f32 v[94:95], v[112:113], v[94:95] op_sel:[1,0]
	v_pk_mul_f32 v[92:93], v[112:113], v[92:93] op_sel:[1,0]
	v_pk_fma_f32 v[90:91], v[188:189], v[94:95], v[90:91]
	v_pk_fma_f32 v[88:89], v[190:191], v[92:93], v[88:89]
	v_add_u32_e32 v92, 0x40010, v148
	v_mov_b32_e32 v93, v159
	v_pk_fma_f32 v[90:91], v[98:99], s[78:79], v[90:91] op_sel_hi:[1,0,1]
	v_pk_fma_f32 v[88:89], v[96:97], s[78:79], v[88:89] op_sel_hi:[1,0,1]
	v_lshl_add_u64 v[92:93], v[92:93], 2, s[88:89]
	global_store_dwordx4 v[92:93], v[88:91], off
	s_nop 1
	v_sub_f32_e32 v89, v127, v134
	v_sub_f32_e32 v88, v126, v134
	v_sub_f32_e32 v91, v129, v134
	v_sub_f32_e32 v90, v128, v134
	v_pk_mul_f32 v[90:91], v[134:135], v[90:91] op_sel:[1,0]
	v_pk_mul_f32 v[88:89], v[134:135], v[88:89] op_sel:[1,0]
	v_pk_fma_f32 v[86:87], v[192:193], v[90:91], v[86:87]
	v_pk_fma_f32 v[84:85], v[194:195], v[88:89], v[84:85]
	v_add_u32_e32 v88, 0x48000, v148
	v_mov_b32_e32 v89, v159
	v_pk_fma_f32 v[86:87], v[102:103], s[78:79], v[86:87] op_sel_hi:[1,0,1]
	v_pk_fma_f32 v[84:85], v[100:101], s[78:79], v[84:85] op_sel_hi:[1,0,1]
	v_lshl_add_u64 v[88:89], v[88:89], 2, s[88:89]
	global_store_dwordx4 v[88:89], v[84:87], off
	s_nop 1
	v_sub_f32_e32 v85, v131, v134
	v_sub_f32_e32 v84, v130, v134
	v_sub_f32_e32 v87, v133, v134
	v_sub_f32_e32 v86, v132, v134
	v_pk_mul_f32 v[86:87], v[134:135], v[86:87] op_sel:[1,0]
	v_pk_mul_f32 v[84:85], v[134:135], v[84:85] op_sel:[1,0]
	v_pk_fma_f32 v[82:83], v[188:189], v[86:87], v[82:83]
	v_pk_fma_f32 v[80:81], v[190:191], v[84:85], v[80:81]
	v_add_u32_e32 v84, 0x48010, v148
	v_mov_b32_e32 v85, v159
	v_pk_fma_f32 v[82:83], v[98:99], s[78:79], v[82:83] op_sel_hi:[1,0,1]
	v_pk_fma_f32 v[80:81], v[96:97], s[78:79], v[80:81] op_sel_hi:[1,0,1]
	v_lshl_add_u64 v[84:85], v[84:85], 2, s[88:89]
	global_store_dwordx4 v[84:85], v[80:83], off
	s_nop 1
	v_add_u32_e32 v82, 0xa0, v203
	v_lshlrev_b32_e32 v80, 1, v82
	v_mov_b32_e32 v81, v159
	v_lshlrev_b32_e32 v116, 11, v82
	v_lshl_add_u64 v[108:109], v[80:81], 2, s[96:97]
	v_add_u32_e32 v80, v116, v158
	v_lshl_add_u64 v[80:81], v[80:81], 2, s[90:91]
	global_load_dwordx2 v[112:113], v[108:109], off
	v_add_u32_e32 v84, v116, v204
	global_load_dwordx4 v[80:83], v[80:81], off
	v_mov_b32_e32 v85, v159
	v_lshl_add_u64 v[84:85], v[84:85], 2, s[90:91]
	global_load_dwordx4 v[84:87], v[84:85], off
	v_add_u32_e32 v90, 0xb0, v203
	v_lshlrev_b32_e32 v88, 1, v90
	v_mov_b32_e32 v89, v159
	v_lshlrev_b32_e32 v117, 11, v90
	v_lshl_add_u64 v[110:111], v[88:89], 2, s[96:97]
	v_add_u32_e32 v88, v117, v158
	v_lshl_add_u64 v[88:89], v[88:89], 2, s[90:91]
	global_load_dwordx2 v[118:119], v[110:111], off
	v_add_u32_e32 v92, v117, v204
	global_load_dwordx4 v[88:91], v[88:89], off
	v_mov_b32_e32 v93, v159
	v_lshl_add_u64 v[92:93], v[92:93], 2, s[90:91]
	global_load_dwordx4 v[92:95], v[92:93], off
	s_waitcnt vmcnt(0)
	v_sub_f32_e32 v81, v81, v112
	v_sub_f32_e32 v80, v80, v112
	v_sub_f32_e32 v83, v83, v112
	v_sub_f32_e32 v82, v82, v112
	v_pk_mul_f32 v[82:83], v[112:113], v[82:83] op_sel:[1,0]
	v_pk_mul_f32 v[80:81], v[112:113], v[80:81] op_sel:[1,0]
	v_pk_fma_f32 v[78:79], v[192:193], v[82:83], v[78:79]
	v_pk_fma_f32 v[76:77], v[194:195], v[80:81], v[76:77]
	v_add_u32_e32 v80, 0x50000, v148
	v_mov_b32_e32 v81, v159
	v_pk_fma_f32 v[78:79], v[102:103], s[78:79], v[78:79] op_sel_hi:[1,0,1]
	v_pk_fma_f32 v[76:77], v[100:101], s[78:79], v[76:77] op_sel_hi:[1,0,1]
	v_lshl_add_u64 v[80:81], v[80:81], 2, s[88:89]
	global_store_dwordx4 v[80:81], v[76:79], off
	s_nop 1
	v_sub_f32_e32 v77, v85, v112
	v_sub_f32_e32 v76, v84, v112
	v_sub_f32_e32 v79, v87, v112
	v_sub_f32_e32 v78, v86, v112
	v_pk_mul_f32 v[78:79], v[112:113], v[78:79] op_sel:[1,0]
	v_pk_mul_f32 v[76:77], v[112:113], v[76:77] op_sel:[1,0]
	v_pk_fma_f32 v[74:75], v[188:189], v[78:79], v[74:75]
	v_pk_fma_f32 v[72:73], v[190:191], v[76:77], v[72:73]
	v_add_u32_e32 v76, 0x50010, v148
	v_mov_b32_e32 v77, v159
	v_pk_fma_f32 v[74:75], v[98:99], s[78:79], v[74:75] op_sel_hi:[1,0,1]
	v_pk_fma_f32 v[72:73], v[96:97], s[78:79], v[72:73] op_sel_hi:[1,0,1]
	v_lshl_add_u64 v[76:77], v[76:77], 2, s[88:89]
	global_store_dwordx4 v[76:77], v[72:75], off
	s_nop 1
	v_sub_f32_e32 v73, v89, v118
	v_sub_f32_e32 v72, v88, v118
	v_sub_f32_e32 v75, v91, v118
	v_sub_f32_e32 v74, v90, v118
	v_pk_mul_f32 v[74:75], v[118:119], v[74:75] op_sel:[1,0]
	v_pk_mul_f32 v[72:73], v[118:119], v[72:73] op_sel:[1,0]
	v_pk_fma_f32 v[70:71], v[192:193], v[74:75], v[70:71]
	v_pk_fma_f32 v[68:69], v[194:195], v[72:73], v[68:69]
	v_add_u32_e32 v72, 0x58000, v148
	v_mov_b32_e32 v73, v159
	v_pk_fma_f32 v[70:71], v[102:103], s[78:79], v[70:71] op_sel_hi:[1,0,1]
	v_pk_fma_f32 v[68:69], v[100:101], s[78:79], v[68:69] op_sel_hi:[1,0,1]
	v_lshl_add_u64 v[72:73], v[72:73], 2, s[88:89]
	global_store_dwordx4 v[72:73], v[68:71], off
	s_nop 1
	v_sub_f32_e32 v69, v93, v118
	v_sub_f32_e32 v68, v92, v118
	v_sub_f32_e32 v71, v95, v118
	v_sub_f32_e32 v70, v94, v118
	v_pk_mul_f32 v[70:71], v[118:119], v[70:71] op_sel:[1,0]
	v_pk_mul_f32 v[68:69], v[118:119], v[68:69] op_sel:[1,0]
	v_pk_fma_f32 v[66:67], v[188:189], v[70:71], v[66:67]
	v_pk_fma_f32 v[64:65], v[190:191], v[68:69], v[64:65]
	v_add_u32_e32 v68, 0x58010, v148
	v_mov_b32_e32 v69, v159
	v_pk_fma_f32 v[66:67], v[98:99], s[78:79], v[66:67] op_sel_hi:[1,0,1]
	v_pk_fma_f32 v[64:65], v[96:97], s[78:79], v[64:65] op_sel_hi:[1,0,1]
	v_lshl_add_u64 v[68:69], v[68:69], 2, s[88:89]
	global_store_dwordx4 v[68:69], v[64:67], off
	global_load_dwordx4 v[64:67], v[150:151], off offset:512
	v_or_b32_e32 v119, 0x80, v158
	v_add_u32_e32 v72, v202, v119
	v_mov_b32_e32 v73, v159
	v_lshl_add_u64 v[72:73], v[72:73], 2, s[90:91]
	v_or_b32_e32 v118, 0x90, v158
	v_add_u32_e32 v158, v202, v118
	s_waitcnt vmcnt(0)
;     template <bool LN, int BJ, int LO, int HI> DI void batch(const f32x4 (&acc)[2][2][4][2], unsigned row0, unsigned col0, const f32x4 (&gv)[2], const f32x4 (&bv)[2]) const {
;         f32x4 r[HI - LO]; float mean[(HI - LO) / 2], rstd[(HI - LO) / 2];
; #pragma unroll
;         for (int i = LO; i < HI; ++i) { const int ai = i >> 3, m = (i >> 1) & 3, n = i & 1; const unsigned row = row0 + ai * HALF + m * 16;
;             if (n == 0) { mean[(i - LO) >> 1] = 0.f; rstd[(i - LO) >> 1] = 1.f;
;                 if (LN) { const float2 st = *(const float2*)(stats + row * 2u); mean[(i - LO) >> 1] = st.x; rstd[(i - LO) >> 1] = st.y; } }
;             r[i - LO] = *(const f32x4*)(src + (row * (unsigned)DM + col0 + BJ * HALF + n * 16)); }
; #pragma unroll
;         for (int i = LO; i < HI; ++i) { const int ai = i >> 3, m = (i >> 1) & 3, n = i & 1; const unsigned row = row0 + ai * HALF + m * 16;
;             *(f32x4*)(Y + (row * (unsigned)DM + col0 + BJ * HALF + n * 16)) = acc[ai][BJ][m][n] + ((r[i - LO] - mean[(i - LO) >> 1]) * rstd[(i - LO) >> 1]) * gv[n] + bv[n]; }
;         __builtin_amdgcn_sched_barrier(0);
;     }
;     template <bool LN, int BJ> DI void load_gb(unsigned col0, f32x4 (&gv)[2], f32x4 (&bv)[2]) const {
; #pragma unroll
;         for (int n = 0; n < 2; ++n) {
;             if (LN) { gv[n] = *(const f32x4*)(gam + col0 + BJ * HALF + n * 16) * ALPHA; bv[n] = *(const f32x4*)(bet + col0 + BJ * HALF + n * 16) * ALPHA; }
;             else { gv[n] = (f32x4){ALPHA, ALPHA, ALPHA, ALPHA}; bv[n] = (f32x4){0.f, 0.f, 0.f, 0.f}; }
;         }
;     }
	v_pk_mul_f32 v[96:97], v[66:67], s[78:79] op_sel_hi:[1,0]
	v_pk_mul_f32 v[98:99], v[64:65], s[78:79] op_sel_hi:[1,0]
	global_load_dwordx4 v[68:71], v[152:153], off offset:512
	global_load_dwordx4 v[64:67], v[150:151], off offset:576
	global_load_dwordx2 v[138:139], v[154:155], off
	global_load_dwordx4 v[126:129], v[72:73], off
	v_lshl_add_u64 v[72:73], v[158:159], 2, s[90:91]
	v_add_u32_e32 v158, v149, v119
	s_waitcnt vmcnt(0)
	v_pk_mul_f32 v[92:93], v[66:67], s[78:79] op_sel_hi:[1,0]
	v_pk_mul_f32 v[94:95], v[64:65], s[78:79] op_sel_hi:[1,0]
	global_load_dwordx4 v[64:67], v[152:153], off offset:576
	global_load_dwordx4 v[130:133], v[72:73], off
	global_load_dwordx2 v[112:113], v[186:187], off
	v_lshl_add_u64 v[72:73], v[158:159], 2, s[90:91]
	global_load_dwordx4 v[134:137], v[72:73], off
	v_add_u32_e32 v158, v149, v118
	v_lshl_add_u64 v[72:73], v[158:159], 2, s[90:91]
	global_load_dwordx4 v[88:91], v[72:73], off
	global_load_dwordx2 v[102:103], v[120:121], off
	v_add_u32_e32 v158, v124, v119
	v_lshl_add_u64 v[72:73], v[158:159], 2, s[90:91]
	global_load_dwordx4 v[84:87], v[72:73], off
	v_add_u32_e32 v158, v124, v118
	v_lshl_add_u64 v[72:73], v[158:159], 2, s[90:91]
	global_load_dwordx4 v[80:83], v[72:73], off
	global_load_dwordx2 v[100:101], v[122:123], off
	v_add_u32_e32 v158, v125, v119
	v_lshl_add_u64 v[72:73], v[158:159], 2, s[90:91]
	global_load_dwordx4 v[76:79], v[72:73], off
	v_add_u32_e32 v158, v125, v118
	v_lshl_add_u64 v[72:73], v[158:159], 2, s[90:91]
	global_load_dwordx4 v[72:75], v[72:73], off
	v_sub_f32_e32 v121, v127, v138
	v_sub_f32_e32 v120, v126, v138
	v_sub_f32_e32 v123, v129, v138
	v_sub_f32_e32 v122, v128, v138
	v_pk_mul_f32 v[122:123], v[138:139], v[122:123] op_sel:[1,0]
	v_pk_mul_f32 v[120:121], v[138:139], v[120:121] op_sel:[1,0]
	v_or_b32_e32 v158, 0x80, v148
	v_pk_fma_f32 v[60:61], v[98:99], v[120:121], v[60:61]
	v_pk_fma_f32 v[62:63], v[96:97], v[122:123], v[62:63]
	v_pk_fma_f32 v[60:61], v[68:69], s[78:79], v[60:61] op_sel_hi:[1,0,1]
	v_pk_fma_f32 v[62:63], v[70:71], s[78:79], v[62:63] op_sel_hi:[1,0,1]
	v_lshl_add_u64 v[120:121], v[158:159], 2, s[88:89]
	global_store_dwordx4 v[120:121], v[60:63], off
	v_or_b32_e32 v158, 0x90, v148
	s_waitcnt vmcnt(0)
	v_sub_f32_e32 v61, v131, v138
	v_sub_f32_e32 v60, v130, v138
	v_sub_f32_e32 v63, v133, v138
	v_sub_f32_e32 v62, v132, v138
	v_pk_mul_f32 v[62:63], v[138:139], v[62:63] op_sel:[1,0]
	v_pk_mul_f32 v[60:61], v[138:139], v[60:61] op_sel:[1,0]
	v_pk_fma_f32 v[58:59], v[92:93], v[62:63], v[58:59]
	v_pk_fma_f32 v[56:57], v[94:95], v[60:61], v[56:57]
	v_pk_fma_f32 v[58:59], v[66:67], s[78:79], v[58:59] op_sel_hi:[1,0,1]
	v_pk_fma_f32 v[56:57], v[64:65], s[78:79], v[56:57] op_sel_hi:[1,0,1]
	v_lshl_add_u64 v[60:61], v[158:159], 2, s[88:89]
	global_store_dwordx4 v[60:61], v[56:59], off
	v_add_u32_e32 v158, 0x8080, v148
	s_nop 0
	v_sub_f32_e32 v57, v135, v112
	v_sub_f32_e32 v56, v134, v112
	v_sub_f32_e32 v59, v137, v112
	v_sub_f32_e32 v58, v136, v112
	v_pk_mul_f32 v[58:59], v[112:113], v[58:59] op_sel:[1,0]
	v_pk_mul_f32 v[56:57], v[112:113], v[56:57] op_sel:[1,0]
	v_pk_fma_f32 v[54:55], v[96:97], v[58:59], v[54:55]
	v_pk_fma_f32 v[52:53], v[98:99], v[56:57], v[52:53]
	v_pk_fma_f32 v[54:55], v[70:71], s[78:79], v[54:55] op_sel_hi:[1,0,1]
	v_pk_fma_f32 v[52:53], v[68:69], s[78:79], v[52:53] op_sel_hi:[1,0,1]
	v_lshl_add_u64 v[56:57], v[158:159], 2, s[88:89]
	global_store_dwordx4 v[56:57], v[52:55], off
	v_add_u32_e32 v158, 0x8090, v148
	s_nop 0
	v_sub_f32_e32 v53, v89, v112
	v_sub_f32_e32 v52, v88, v112
	v_sub_f32_e32 v55, v91, v112
	v_sub_f32_e32 v54, v90, v112
	v_pk_mul_f32 v[54:55], v[112:113], v[54:55] op_sel:[1,0]
	v_pk_mul_f32 v[52:53], v[112:113], v[52:53] op_sel:[1,0]
	v_pk_fma_f32 v[50:51], v[92:93], v[54:55], v[50:51]
	v_pk_fma_f32 v[48:49], v[94:95], v[52:53], v[48:49]
	v_pk_fma_f32 v[50:51], v[66:67], s[78:79], v[50:51] op_sel_hi:[1,0,1]
	v_pk_fma_f32 v[48:49], v[64:65], s[78:79], v[48:49] op_sel_hi:[1,0,1]
	v_lshl_add_u64 v[52:53], v[158:159], 2, s[88:89]
	global_store_dwordx4 v[52:53], v[48:51], off
	v_add_u32_e32 v158, 0x10080, v148
	s_nop 0
	v_sub_f32_e32 v49, v85, v102
	v_sub_f32_e32 v48, v84, v102
	v_sub_f32_e32 v51, v87, v102
	v_sub_f32_e32 v50, v86, v102
	v_pk_mul_f32 v[50:51], v[102:103], v[50:51] op_sel:[1,0]
	v_pk_mul_f32 v[48:49], v[102:103], v[48:49] op_sel:[1,0]
	v_pk_fma_f32 v[46:47], v[96:97], v[50:51], v[46:47]
	v_pk_fma_f32 v[44:45], v[98:99], v[48:49], v[44:45]
	v_pk_fma_f32 v[46:47], v[70:71], s[78:79], v[46:47] op_sel_hi:[1,0,1]
	v_pk_fma_f32 v[44:45], v[68:69], s[78:79], v[44:45] op_sel_hi:[1,0,1]
	v_lshl_add_u64 v[48:49], v[158:159], 2, s[88:89]
	global_store_dwordx4 v[48:49], v[44:47], off
	v_add_u32_e32 v158, 0x10090, v148
	s_nop 0
	v_sub_f32_e32 v45, v81, v102
	v_sub_f32_e32 v44, v80, v102
	v_sub_f32_e32 v47, v83, v102
	v_sub_f32_e32 v46, v82, v102
	v_pk_mul_f32 v[46:47], v[102:103], v[46:47] op_sel:[1,0]
	v_pk_mul_f32 v[44:45], v[102:103], v[44:45] op_sel:[1,0]
	v_pk_fma_f32 v[42:43], v[92:93], v[46:47], v[42:43]
	v_pk_fma_f32 v[40:41], v[94:95], v[44:45], v[40:41]
	v_pk_fma_f32 v[42:43], v[66:67], s[78:79], v[42:43] op_sel_hi:[1,0,1]
	v_pk_fma_f32 v[40:41], v[64:65], s[78:79], v[40:41] op_sel_hi:[1,0,1]
	v_lshl_add_u64 v[44:45], v[158:159], 2, s[88:89]
	global_store_dwordx4 v[44:45], v[40:43], off
	v_add_u32_e32 v158, 0x18080, v148
	s_nop 0
	v_sub_f32_e32 v41, v77, v100
	v_sub_f32_e32 v40, v76, v100
	v_sub_f32_e32 v43, v79, v100
	v_sub_f32_e32 v42, v78, v100
	v_pk_mul_f32 v[42:43], v[100:101], v[42:43] op_sel:[1,0]
	v_pk_mul_f32 v[40:41], v[100:101], v[40:41] op_sel:[1,0]
	v_pk_fma_f32 v[38:39], v[96:97], v[42:43], v[38:39]
;     template <bool LN, int BJ, int LO, int HI> DI void batch(const f32x4 (&acc)[2][2][4][2], unsigned row0, unsigned col0, const f32x4 (&gv)[2], const f32x4 (&bv)[2]) const {
;         f32x4 r[HI - LO]; float mean[(HI - LO) / 2], rstd[(HI - LO) / 2];
; #pragma unroll
;         for (int i = LO; i < HI; ++i) { const int ai = i >> 3, m = (i >> 1) & 3, n = i & 1; const unsigned row = row0 + ai * HALF + m * 16;
;             if (n == 0) { mean[(i - LO) >> 1] = 0.f; rstd[(i - LO) >> 1] = 1.f;
;                 if (LN) { const float2 st = *(const float2*)(stats + row * 2u); mean[(i - LO) >> 1] = st.x; rstd[(i - LO) >> 1] = st.y; } }
;             r[i - LO] = *(const f32x4*)(src + (row * (unsigned)DM + col0 + BJ * HALF + n * 16)); }
; #pragma unroll
;         for (int i = LO; i < HI; ++i) { const int ai = i >> 3, m = (i >> 1) & 3, n = i & 1; const unsigned row = row0 + ai * HALF + m * 16;
;             *(f32x4*)(Y + (row * (unsigned)DM + col0 + BJ * HALF + n * 16)) = acc[ai][BJ][m][n] + ((r[i - LO] - mean[(i - LO) >> 1]) * rstd[(i - LO) >> 1]) * gv[n] + bv[n]; }
	v_pk_fma_f32 v[36:37], v[98:99], v[40:41], v[36:37]
	v_pk_fma_f32 v[38:39], v[70:71], s[78:79], v[38:39] op_sel_hi:[1,0,1]
	v_pk_fma_f32 v[36:37], v[68:69], s[78:79], v[36:37] op_sel_hi:[1,0,1]
	v_lshl_add_u64 v[40:41], v[158:159], 2, s[88:89]
	global_store_dwordx4 v[40:41], v[36:39], off
	v_add_u32_e32 v158, 0x18090, v148
	s_nop 0
	v_sub_f32_e32 v37, v73, v100
	v_sub_f32_e32 v36, v72, v100
	v_sub_f32_e32 v39, v75, v100
	v_sub_f32_e32 v38, v74, v100
	v_pk_mul_f32 v[38:39], v[100:101], v[38:39] op_sel:[1,0]
	v_pk_mul_f32 v[36:37], v[100:101], v[36:37] op_sel:[1,0]
	v_pk_fma_f32 v[34:35], v[92:93], v[38:39], v[34:35]
	v_pk_fma_f32 v[32:33], v[94:95], v[36:37], v[32:33]
	v_pk_fma_f32 v[34:35], v[66:67], s[78:79], v[34:35] op_sel_hi:[1,0,1]
	v_pk_fma_f32 v[32:33], v[64:65], s[78:79], v[32:33] op_sel_hi:[1,0,1]
	v_lshl_add_u64 v[36:37], v[158:159], 2, s[88:89]
	global_store_dwordx4 v[36:37], v[32:35], off
	v_add_u32_e32 v158, v114, v119
	s_nop 0
	v_lshl_add_u64 v[32:33], v[158:159], 2, s[90:91]
	global_load_dwordx2 v[62:63], v[104:105], off
	global_load_dwordx4 v[54:57], v[32:33], off
	v_add_u32_e32 v158, v114, v118
	v_lshl_add_u64 v[32:33], v[158:159], 2, s[90:91]
	global_load_dwordx4 v[58:61], v[32:33], off
	global_load_dwordx2 v[52:53], v[106:107], off
	v_add_u32_e32 v158, v115, v119
	v_lshl_add_u64 v[32:33], v[158:159], 2, s[90:91]
	global_load_dwordx4 v[72:75], v[32:33], off
	v_add_u32_e32 v158, v115, v118
	v_lshl_add_u64 v[32:33], v[158:159], 2, s[90:91]
	global_load_dwordx4 v[76:79], v[32:33], off
	global_load_dwordx2 v[50:51], v[108:109], off
	v_add_u32_e32 v158, v116, v119
	v_lshl_add_u64 v[32:33], v[158:159], 2, s[90:91]
	global_load_dwordx4 v[44:47], v[32:33], off
	v_add_u32_e32 v158, v116, v118
	v_lshl_add_u64 v[32:33], v[158:159], 2, s[90:91]
	global_load_dwordx4 v[40:43], v[32:33], off
	global_load_dwordx2 v[48:49], v[110:111], off
	v_add_u32_e32 v158, v117, v119
	v_lshl_add_u64 v[32:33], v[158:159], 2, s[90:91]
	global_load_dwordx4 v[36:39], v[32:33], off
	v_add_u32_e32 v158, v117, v118
	v_lshl_add_u64 v[32:33], v[158:159], 2, s[90:91]
	global_load_dwordx4 v[32:35], v[32:33], off
	v_add_u32_e32 v158, 0x40080, v148
	s_waitcnt vmcnt(0)
; #define PG8_WAIT_V(n) asm volatile("s_waitcnt vmcnt(" #n ")" ::: "memory")
; #define PG8_BAR __builtin_amdgcn_s_barrier()
; template <class Epi>
; DI void gemm_phase(LAS unsigned char* lds, const Gemm g, const StaticOrder& S, const Epi& E) {
;     ...
;         E(acc, cur, wr, wc, fr, fq);
;         if (!has_next) break;
; #pragma unroll
;         for (int a = 0; a < 2; ++a)
; #pragma unroll
;             for (int b = 0; b < 2; ++b)
; #pragma unroll
;                 for (int m = 0; m < 4; ++m)
; #pragma unroll
;                     for (int n = 0; n < 2; ++n) acc[a][b][m][n] = (f32x4){0.f, 0.f, 0.f, 0.f};
;         cur = nxt; cA = nA; cB = nB; ++ui;
;     }
;     PG8_WAIT_V(0);
;     if (wr == 0) PG8_BAR;
;     PG8_BAR;
;     template <bool LN, int BJ, int LO, int HI> DI void batch(const f32x4 (&acc)[2][2][4][2], unsigned row0, unsigned col0, const f32x4 (&gv)[2], const f32x4 (&bv)[2]) const {
;         f32x4 r[HI - LO]; float mean[(HI - LO) / 2], rstd[(HI - LO) / 2];
; #pragma unroll
;         for (int i = LO; i < HI; ++i) { const int ai = i >> 3, m = (i >> 1) & 3, n = i & 1; const unsigned row = row0 + ai * HALF + m * 16;
;             if (n == 0) { mean[(i - LO) >> 1] = 0.f; rstd[(i - LO) >> 1] = 1.f;
;                 if (LN) { const float2 st = *(const float2*)(stats + row * 2u); mean[(i - LO) >> 1] = st.x; rstd[(i - LO) >> 1] = st.y; } }
;             r[i - LO] = *(const f32x4*)(src + (row * (unsigned)DM + col0 + BJ * HALF + n * 16)); }
; #pragma unroll
;         for (int i = LO; i < HI; ++i) { const int ai = i >> 3, m = (i >> 1) & 3, n = i & 1; const unsigned row = row0 + ai * HALF + m * 16;
;             *(f32x4*)(Y + (row * (unsigned)DM + col0 + BJ * HALF + n * 16)) = acc[ai][BJ][m][n] + ((r[i - LO] - mean[(i - LO) >> 1]) * rstd[(i - LO) >> 1]) * gv[n] + bv[n]; }
	v_sub_f32_e32 v55, v55, v62
	v_sub_f32_e32 v54, v54, v62
	v_sub_f32_e32 v57, v57, v62
	v_sub_f32_e32 v56, v56, v62
	v_pk_mul_f32 v[56:57], v[62:63], v[56:57] op_sel:[1,0]
	v_pk_mul_f32 v[54:55], v[62:63], v[54:55] op_sel:[1,0]
	v_pk_fma_f32 v[30:31], v[96:97], v[56:57], v[30:31]
	v_pk_fma_f32 v[28:29], v[98:99], v[54:55], v[28:29]
	v_pk_fma_f32 v[30:31], v[70:71], s[78:79], v[30:31] op_sel_hi:[1,0,1]
	v_pk_fma_f32 v[28:29], v[68:69], s[78:79], v[28:29] op_sel_hi:[1,0,1]
	v_lshl_add_u64 v[54:55], v[158:159], 2, s[88:89]
	global_store_dwordx4 v[54:55], v[28:31], off
	v_add_u32_e32 v158, 0x40090, v148
	s_nop 0
	v_sub_f32_e32 v29, v59, v62
	v_sub_f32_e32 v28, v58, v62
	v_sub_f32_e32 v31, v61, v62
	v_sub_f32_e32 v30, v60, v62
	v_pk_mul_f32 v[30:31], v[62:63], v[30:31] op_sel:[1,0]
	v_pk_mul_f32 v[28:29], v[62:63], v[28:29] op_sel:[1,0]
	v_pk_fma_f32 v[26:27], v[92:93], v[30:31], v[26:27]
	v_pk_fma_f32 v[24:25], v[94:95], v[28:29], v[24:25]
	v_pk_fma_f32 v[26:27], v[66:67], s[78:79], v[26:27] op_sel_hi:[1,0,1]
	v_pk_fma_f32 v[24:25], v[64:65], s[78:79], v[24:25] op_sel_hi:[1,0,1]
	v_lshl_add_u64 v[28:29], v[158:159], 2, s[88:89]
	global_store_dwordx4 v[28:29], v[24:27], off
	v_add_u32_e32 v158, 0x48080, v148
	s_nop 0
	v_sub_f32_e32 v25, v73, v52
	v_sub_f32_e32 v24, v72, v52
	v_sub_f32_e32 v27, v75, v52
	v_sub_f32_e32 v26, v74, v52
	v_pk_mul_f32 v[26:27], v[52:53], v[26:27] op_sel:[1,0]
	v_pk_mul_f32 v[24:25], v[52:53], v[24:25] op_sel:[1,0]
	v_pk_fma_f32 v[22:23], v[96:97], v[26:27], v[22:23]
	v_pk_fma_f32 v[20:21], v[98:99], v[24:25], v[20:21]
	v_pk_fma_f32 v[22:23], v[70:71], s[78:79], v[22:23] op_sel_hi:[1,0,1]
	v_pk_fma_f32 v[20:21], v[68:69], s[78:79], v[20:21] op_sel_hi:[1,0,1]
	v_lshl_add_u64 v[24:25], v[158:159], 2, s[88:89]
	global_store_dwordx4 v[24:25], v[20:23], off
	v_add_u32_e32 v158, 0x48090, v148
	s_nop 0
	v_sub_f32_e32 v21, v77, v52
	v_sub_f32_e32 v20, v76, v52
	v_sub_f32_e32 v23, v79, v52
	v_sub_f32_e32 v22, v78, v52
	v_pk_mul_f32 v[22:23], v[52:53], v[22:23] op_sel:[1,0]
	v_pk_mul_f32 v[20:21], v[52:53], v[20:21] op_sel:[1,0]
	v_pk_fma_f32 v[18:19], v[92:93], v[22:23], v[18:19]
	v_pk_fma_f32 v[16:17], v[94:95], v[20:21], v[16:17]
	v_pk_fma_f32 v[18:19], v[66:67], s[78:79], v[18:19] op_sel_hi:[1,0,1]
	v_pk_fma_f32 v[16:17], v[64:65], s[78:79], v[16:17] op_sel_hi:[1,0,1]
	v_lshl_add_u64 v[20:21], v[158:159], 2, s[88:89]
	global_store_dwordx4 v[20:21], v[16:19], off
	v_add_u32_e32 v158, 0x50080, v148
	s_nop 0
	v_sub_f32_e32 v17, v45, v50
	v_sub_f32_e32 v16, v44, v50
	v_sub_f32_e32 v19, v47, v50
	v_sub_f32_e32 v18, v46, v50
	v_pk_mul_f32 v[18:19], v[50:51], v[18:19] op_sel:[1,0]
	v_pk_mul_f32 v[16:17], v[50:51], v[16:17] op_sel:[1,0]
	v_pk_fma_f32 v[14:15], v[96:97], v[18:19], v[14:15]
	v_pk_fma_f32 v[12:13], v[98:99], v[16:17], v[12:13]
	v_pk_fma_f32 v[14:15], v[70:71], s[78:79], v[14:15] op_sel_hi:[1,0,1]
	v_pk_fma_f32 v[12:13], v[68:69], s[78:79], v[12:13] op_sel_hi:[1,0,1]
	v_lshl_add_u64 v[16:17], v[158:159], 2, s[88:89]
	global_store_dwordx4 v[16:17], v[12:15], off
	v_add_u32_e32 v158, 0x50090, v148
	s_nop 0
	v_sub_f32_e32 v13, v41, v50
	v_sub_f32_e32 v12, v40, v50
	v_sub_f32_e32 v15, v43, v50
	v_sub_f32_e32 v14, v42, v50
	v_pk_mul_f32 v[14:15], v[50:51], v[14:15] op_sel:[1,0]
	v_pk_mul_f32 v[12:13], v[50:51], v[12:13] op_sel:[1,0]
	v_pk_fma_f32 v[10:11], v[92:93], v[14:15], v[10:11]
	v_pk_fma_f32 v[8:9], v[94:95], v[12:13], v[8:9]
	v_pk_fma_f32 v[10:11], v[66:67], s[78:79], v[10:11] op_sel_hi:[1,0,1]
	v_pk_fma_f32 v[8:9], v[64:65], s[78:79], v[8:9] op_sel_hi:[1,0,1]
	v_lshl_add_u64 v[12:13], v[158:159], 2, s[88:89]
	global_store_dwordx4 v[12:13], v[8:11], off
	v_add_u32_e32 v158, 0x58080, v148
	s_nop 0
	v_sub_f32_e32 v9, v37, v48
	v_sub_f32_e32 v8, v36, v48
	v_sub_f32_e32 v11, v39, v48
	v_sub_f32_e32 v10, v38, v48
	v_pk_mul_f32 v[10:11], v[48:49], v[10:11] op_sel:[1,0]
	v_pk_mul_f32 v[8:9], v[48:49], v[8:9] op_sel:[1,0]
	v_pk_fma_f32 v[6:7], v[96:97], v[10:11], v[6:7]
	v_pk_fma_f32 v[4:5], v[98:99], v[8:9], v[4:5]
	v_pk_fma_f32 v[6:7], v[70:71], s[78:79], v[6:7] op_sel_hi:[1,0,1]
	v_pk_fma_f32 v[4:5], v[68:69], s[78:79], v[4:5] op_sel_hi:[1,0,1]
	v_lshl_add_u64 v[8:9], v[158:159], 2, s[88:89]
	global_store_dwordx4 v[8:9], v[4:7], off
	v_add_u32_e32 v158, 0x58090, v148
	s_nop 0
	v_sub_f32_e32 v5, v33, v48
	v_sub_f32_e32 v4, v32, v48
	v_sub_f32_e32 v7, v35, v48
	v_sub_f32_e32 v6, v34, v48
	v_pk_mul_f32 v[6:7], v[48:49], v[6:7] op_sel:[1,0]
	v_pk_mul_f32 v[4:5], v[48:49], v[4:5] op_sel:[1,0]
	v_pk_fma_f32 v[2:3], v[92:93], v[6:7], v[2:3]
	v_pk_fma_f32 v[0:1], v[94:95], v[4:5], v[0:1]
	v_pk_fma_f32 v[2:3], v[66:67], s[78:79], v[2:3] op_sel_hi:[1,0,1]
	v_pk_fma_f32 v[0:1], v[64:65], s[78:79], v[0:1] op_sel_hi:[1,0,1]
	v_lshl_add_u64 v[4:5], v[158:159], 2, s[88:89]
	global_store_dwordx4 v[4:5], v[0:3], off
	s_and_b64 vcc, exec, s[6:7]
	s_mov_b32 s2, s37
	s_mov_b32 s3, s38
	s_mov_b64 s[18:19], s[10:11]
	s_mov_b64 s[16:17], s[8:9]
	v_readlane_b32 s33, v255, 39
	s_cbranch_vccz .LBB0_123
	s_waitcnt vmcnt(0)
	s_cmpk_gt_u32 s24, 0xff
	s_cbranch_scc1 .LBB0_138
	s_barrier

; #define PG8_STAGE(bufoff, gbase) do { _Pragma("unroll") for (int _i = 0; _i < 2; ++_i) \
;         __builtin_amdgcn_global_load_lds((const unsigned*)((const char*)(gbase) + voff[_i]), (LAS unsigned*)(lds + (bufoff) + ldsw + _i * 8192), 16, 0, 0); } while (0)
; #define PG8_LDA(dst, b, h) do { _Pragma("unroll") for (int m = 0; m < 4; ++m) _Pragma("unroll") for (int k = 0; k < 2; ++k) dst[m][k] = *(const LAS bf16x8*)(lds + PG8_SA(b, h) + aoff + m * 2048 + k * 1024); } while (0)
; #define PG8_LDB(dst, b, h) do { _Pragma("unroll") for (int n = 0; n < 2; ++n) _Pragma("unroll") for (int k = 0; k < 2; ++k) dst[n][k] = *(const LAS bf16x8*)(lds + PG8_SB(b, h) + boff + n * 2048 + k * 1024); } while (0)
; #define PG8_MMA(ai, bj, At, Bt) do { __builtin_amdgcn_s_setprio(1); _Pragma("unroll") for (int m = 0; m < 4; ++m) _Pragma("unroll") for (int n = 0; n < 2; ++n) _Pragma("unroll") for (int k = 0; k < 2; ++k) \
;         acc[ai][bj][m][n] = __builtin_amdgcn_mfma_f32_16x16x32_bf16(Bt[n][k], At[m][k], acc[ai][bj][m][n], 0, 0, 0); __builtin_amdgcn_s_setprio(0); } while (0)
; #define PG8_WAIT_V(n) asm volatile("s_waitcnt vmcnt(" #n ")" ::: "memory")
; #define PG8_WAIT_L(n) asm volatile("s_waitcnt lgkmcnt(" #n ")" ::: "memory")
; #define PG8_BAR __builtin_amdgcn_s_barrier()
; #define PG8_SCHED __builtin_amdgcn_sched_barrier(0)
; template <class Epi>
; DI void gemm_phase(LAS unsigned char* lds, const Gemm g, const StaticOrder& S, const Epi& E) {
;     ...
;             PG8_LDB(B0, 0, 0); PG8_SCHED; PG8_LDA(At, 0, 0); PG8_STAGE(PG8_SA(1, 1), a1 + hstep);
;             PG8_WAIT_L(8); PG8_BAR; PG8_WAIT_L(0); PG8_MMA(0, 0, At, B0); PG8_BAR; PG8_SCHED;
;             PG8_LDB(B1, 0, 1); PG8_STAGE(PG8_SB(0, 0), b2);
;             PG8_BAR; PG8_WAIT_L(0); PG8_MMA(0, 1, At, B1); PG8_BAR;
;             PG8_LDA(At, 0, 1); PG8_STAGE(PG8_SA(0, 0), a2);
;             PG8_BAR; PG8_WAIT_L(0); PG8_MMA(1, 0, At, B0); PG8_BAR; PG8_SCHED;
;             PG8_STAGE(PG8_SB(0, 1), b2 + hstep);
;             PG8_WAIT_V(6); PG8_BAR; PG8_MMA(1, 1, At, B1); PG8_BAR;
.LBB0_202:
	s_add_u32 s18, s8, 0xfff80080
	s_addc_u32 s19, s9, -1
	s_add_i32 s37, 0, 0x10000
	s_waitcnt lgkmcnt(0)
	ds_read_b128 v[128:131], v187
	ds_read_b128 v[132:135], v187 offset:1024
	ds_read_b128 v[136:139], v187 offset:2048
	ds_read_b128 v[190:193], v187 offset:3072
	s_cmp_eq_u32 s36, 28
	s_cselect_b32 s21, s4, s19
	s_cselect_b32 s20, s5, s18
	s_cselect_b32 s19, s11, s35
	s_cselect_b32 s18, s13, s33
	v_lshl_add_u64 v[140:141], s[8:9], 0, v[150:151]
	s_add_i32 m0, s26, 0xc000
	ds_read_b128 v[194:197], v189
	ds_read_b128 v[198:201], v189 offset:1024
	ds_read_b128 v[202:205], v189 offset:2048
	ds_read_b128 v[206:209], v189 offset:3072
	ds_read_b128 v[210:213], v189 offset:4096
	ds_read_b128 v[214:217], v189 offset:5120
	ds_read_b128 v[226:229], v189 offset:6144
	ds_read_b128 v[230:233], v189 offset:7168
	global_load_lds_dwordx4 v[140:141], off
	v_lshl_add_u64 v[140:141], s[8:9], 0, v[152:153]
	s_add_i32 m0, s26, 0xe000
	s_nop 0
	global_load_lds_dwordx4 v[140:141], off
	s_waitcnt lgkmcnt(8)
	s_setprio 1
	s_barrier
	s_waitcnt lgkmcnt(0)
	v_mfma_f32_16x16x32_bf16 v[124:127], v[128:131], v[194:197], v[124:127]
	v_mfma_f32_16x16x32_bf16 v[120:123], v[136:139], v[194:197], v[120:123]
	v_mfma_f32_16x16x32_bf16 v[108:111], v[128:131], v[202:205], v[108:111]
	v_mfma_f32_16x16x32_bf16 v[104:107], v[136:139], v[202:205], v[104:107]
	v_mfma_f32_16x16x32_bf16 v[92:95], v[128:131], v[210:213], v[92:95]
	v_mfma_f32_16x16x32_bf16 v[88:91], v[136:139], v[210:213], v[88:91]
	v_mfma_f32_16x16x32_bf16 v[76:79], v[128:131], v[226:229], v[76:79]
	v_mfma_f32_16x16x32_bf16 v[72:75], v[136:139], v[226:229], v[72:75]
	v_mfma_f32_16x16x32_bf16 v[124:127], v[132:135], v[198:201], v[124:127]
	v_mfma_f32_16x16x32_bf16 v[120:123], v[190:193], v[198:201], v[120:123]
	v_mfma_f32_16x16x32_bf16 v[108:111], v[132:135], v[206:209], v[108:111]
	v_mfma_f32_16x16x32_bf16 v[104:107], v[190:193], v[206:209], v[104:107]
	v_mfma_f32_16x16x32_bf16 v[92:95], v[132:135], v[214:217], v[92:95]
	v_mfma_f32_16x16x32_bf16 v[88:91], v[190:193], v[214:217], v[88:91]
	v_mfma_f32_16x16x32_bf16 v[76:79], v[132:135], v[230:233], v[76:79]
	s_setprio 0
	v_mfma_f32_16x16x32_bf16 v[72:75], v[190:193], v[230:233], v[72:75]
	s_barrier
	s_add_i32 s40, 0, 0x14000
	s_add_i32 s37, s37, s25
	ds_read_b128 v[234:237], v187 offset:16384
	ds_read_b128 v[238:241], v187 offset:17408
	ds_read_b128 v[242:245], v187 offset:18432
	ds_read_b128 v[246:249], v187 offset:19456
	v_lshl_add_u64 v[140:141], s[18:19], 0, v[144:145]
	s_mov_b32 m0, s37
	v_lshl_add_u64 v[154:155], s[18:19], 0, v[142:143]
	global_load_lds_dwordx4 v[140:141], off
	s_add_i32 m0, s37, 0x2000
	s_nop 0
	global_load_lds_dwordx4 v[154:155], off
	s_waitcnt lgkmcnt(0)
	s_setprio 1
	s_barrier
	v_mfma_f32_16x16x32_bf16 v[116:119], v[234:237], v[194:197], v[116:119]
	v_mfma_f32_16x16x32_bf16 v[112:115], v[242:245], v[194:197], v[112:115]
	v_mfma_f32_16x16x32_bf16 v[100:103], v[234:237], v[202:205], v[100:103]
	v_mfma_f32_16x16x32_bf16 v[96:99], v[242:245], v[202:205], v[96:99]
	v_mfma_f32_16x16x32_bf16 v[84:87], v[234:237], v[210:213], v[84:87]
	v_mfma_f32_16x16x32_bf16 v[80:83], v[242:245], v[210:213], v[80:83]
	v_mfma_f32_16x16x32_bf16 v[68:71], v[234:237], v[226:229], v[68:71]
	v_mfma_f32_16x16x32_bf16 v[64:67], v[242:245], v[226:229], v[64:67]
	v_mfma_f32_16x16x32_bf16 v[116:119], v[238:241], v[198:201], v[116:119]
	s_mov_b32 m0, s26
	v_mfma_f32_16x16x32_bf16 v[112:115], v[246:249], v[198:201], v[112:115]
	v_lshl_add_u64 v[218:219], s[20:21], 0, v[144:145]
	v_mfma_f32_16x16x32_bf16 v[100:103], v[238:241], v[206:209], v[100:103]
	v_mfma_f32_16x16x32_bf16 v[96:99], v[246:249], v[206:209], v[96:99]
	v_mfma_f32_16x16x32_bf16 v[84:87], v[238:241], v[214:217], v[84:87]
	v_mfma_f32_16x16x32_bf16 v[80:83], v[246:249], v[214:217], v[80:83]
	v_mfma_f32_16x16x32_bf16 v[68:71], v[238:241], v[230:233], v[68:71]
	s_setprio 0
	v_mfma_f32_16x16x32_bf16 v[64:67], v[246:249], v[230:233], v[64:67]
	s_barrier
	ds_read_b128 v[194:197], v189 offset:16384
	ds_read_b128 v[198:201], v189 offset:17408
	ds_read_b128 v[202:205], v189 offset:18432
	ds_read_b128 v[206:209], v189 offset:19456
	ds_read_b128 v[210:213], v189 offset:20480
	ds_read_b128 v[214:217], v189 offset:21504
	ds_read_b128 v[226:229], v189 offset:22528
	ds_read_b128 v[230:233], v189 offset:23552
	global_load_lds_dwordx4 v[218:219], off
	v_lshl_add_u64 v[250:251], s[20:21], 0, v[142:143]
	s_mov_b32 m0, s27
	s_nop 0
	global_load_lds_dwordx4 v[250:251], off
	s_waitcnt lgkmcnt(0)
	s_setprio 1
	s_barrier
	v_mfma_f32_16x16x32_bf16 v[60:63], v[128:131], v[194:197], v[60:63]
	v_mfma_f32_16x16x32_bf16 v[56:59], v[136:139], v[194:197], v[56:59]
	v_mfma_f32_16x16x32_bf16 v[44:47], v[128:131], v[202:205], v[44:47]
	v_mfma_f32_16x16x32_bf16 v[40:43], v[136:139], v[202:205], v[40:43]
	v_mfma_f32_16x16x32_bf16 v[28:31], v[128:131], v[210:213], v[28:31]
	v_mfma_f32_16x16x32_bf16 v[24:27], v[136:139], v[210:213], v[24:27]
	v_mfma_f32_16x16x32_bf16 v[12:15], v[128:131], v[226:229], v[12:15]
	v_mfma_f32_16x16x32_bf16 v[8:11], v[136:139], v[226:229], v[8:11]
	v_mfma_f32_16x16x32_bf16 v[60:63], v[132:135], v[198:201], v[60:63]
	v_mfma_f32_16x16x32_bf16 v[56:59], v[190:193], v[198:201], v[56:59]
	v_mfma_f32_16x16x32_bf16 v[44:47], v[132:135], v[206:209], v[44:47]
	v_mfma_f32_16x16x32_bf16 v[40:43], v[190:193], v[206:209], v[40:43]
	v_mfma_f32_16x16x32_bf16 v[28:31], v[132:135], v[214:217], v[28:31]
	v_mfma_f32_16x16x32_bf16 v[24:27], v[190:193], v[214:217], v[24:27]
	v_mfma_f32_16x16x32_bf16 v[12:15], v[132:135], v[230:233], v[12:15]
	s_setprio 0
	v_mfma_f32_16x16x32_bf16 v[8:11], v[190:193], v[230:233], v[8:11]
	s_barrier
; #define PG8_STAGE(bufoff, gbase) do { _Pragma("unroll") for (int _i = 0; _i < 2; ++_i) \
;         __builtin_amdgcn_global_load_lds((const unsigned*)((const char*)(gbase) + voff[_i]), (LAS unsigned*)(lds + (bufoff) + ldsw + _i * 8192), 16, 0, 0); } while (0)
; #define PG8_LDA(dst, b, h) do { _Pragma("unroll") for (int m = 0; m < 4; ++m) _Pragma("unroll") for (int k = 0; k < 2; ++k) dst[m][k] = *(const LAS bf16x8*)(lds + PG8_SA(b, h) + aoff + m * 2048 + k * 1024); } while (0)
; #define PG8_LDB(dst, b, h) do { _Pragma("unroll") for (int n = 0; n < 2; ++n) _Pragma("unroll") for (int k = 0; k < 2; ++k) dst[n][k] = *(const LAS bf16x8*)(lds + PG8_SB(b, h) + boff + n * 2048 + k * 1024); } while (0)
; #define PG8_MMA(ai, bj, At, Bt) do { __builtin_amdgcn_s_setprio(1); _Pragma("unroll") for (int m = 0; m < 4; ++m) _Pragma("unroll") for (int n = 0; n < 2; ++n) _Pragma("unroll") for (int k = 0; k < 2; ++k) \
;         acc[ai][bj][m][n] = __builtin_amdgcn_mfma_f32_16x16x32_bf16(Bt[n][k], At[m][k], acc[ai][bj][m][n], 0, 0, 0); __builtin_amdgcn_s_setprio(0); } while (0)
; #define PG8_WAIT_V(n) asm volatile("s_waitcnt vmcnt(" #n ")" ::: "memory")
; #define PG8_WAIT_L(n) asm volatile("s_waitcnt lgkmcnt(" #n ")" ::: "memory")
; #define PG8_BAR __builtin_amdgcn_s_barrier()
; #define PG8_SCHED __builtin_amdgcn_sched_barrier(0)
; template <class Epi>
; DI void gemm_phase(LAS unsigned char* lds, const Gemm g, const StaticOrder& S, const Epi& E) {
;     ...
;             PG8_STAGE(PG8_SB(0, 1), b2 + hstep);
;             PG8_WAIT_V(6); PG8_BAR; PG8_MMA(1, 1, At, B1); PG8_BAR;
;             PG8_LDB(B0, 1, 0); PG8_SCHED; PG8_LDA(At, 1, 0); PG8_STAGE(PG8_SA(0, 1), a2 + hstep);
;             PG8_WAIT_L(8); PG8_BAR; PG8_WAIT_L(0); PG8_MMA(0, 0, At, B0); PG8_BAR; PG8_SCHED;
;             PG8_LDB(B1, 1, 1); PG8_STAGE(PG8_SB(1, 0), b3);
;             PG8_BAR; PG8_WAIT_L(0); PG8_MMA(0, 1, At, B1); PG8_BAR;
	s_add_u32 s38, s18, 0x80000
	s_addc_u32 s39, s19, 0
	s_add_i32 s37, s40, s25
	v_lshl_add_u64 v[128:129], s[38:39], 0, v[144:145]
	s_mov_b32 m0, s37
	s_nop 0
	global_load_lds_dwordx4 v[128:129], off
	v_lshl_add_u64 v[128:129], s[38:39], 0, v[142:143]
	s_add_i32 m0, s37, 0x2000
	s_nop 0
	global_load_lds_dwordx4 v[128:129], off
	s_waitcnt vmcnt(6)
	s_setprio 1
	s_barrier
	v_mfma_f32_16x16x32_bf16 v[52:55], v[234:237], v[194:197], v[52:55]
	v_mfma_f32_16x16x32_bf16 v[48:51], v[242:245], v[194:197], v[48:51]
	v_mfma_f32_16x16x32_bf16 v[36:39], v[234:237], v[202:205], v[36:39]
	v_mfma_f32_16x16x32_bf16 v[32:35], v[242:245], v[202:205], v[32:35]
	v_mfma_f32_16x16x32_bf16 v[20:23], v[234:237], v[210:213], v[20:23]
	v_mfma_f32_16x16x32_bf16 v[16:19], v[242:245], v[210:213], v[16:19]
	v_mfma_f32_16x16x32_bf16 v[4:7], v[234:237], v[226:229], v[4:7]
	v_mfma_f32_16x16x32_bf16 v[0:3], v[242:245], v[226:229], v[0:3]
	v_mfma_f32_16x16x32_bf16 v[52:55], v[238:241], v[198:201], v[52:55]
	s_add_i32 s37, 0, 0x18000
	v_mfma_f32_16x16x32_bf16 v[48:51], v[246:249], v[198:201], v[48:51]
	v_mfma_f32_16x16x32_bf16 v[36:39], v[238:241], v[206:209], v[36:39]
	v_mfma_f32_16x16x32_bf16 v[32:35], v[246:249], v[206:209], v[32:35]
	v_mfma_f32_16x16x32_bf16 v[20:23], v[238:241], v[214:217], v[20:23]
	v_mfma_f32_16x16x32_bf16 v[16:19], v[246:249], v[214:217], v[16:19]
	v_mfma_f32_16x16x32_bf16 v[4:7], v[238:241], v[230:233], v[4:7]
	s_setprio 0
	v_mfma_f32_16x16x32_bf16 v[0:3], v[246:249], v[230:233], v[0:3]
	s_barrier
	ds_read_b128 v[128:131], v187 offset:32768
	ds_read_b128 v[132:135], v187 offset:33792
	ds_read_b128 v[136:139], v187 offset:34816
	ds_read_b128 v[190:193], v187 offset:35840
	s_add_u32 s20, s20, 0x80000
	s_addc_u32 s21, s21, 0
	s_mov_b32 m0, s28
	v_lshl_add_u64 v[234:235], s[20:21], 0, v[144:145]
	ds_read_b128 v[194:197], v189 offset:32768
	ds_read_b128 v[198:201], v189 offset:33792
	ds_read_b128 v[202:205], v189 offset:34816
	ds_read_b128 v[206:209], v189 offset:35840
	ds_read_b128 v[210:213], v189 offset:36864
	ds_read_b128 v[214:217], v189 offset:37888
	ds_read_b128 v[226:229], v189 offset:38912
	ds_read_b128 v[230:233], v189 offset:39936
	global_load_lds_dwordx4 v[234:235], off
	v_lshl_add_u64 v[234:235], s[20:21], 0, v[142:143]
	s_mov_b32 m0, s29
	s_nop 0
	global_load_lds_dwordx4 v[234:235], off
	s_waitcnt lgkmcnt(8)
	s_setprio 1
	s_barrier
	s_waitcnt lgkmcnt(0)
	v_mfma_f32_16x16x32_bf16 v[124:127], v[128:131], v[194:197], v[124:127]
	v_mfma_f32_16x16x32_bf16 v[120:123], v[136:139], v[194:197], v[120:123]
	v_mfma_f32_16x16x32_bf16 v[108:111], v[128:131], v[202:205], v[108:111]
	v_mfma_f32_16x16x32_bf16 v[104:107], v[136:139], v[202:205], v[104:107]
	v_mfma_f32_16x16x32_bf16 v[92:95], v[128:131], v[210:213], v[92:95]
	v_mfma_f32_16x16x32_bf16 v[88:91], v[136:139], v[210:213], v[88:91]
	v_mfma_f32_16x16x32_bf16 v[76:79], v[128:131], v[226:229], v[76:79]
	v_mfma_f32_16x16x32_bf16 v[72:75], v[136:139], v[226:229], v[72:75]
	v_mfma_f32_16x16x32_bf16 v[124:127], v[132:135], v[198:201], v[124:127]
	v_mfma_f32_16x16x32_bf16 v[120:123], v[190:193], v[198:201], v[120:123]
	v_mfma_f32_16x16x32_bf16 v[108:111], v[132:135], v[206:209], v[108:111]
	v_mfma_f32_16x16x32_bf16 v[104:107], v[190:193], v[206:209], v[104:107]
	v_mfma_f32_16x16x32_bf16 v[92:95], v[132:135], v[214:217], v[92:95]
	v_mfma_f32_16x16x32_bf16 v[88:91], v[190:193], v[214:217], v[88:91]
	v_mfma_f32_16x16x32_bf16 v[76:79], v[132:135], v[230:233], v[76:79]
	s_setprio 0
	v_mfma_f32_16x16x32_bf16 v[72:75], v[190:193], v[230:233], v[72:75]
	s_barrier
	s_add_i32 s20, 0, 0x1c000
	s_add_i32 s21, s37, s25
	v_lshl_add_u64 v[140:141], v[140:141], 0, s[94:95]
	s_mov_b32 m0, s21
	ds_read_b128 v[234:237], v187 offset:49152
	ds_read_b128 v[238:241], v187 offset:50176
	ds_read_b128 v[242:245], v187 offset:51200
	ds_read_b128 v[246:249], v187 offset:52224
	global_load_lds_dwordx4 v[140:141], off
	v_lshl_add_u64 v[140:141], v[154:155], 0, s[94:95]
	s_add_i32 m0, s21, 0x2000
	s_nop 0
	global_load_lds_dwordx4 v[140:141], off
	s_waitcnt lgkmcnt(0)
	s_setprio 1
	s_barrier
; #define PG8_STAGE(bufoff, gbase) do { _Pragma("unroll") for (int _i = 0; _i < 2; ++_i) \
;         __builtin_amdgcn_global_load_lds((const unsigned*)((const char*)(gbase) + voff[_i]), (LAS unsigned*)(lds + (bufoff) + ldsw + _i * 8192), 16, 0, 0); } while (0)
; #define PG8_LDA(dst, b, h) do { _Pragma("unroll") for (int m = 0; m < 4; ++m) _Pragma("unroll") for (int k = 0; k < 2; ++k) dst[m][k] = *(const LAS bf16x8*)(lds + PG8_SA(b, h) + aoff + m * 2048 + k * 1024); } while (0)
; #define PG8_MMA(ai, bj, At, Bt) do { __builtin_amdgcn_s_setprio(1); _Pragma("unroll") for (int m = 0; m < 4; ++m) _Pragma("unroll") for (int n = 0; n < 2; ++n) _Pragma("unroll") for (int k = 0; k < 2; ++k) \
;         acc[ai][bj][m][n] = __builtin_amdgcn_mfma_f32_16x16x32_bf16(Bt[n][k], At[m][k], acc[ai][bj][m][n], 0, 0, 0); __builtin_amdgcn_s_setprio(0); } while (0)
; #define PG8_WAIT_V(n) asm volatile("s_waitcnt vmcnt(" #n ")" ::: "memory")
; #define PG8_WAIT_L(n) asm volatile("s_waitcnt lgkmcnt(" #n ")" ::: "memory")
; #define PG8_BAR __builtin_amdgcn_s_barrier()
; #define PG8_SCHED __builtin_amdgcn_sched_barrier(0)
; template <class Epi>
; DI void gemm_phase(LAS unsigned char* lds, const Gemm g, const StaticOrder& S, const Epi& E) {
;     ...
;             PG8_BAR; PG8_WAIT_L(0); PG8_MMA(0, 1, At, B1); PG8_BAR;
;             PG8_LDA(At, 1, 1); PG8_STAGE(PG8_SA(1, 0), a3);
;             PG8_BAR; PG8_WAIT_L(0); PG8_MMA(1, 0, At, B0); PG8_BAR; PG8_SCHED;
;             PG8_STAGE(PG8_SB(1, 1), b3 + hstep);
;             PG8_WAIT_V(6); PG8_BAR; PG8_MMA(1, 1, At, B1); PG8_BAR;
;     DI void operator()(const f32x4 (&acc)[2][2][4][2], const Unit& u, int wr, int wc, int fr, int fq) const {
;         const int row0 = u.pm * BM + wr * 64 + fr, col0 = u.pn * BM + wc * 16 + 4 * fq;
;         const bool rot = u.pn < 18;
; #pragma unroll
;         for (int ai = 0; ai < 2; ++ai)
; #pragma unroll
;             for (int m = 0; m < 4; ++m) { const int row = row0 + ai * HALF + m * 16; u16* rowp = O + (size_t)row * NQKV_DIL + col0;
;                 f32x4 c4 = (f32x4){1.f, 1.f, 1.f, 1.f}, s4 = (f32x4){0.f, 0.f, 0.f, 0.f};
;                 if (rot) { const int pos = row & (SEQ - 1); c4 = *(const f32x4*)(cs + pos * 64 + wc * 16 + 4 * fq); s4 = *(const f32x4*)(sn + pos * 64 + wc * 16 + 4 * fq); }
	v_mfma_f32_16x16x32_bf16 v[116:119], v[234:237], v[194:197], v[116:119]
	v_mfma_f32_16x16x32_bf16 v[112:115], v[242:245], v[194:197], v[112:115]
	v_mfma_f32_16x16x32_bf16 v[100:103], v[234:237], v[202:205], v[100:103]
	v_mfma_f32_16x16x32_bf16 v[96:99], v[242:245], v[202:205], v[96:99]
	v_mfma_f32_16x16x32_bf16 v[84:87], v[234:237], v[210:213], v[84:87]
	v_mfma_f32_16x16x32_bf16 v[80:83], v[242:245], v[210:213], v[80:83]
	v_mfma_f32_16x16x32_bf16 v[68:71], v[234:237], v[226:229], v[68:71]
	v_mfma_f32_16x16x32_bf16 v[64:67], v[242:245], v[226:229], v[64:67]
	v_mfma_f32_16x16x32_bf16 v[116:119], v[238:241], v[198:201], v[116:119]
	s_mov_b32 m0, s30
	v_mfma_f32_16x16x32_bf16 v[112:115], v[246:249], v[198:201], v[112:115]
	v_lshl_add_u64 v[140:141], v[218:219], 0, s[94:95]
	v_mfma_f32_16x16x32_bf16 v[100:103], v[238:241], v[206:209], v[100:103]
	v_mfma_f32_16x16x32_bf16 v[96:99], v[246:249], v[206:209], v[96:99]
	v_mfma_f32_16x16x32_bf16 v[84:87], v[238:241], v[214:217], v[84:87]
	v_mfma_f32_16x16x32_bf16 v[80:83], v[246:249], v[214:217], v[80:83]
	v_mfma_f32_16x16x32_bf16 v[68:71], v[238:241], v[230:233], v[68:71]
	s_setprio 0
	v_mfma_f32_16x16x32_bf16 v[64:67], v[246:249], v[230:233], v[64:67]
	s_barrier
	ds_read_b128 v[194:197], v189 offset:49152
	ds_read_b128 v[198:201], v189 offset:50176
	ds_read_b128 v[202:205], v189 offset:51200
	ds_read_b128 v[206:209], v189 offset:52224
	ds_read_b128 v[210:213], v189 offset:53248
	ds_read_b128 v[214:217], v189 offset:54272
	ds_read_b128 v[226:229], v189 offset:55296
	ds_read_b128 v[230:233], v189 offset:56320
	global_load_lds_dwordx4 v[140:141], off
	v_lshl_add_u64 v[140:141], v[250:251], 0, s[94:95]
	s_mov_b32 m0, s31
	s_nop 0
	global_load_lds_dwordx4 v[140:141], off
	s_waitcnt lgkmcnt(0)
	s_setprio 1
	s_barrier
	v_mfma_f32_16x16x32_bf16 v[60:63], v[128:131], v[194:197], v[60:63]
	v_mfma_f32_16x16x32_bf16 v[56:59], v[136:139], v[194:197], v[56:59]
	v_mfma_f32_16x16x32_bf16 v[44:47], v[128:131], v[202:205], v[44:47]
	v_mfma_f32_16x16x32_bf16 v[40:43], v[136:139], v[202:205], v[40:43]
	v_mfma_f32_16x16x32_bf16 v[28:31], v[128:131], v[210:213], v[28:31]
	v_mfma_f32_16x16x32_bf16 v[24:27], v[136:139], v[210:213], v[24:27]
	v_mfma_f32_16x16x32_bf16 v[12:15], v[128:131], v[226:229], v[12:15]
	v_mfma_f32_16x16x32_bf16 v[8:11], v[136:139], v[226:229], v[8:11]
	v_mfma_f32_16x16x32_bf16 v[60:63], v[132:135], v[198:201], v[60:63]
	v_mfma_f32_16x16x32_bf16 v[56:59], v[190:193], v[198:201], v[56:59]
	v_mfma_f32_16x16x32_bf16 v[44:47], v[132:135], v[206:209], v[44:47]
	v_mfma_f32_16x16x32_bf16 v[40:43], v[190:193], v[206:209], v[40:43]
	v_mfma_f32_16x16x32_bf16 v[28:31], v[132:135], v[214:217], v[28:31]
	v_mfma_f32_16x16x32_bf16 v[24:27], v[190:193], v[214:217], v[24:27]
	v_mfma_f32_16x16x32_bf16 v[12:15], v[132:135], v[230:233], v[12:15]
	s_setprio 0
	v_mfma_f32_16x16x32_bf16 v[8:11], v[190:193], v[230:233], v[8:11]
	s_barrier
	s_add_u32 s18, s18, 0x80080
	s_addc_u32 s19, s19, 0
	s_add_i32 s20, s20, s25
	v_lshl_add_u64 v[128:129], s[18:19], 0, v[144:145]
	s_mov_b32 m0, s20
	s_nop 0
	global_load_lds_dwordx4 v[128:129], off
	v_lshl_add_u64 v[128:129], s[18:19], 0, v[142:143]
	s_add_i32 m0, s20, 0x2000
	s_nop 0
	global_load_lds_dwordx4 v[128:129], off
	s_waitcnt vmcnt(6)
	s_setprio 1
	s_barrier
	v_mfma_f32_16x16x32_bf16 v[52:55], v[234:237], v[194:197], v[52:55]
	v_mfma_f32_16x16x32_bf16 v[48:51], v[242:245], v[194:197], v[48:51]
	v_mfma_f32_16x16x32_bf16 v[36:39], v[234:237], v[202:205], v[36:39]
	v_mfma_f32_16x16x32_bf16 v[32:35], v[242:245], v[202:205], v[32:35]
	v_mfma_f32_16x16x32_bf16 v[20:23], v[234:237], v[210:213], v[20:23]
	v_mfma_f32_16x16x32_bf16 v[16:19], v[242:245], v[210:213], v[16:19]
	v_mfma_f32_16x16x32_bf16 v[4:7], v[234:237], v[226:229], v[4:7]
	v_mfma_f32_16x16x32_bf16 v[0:3], v[242:245], v[226:229], v[0:3]
	v_mfma_f32_16x16x32_bf16 v[52:55], v[238:241], v[198:201], v[52:55]
	s_add_i32 s36, s36, 2
	v_mfma_f32_16x16x32_bf16 v[48:51], v[246:249], v[198:201], v[48:51]
	s_add_u32 s8, s8, 0x100
	v_mfma_f32_16x16x32_bf16 v[36:39], v[238:241], v[206:209], v[36:39]
	s_addc_u32 s9, s9, 0
	v_mfma_f32_16x16x32_bf16 v[32:35], v[246:249], v[206:209], v[32:35]
	s_add_u32 s33, s33, 0x100
	v_mfma_f32_16x16x32_bf16 v[20:23], v[238:241], v[214:217], v[20:23]
	s_addc_u32 s35, s35, 0
	v_mfma_f32_16x16x32_bf16 v[16:19], v[246:249], v[214:217], v[16:19]
	s_cmp_gt_u32 s36, 29
	v_mfma_f32_16x16x32_bf16 v[4:7], v[238:241], v[230:233], v[4:7]
	s_setprio 0
	v_mfma_f32_16x16x32_bf16 v[0:3], v[246:249], v[230:233], v[0:3]
	s_barrier
	s_cbranch_scc0 .LBB0_202
	s_cmp_lt_i32 s2, 18
	v_lshl_add_u32 v190, s3, 8, v186
	v_mov_b32_e32 v128, 1.0
	v_mov_b32_e32 v132, 0
	s_cselect_b64 s[18:19], -1, 0
	s_cmp_gt_i32 s2, 17
	v_mov_b32_e32 v134, 0
	v_mov_b32_e32 v135, 0
	v_mov_b32_e32 v136, 0
	v_mov_b32_e32 v137, 0
	v_mov_b32_e32 v138, 1.0
	v_mov_b32_e32 v139, 1.0
	v_mov_b32_e32 v140, 1.0
	v_mov_b32_e32 v141, 1.0
	s_cbranch_scc1 .LBB0_205
	v_lshlrev_b32_e32 v129, 8, v190
	v_and_b32_e32 v158, 0xfcf00, v129
	v_lshl_add_u64 v[130:131], v[146:147], 0, v[158:159]
	v_lshl_add_u64 v[134:135], v[148:149], 0, v[158:159]
	global_load_dwordx4 v[138:141], v[130:131], off
	s_nop 0
	global_load_dwordx4 v[134:137], v[134:135], off

; #define PG8_STAGE(bufoff, gbase) do { _Pragma("unroll") for (int _i = 0; _i < 2; ++_i) \
;         __builtin_amdgcn_global_load_lds((const unsigned*)((const char*)(gbase) + voff[_i]), (LAS unsigned*)(lds + (bufoff) + ldsw + _i * 8192), 16, 0, 0); } while (0)
; #define PG8_LDA(dst, b, h) do { _Pragma("unroll") for (int m = 0; m < 4; ++m) _Pragma("unroll") for (int k = 0; k < 2; ++k) dst[m][k] = *(const LAS bf16x8*)(lds + PG8_SA(b, h) + aoff + m * 2048 + k * 1024); } while (0)
; #define PG8_LDB(dst, b, h) do { _Pragma("unroll") for (int n = 0; n < 2; ++n) _Pragma("unroll") for (int k = 0; k < 2; ++k) dst[n][k] = *(const LAS bf16x8*)(lds + PG8_SB(b, h) + boff + n * 2048 + k * 1024); } while (0)
; #define PG8_MMA(ai, bj, At, Bt) do { __builtin_amdgcn_s_setprio(1); _Pragma("unroll") for (int m = 0; m < 4; ++m) _Pragma("unroll") for (int n = 0; n < 2; ++n) _Pragma("unroll") for (int k = 0; k < 2; ++k) \
;         acc[ai][bj][m][n] = __builtin_amdgcn_mfma_f32_16x16x32_bf16(Bt[n][k], At[m][k], acc[ai][bj][m][n], 0, 0, 0); __builtin_amdgcn_s_setprio(0); } while (0)
; #define PG8_WAIT_V(n) asm volatile("s_waitcnt vmcnt(" #n ")" ::: "memory")
; #define PG8_WAIT_L(n) asm volatile("s_waitcnt lgkmcnt(" #n ")" ::: "memory")
; #define PG8_BAR __builtin_amdgcn_s_barrier()
; #define PG8_SCHED __builtin_amdgcn_sched_barrier(0)
; template <class Epi>
; DI void gemm_phase(LAS unsigned char* lds, const Gemm g, const StaticOrder& S, const Epi& E) {
;     ...
;             PG8_LDB(B0, 0, 0); PG8_SCHED; PG8_LDA(At, 0, 0); PG8_STAGE(PG8_SA(1, 1), a1 + hstep);
;             PG8_WAIT_L(8); PG8_BAR; PG8_WAIT_L(0); PG8_MMA(0, 0, At, B0); PG8_BAR; PG8_SCHED;
;             PG8_LDB(B1, 0, 1); PG8_STAGE(PG8_SB(0, 0), b2);
;             PG8_BAR; PG8_WAIT_L(0); PG8_MMA(0, 1, At, B1); PG8_BAR;
;             PG8_LDA(At, 0, 1); PG8_STAGE(PG8_SA(0, 0), a2);
;             PG8_BAR; PG8_WAIT_L(0); PG8_MMA(1, 0, At, B0); PG8_BAR; PG8_SCHED;
;             PG8_STAGE(PG8_SB(0, 1), b2 + hstep);
;             PG8_WAIT_V(6); PG8_BAR; PG8_MMA(1, 1, At, B1); PG8_BAR;
.LBB0_231:
	s_add_u32 s18, s16, 0xfff80080
	s_addc_u32 s19, s17, -1
	s_add_i32 s37, 0, 0x10000
	ds_read_b128 v[138:141], v135
	ds_read_b128 v[142:145], v135 offset:1024
	ds_read_b128 v[146:149], v135 offset:2048
	ds_read_b128 v[150:153], v135 offset:3072
	s_cmp_eq_u32 s36, 28
	s_cselect_b32 s21, s4, s19
	s_cselect_b32 s20, s5, s18
	s_cselect_b32 s19, s9, s35
	s_cselect_b32 s18, s11, s34
	v_lshl_add_u64 v[154:155], s[16:17], 0, v[130:131]
	s_add_i32 m0, s24, 0xc000
	ds_read_b128 v[186:189], v137
	ds_read_b128 v[190:193], v137 offset:1024
	ds_read_b128 v[194:197], v137 offset:2048
	ds_read_b128 v[198:201], v137 offset:3072
	ds_read_b128 v[202:205], v137 offset:4096
	ds_read_b128 v[206:209], v137 offset:5120
	ds_read_b128 v[210:213], v137 offset:6144
	ds_read_b128 v[214:217], v137 offset:7168
	global_load_lds_dwordx4 v[154:155], off
	v_lshl_add_u64 v[154:155], s[16:17], 0, v[132:133]
	s_add_i32 m0, s24, 0xe000
	s_nop 0
	global_load_lds_dwordx4 v[154:155], off
	s_waitcnt lgkmcnt(8)
	s_setprio 1
	s_barrier
	s_waitcnt lgkmcnt(0)
	v_mfma_f32_16x16x32_bf16 v[124:127], v[138:141], v[186:189], v[124:127]
	v_mfma_f32_16x16x32_bf16 v[120:123], v[146:149], v[186:189], v[120:123]
	v_mfma_f32_16x16x32_bf16 v[116:119], v[138:141], v[194:197], v[116:119]
	v_mfma_f32_16x16x32_bf16 v[112:115], v[146:149], v[194:197], v[112:115]
	v_mfma_f32_16x16x32_bf16 v[100:103], v[138:141], v[202:205], v[100:103]
	v_mfma_f32_16x16x32_bf16 v[96:99], v[146:149], v[202:205], v[96:99]
	v_mfma_f32_16x16x32_bf16 v[84:87], v[138:141], v[210:213], v[84:87]
	v_mfma_f32_16x16x32_bf16 v[80:83], v[146:149], v[210:213], v[80:83]
	v_mfma_f32_16x16x32_bf16 v[124:127], v[142:145], v[190:193], v[124:127]
	v_mfma_f32_16x16x32_bf16 v[120:123], v[150:153], v[190:193], v[120:123]
	v_mfma_f32_16x16x32_bf16 v[116:119], v[142:145], v[198:201], v[116:119]
	v_mfma_f32_16x16x32_bf16 v[112:115], v[150:153], v[198:201], v[112:115]
	v_mfma_f32_16x16x32_bf16 v[100:103], v[142:145], v[206:209], v[100:103]
	v_mfma_f32_16x16x32_bf16 v[96:99], v[150:153], v[206:209], v[96:99]
	v_mfma_f32_16x16x32_bf16 v[84:87], v[142:145], v[214:217], v[84:87]
	s_setprio 0
	v_mfma_f32_16x16x32_bf16 v[80:83], v[150:153], v[214:217], v[80:83]
	s_barrier
	s_add_i32 s40, 0, 0x14000
	s_add_i32 s37, s37, s23
	ds_read_b128 v[226:229], v135 offset:16384
	ds_read_b128 v[230:233], v135 offset:17408
	ds_read_b128 v[234:237], v135 offset:18432
	ds_read_b128 v[238:241], v135 offset:19456
	v_lshl_add_u64 v[154:155], s[18:19], 0, v[158:159]
	s_mov_b32 m0, s37
	v_lshl_add_u64 v[218:219], s[18:19], 0, v[128:129]
	global_load_lds_dwordx4 v[154:155], off
	s_add_i32 m0, s37, 0x2000
	s_nop 0
	global_load_lds_dwordx4 v[218:219], off
	s_waitcnt lgkmcnt(0)
	s_setprio 1
	s_barrier
	v_mfma_f32_16x16x32_bf16 v[108:111], v[226:229], v[186:189], v[108:111]
	v_mfma_f32_16x16x32_bf16 v[104:107], v[234:237], v[186:189], v[104:107]
	v_mfma_f32_16x16x32_bf16 v[92:95], v[226:229], v[194:197], v[92:95]
	v_mfma_f32_16x16x32_bf16 v[88:91], v[234:237], v[194:197], v[88:91]
	v_mfma_f32_16x16x32_bf16 v[76:79], v[226:229], v[202:205], v[76:79]
	v_mfma_f32_16x16x32_bf16 v[72:75], v[234:237], v[202:205], v[72:75]
	v_mfma_f32_16x16x32_bf16 v[68:71], v[226:229], v[210:213], v[68:71]
	v_mfma_f32_16x16x32_bf16 v[64:67], v[234:237], v[210:213], v[64:67]
	v_mfma_f32_16x16x32_bf16 v[108:111], v[230:233], v[190:193], v[108:111]
	s_mov_b32 m0, s24
	v_mfma_f32_16x16x32_bf16 v[104:107], v[238:241], v[190:193], v[104:107]
	v_lshl_add_u64 v[242:243], s[20:21], 0, v[158:159]
	v_mfma_f32_16x16x32_bf16 v[92:95], v[230:233], v[198:201], v[92:95]
	v_mfma_f32_16x16x32_bf16 v[88:91], v[238:241], v[198:201], v[88:91]
	v_mfma_f32_16x16x32_bf16 v[76:79], v[230:233], v[206:209], v[76:79]
	v_mfma_f32_16x16x32_bf16 v[72:75], v[238:241], v[206:209], v[72:75]
	v_mfma_f32_16x16x32_bf16 v[68:71], v[230:233], v[214:217], v[68:71]
	s_setprio 0
	v_mfma_f32_16x16x32_bf16 v[64:67], v[238:241], v[214:217], v[64:67]
	s_barrier
	ds_read_b128 v[186:189], v137 offset:16384
	ds_read_b128 v[190:193], v137 offset:17408
	ds_read_b128 v[194:197], v137 offset:18432
	ds_read_b128 v[198:201], v137 offset:19456
	ds_read_b128 v[202:205], v137 offset:20480
	ds_read_b128 v[206:209], v137 offset:21504
	ds_read_b128 v[210:213], v137 offset:22528
	ds_read_b128 v[214:217], v137 offset:23552
	global_load_lds_dwordx4 v[242:243], off
	v_lshl_add_u64 v[244:245], s[20:21], 0, v[128:129]
	s_mov_b32 m0, s25
	s_nop 0
	global_load_lds_dwordx4 v[244:245], off
	s_waitcnt lgkmcnt(0)
	s_setprio 1
	s_barrier
	v_mfma_f32_16x16x32_bf16 v[60:63], v[138:141], v[186:189], v[60:63]
	v_mfma_f32_16x16x32_bf16 v[56:59], v[146:149], v[186:189], v[56:59]
	v_mfma_f32_16x16x32_bf16 v[52:55], v[138:141], v[194:197], v[52:55]
	v_mfma_f32_16x16x32_bf16 v[48:51], v[146:149], v[194:197], v[48:51]
	v_mfma_f32_16x16x32_bf16 v[36:39], v[138:141], v[202:205], v[36:39]
	v_mfma_f32_16x16x32_bf16 v[32:35], v[146:149], v[202:205], v[32:35]
	v_mfma_f32_16x16x32_bf16 v[20:23], v[138:141], v[210:213], v[20:23]
	v_mfma_f32_16x16x32_bf16 v[16:19], v[146:149], v[210:213], v[16:19]
	v_mfma_f32_16x16x32_bf16 v[60:63], v[142:145], v[190:193], v[60:63]
	v_mfma_f32_16x16x32_bf16 v[56:59], v[150:153], v[190:193], v[56:59]
	v_mfma_f32_16x16x32_bf16 v[52:55], v[142:145], v[198:201], v[52:55]
	v_mfma_f32_16x16x32_bf16 v[48:51], v[150:153], v[198:201], v[48:51]
	v_mfma_f32_16x16x32_bf16 v[36:39], v[142:145], v[206:209], v[36:39]
	v_mfma_f32_16x16x32_bf16 v[32:35], v[150:153], v[206:209], v[32:35]
	v_mfma_f32_16x16x32_bf16 v[20:23], v[142:145], v[214:217], v[20:23]
	s_setprio 0
	v_mfma_f32_16x16x32_bf16 v[16:19], v[150:153], v[214:217], v[16:19]
	s_barrier
; #define PG8_STAGE(bufoff, gbase) do { _Pragma("unroll") for (int _i = 0; _i < 2; ++_i) \
;         __builtin_amdgcn_global_load_lds((const unsigned*)((const char*)(gbase) + voff[_i]), (LAS unsigned*)(lds + (bufoff) + ldsw + _i * 8192), 16, 0, 0); } while (0)
; #define PG8_LDA(dst, b, h) do { _Pragma("unroll") for (int m = 0; m < 4; ++m) _Pragma("unroll") for (int k = 0; k < 2; ++k) dst[m][k] = *(const LAS bf16x8*)(lds + PG8_SA(b, h) + aoff + m * 2048 + k * 1024); } while (0)
; #define PG8_LDB(dst, b, h) do { _Pragma("unroll") for (int n = 0; n < 2; ++n) _Pragma("unroll") for (int k = 0; k < 2; ++k) dst[n][k] = *(const LAS bf16x8*)(lds + PG8_SB(b, h) + boff + n * 2048 + k * 1024); } while (0)
; #define PG8_MMA(ai, bj, At, Bt) do { __builtin_amdgcn_s_setprio(1); _Pragma("unroll") for (int m = 0; m < 4; ++m) _Pragma("unroll") for (int n = 0; n < 2; ++n) _Pragma("unroll") for (int k = 0; k < 2; ++k) \
;         acc[ai][bj][m][n] = __builtin_amdgcn_mfma_f32_16x16x32_bf16(Bt[n][k], At[m][k], acc[ai][bj][m][n], 0, 0, 0); __builtin_amdgcn_s_setprio(0); } while (0)
; #define PG8_WAIT_V(n) asm volatile("s_waitcnt vmcnt(" #n ")" ::: "memory")
; #define PG8_WAIT_L(n) asm volatile("s_waitcnt lgkmcnt(" #n ")" ::: "memory")
; #define PG8_BAR __builtin_amdgcn_s_barrier()
; #define PG8_SCHED __builtin_amdgcn_sched_barrier(0)
; template <class Epi>
; DI void gemm_phase(LAS unsigned char* lds, const Gemm g, const StaticOrder& S, const Epi& E) {
;     ...
;             PG8_STAGE(PG8_SB(0, 1), b2 + hstep);
;             PG8_WAIT_V(6); PG8_BAR; PG8_MMA(1, 1, At, B1); PG8_BAR;
;             PG8_LDB(B0, 1, 0); PG8_SCHED; PG8_LDA(At, 1, 0); PG8_STAGE(PG8_SA(0, 1), a2 + hstep);
;             PG8_WAIT_L(8); PG8_BAR; PG8_WAIT_L(0); PG8_MMA(0, 0, At, B0); PG8_BAR; PG8_SCHED;
;             PG8_LDB(B1, 1, 1); PG8_STAGE(PG8_SB(1, 0), b3);
;             PG8_BAR; PG8_WAIT_L(0); PG8_MMA(0, 1, At, B1); PG8_BAR;
;             PG8_LDA(At, 1, 1); PG8_STAGE(PG8_SA(1, 0), a3);
	s_add_u32 s38, s18, 0x80000
	s_addc_u32 s39, s19, 0
	s_add_i32 s37, s40, s23
	v_lshl_add_u64 v[138:139], s[38:39], 0, v[158:159]
	s_mov_b32 m0, s37
	s_nop 0
	global_load_lds_dwordx4 v[138:139], off
	v_lshl_add_u64 v[138:139], s[38:39], 0, v[128:129]
	s_add_i32 m0, s37, 0x2000
	s_nop 0
	global_load_lds_dwordx4 v[138:139], off
	s_waitcnt vmcnt(6)
	s_setprio 1
	s_barrier
	v_mfma_f32_16x16x32_bf16 v[44:47], v[226:229], v[186:189], v[44:47]
	v_mfma_f32_16x16x32_bf16 v[40:43], v[234:237], v[186:189], v[40:43]
	v_mfma_f32_16x16x32_bf16 v[28:31], v[226:229], v[194:197], v[28:31]
	v_mfma_f32_16x16x32_bf16 v[24:27], v[234:237], v[194:197], v[24:27]
	v_mfma_f32_16x16x32_bf16 v[12:15], v[226:229], v[202:205], v[12:15]
	v_mfma_f32_16x16x32_bf16 v[8:11], v[234:237], v[202:205], v[8:11]
	v_mfma_f32_16x16x32_bf16 v[4:7], v[226:229], v[210:213], v[4:7]
	v_mfma_f32_16x16x32_bf16 v[0:3], v[234:237], v[210:213], v[0:3]
	v_mfma_f32_16x16x32_bf16 v[44:47], v[230:233], v[190:193], v[44:47]
	s_add_i32 s37, 0, 0x18000
	v_mfma_f32_16x16x32_bf16 v[40:43], v[238:241], v[190:193], v[40:43]
	v_mfma_f32_16x16x32_bf16 v[28:31], v[230:233], v[198:201], v[28:31]
	v_mfma_f32_16x16x32_bf16 v[24:27], v[238:241], v[198:201], v[24:27]
	v_mfma_f32_16x16x32_bf16 v[12:15], v[230:233], v[206:209], v[12:15]
	v_mfma_f32_16x16x32_bf16 v[8:11], v[238:241], v[206:209], v[8:11]
	v_mfma_f32_16x16x32_bf16 v[4:7], v[230:233], v[214:217], v[4:7]
	s_setprio 0
	v_mfma_f32_16x16x32_bf16 v[0:3], v[238:241], v[214:217], v[0:3]
	s_barrier
	ds_read_b128 v[138:141], v135 offset:32768
	ds_read_b128 v[142:145], v135 offset:33792
	ds_read_b128 v[146:149], v135 offset:34816
	ds_read_b128 v[150:153], v135 offset:35840
	s_add_u32 s20, s20, 0x80000
	s_addc_u32 s21, s21, 0
	s_mov_b32 m0, s26
	v_lshl_add_u64 v[226:227], s[20:21], 0, v[158:159]
	ds_read_b128 v[186:189], v137 offset:32768
	ds_read_b128 v[190:193], v137 offset:33792
	ds_read_b128 v[194:197], v137 offset:34816
	ds_read_b128 v[198:201], v137 offset:35840
	ds_read_b128 v[202:205], v137 offset:36864
	ds_read_b128 v[206:209], v137 offset:37888
	ds_read_b128 v[210:213], v137 offset:38912
	ds_read_b128 v[214:217], v137 offset:39936
	global_load_lds_dwordx4 v[226:227], off
	v_lshl_add_u64 v[226:227], s[20:21], 0, v[128:129]
	s_mov_b32 m0, s27
	s_nop 0
	global_load_lds_dwordx4 v[226:227], off
	s_waitcnt lgkmcnt(8)
	s_setprio 1
	s_barrier
	s_waitcnt lgkmcnt(0)
	v_mfma_f32_16x16x32_bf16 v[124:127], v[138:141], v[186:189], v[124:127]
	v_mfma_f32_16x16x32_bf16 v[120:123], v[146:149], v[186:189], v[120:123]
	v_mfma_f32_16x16x32_bf16 v[116:119], v[138:141], v[194:197], v[116:119]
	v_mfma_f32_16x16x32_bf16 v[112:115], v[146:149], v[194:197], v[112:115]
	v_mfma_f32_16x16x32_bf16 v[100:103], v[138:141], v[202:205], v[100:103]
	v_mfma_f32_16x16x32_bf16 v[96:99], v[146:149], v[202:205], v[96:99]
	v_mfma_f32_16x16x32_bf16 v[84:87], v[138:141], v[210:213], v[84:87]
	v_mfma_f32_16x16x32_bf16 v[80:83], v[146:149], v[210:213], v[80:83]
	v_mfma_f32_16x16x32_bf16 v[124:127], v[142:145], v[190:193], v[124:127]
	v_mfma_f32_16x16x32_bf16 v[120:123], v[150:153], v[190:193], v[120:123]
	v_mfma_f32_16x16x32_bf16 v[116:119], v[142:145], v[198:201], v[116:119]
	v_mfma_f32_16x16x32_bf16 v[112:115], v[150:153], v[198:201], v[112:115]
	v_mfma_f32_16x16x32_bf16 v[100:103], v[142:145], v[206:209], v[100:103]
	v_mfma_f32_16x16x32_bf16 v[96:99], v[150:153], v[206:209], v[96:99]
	v_mfma_f32_16x16x32_bf16 v[84:87], v[142:145], v[214:217], v[84:87]
	s_setprio 0
	v_mfma_f32_16x16x32_bf16 v[80:83], v[150:153], v[214:217], v[80:83]
	s_barrier
	s_add_i32 s20, 0, 0x1c000
	s_add_i32 s21, s37, s23
	v_lshl_add_u64 v[154:155], v[154:155], 0, s[94:95]
	s_mov_b32 m0, s21
	ds_read_b128 v[226:229], v135 offset:49152
	ds_read_b128 v[230:233], v135 offset:50176
	ds_read_b128 v[234:237], v135 offset:51200
	ds_read_b128 v[238:241], v135 offset:52224
	global_load_lds_dwordx4 v[154:155], off
	v_lshl_add_u64 v[154:155], v[218:219], 0, s[94:95]
	s_add_i32 m0, s21, 0x2000
	s_nop 0
	global_load_lds_dwordx4 v[154:155], off
	s_waitcnt lgkmcnt(0)
	s_setprio 1
	s_barrier
	v_mfma_f32_16x16x32_bf16 v[108:111], v[226:229], v[186:189], v[108:111]
	v_mfma_f32_16x16x32_bf16 v[104:107], v[234:237], v[186:189], v[104:107]
	v_mfma_f32_16x16x32_bf16 v[92:95], v[226:229], v[194:197], v[92:95]
	v_mfma_f32_16x16x32_bf16 v[88:91], v[234:237], v[194:197], v[88:91]
	v_mfma_f32_16x16x32_bf16 v[76:79], v[226:229], v[202:205], v[76:79]
	v_mfma_f32_16x16x32_bf16 v[72:75], v[234:237], v[202:205], v[72:75]
	v_mfma_f32_16x16x32_bf16 v[68:71], v[226:229], v[210:213], v[68:71]
	v_mfma_f32_16x16x32_bf16 v[64:67], v[234:237], v[210:213], v[64:67]
	v_mfma_f32_16x16x32_bf16 v[108:111], v[230:233], v[190:193], v[108:111]
	s_mov_b32 m0, s28
	v_mfma_f32_16x16x32_bf16 v[104:107], v[238:241], v[190:193], v[104:107]
	v_lshl_add_u64 v[154:155], v[242:243], 0, s[94:95]
	v_mfma_f32_16x16x32_bf16 v[92:95], v[230:233], v[198:201], v[92:95]
	v_mfma_f32_16x16x32_bf16 v[88:91], v[238:241], v[198:201], v[88:91]
	v_mfma_f32_16x16x32_bf16 v[76:79], v[230:233], v[206:209], v[76:79]
	v_mfma_f32_16x16x32_bf16 v[72:75], v[238:241], v[206:209], v[72:75]
	v_mfma_f32_16x16x32_bf16 v[68:71], v[230:233], v[214:217], v[68:71]
	s_setprio 0
	v_mfma_f32_16x16x32_bf16 v[64:67], v[238:241], v[214:217], v[64:67]
	s_barrier
	ds_read_b128 v[186:189], v137 offset:49152
	ds_read_b128 v[190:193], v137 offset:50176
	ds_read_b128 v[194:197], v137 offset:51200
	ds_read_b128 v[198:201], v137 offset:52224
	ds_read_b128 v[202:205], v137 offset:53248
	ds_read_b128 v[206:209], v137 offset:54272
	ds_read_b128 v[210:213], v137 offset:55296
	ds_read_b128 v[214:217], v137 offset:56320
	global_load_lds_dwordx4 v[154:155], off
	v_lshl_add_u64 v[154:155], v[244:245], 0, s[94:95]
	s_mov_b32 m0, s29
	s_nop 0
	global_load_lds_dwordx4 v[154:155], off
	s_waitcnt lgkmcnt(0)
	s_setprio 1
	s_barrier
; #define PG8_STAGE(bufoff, gbase) do { _Pragma("unroll") for (int _i = 0; _i < 2; ++_i) \
;         __builtin_amdgcn_global_load_lds((const unsigned*)((const char*)(gbase) + voff[_i]), (LAS unsigned*)(lds + (bufoff) + ldsw + _i * 8192), 16, 0, 0); } while (0)
; #define PG8_MMA(ai, bj, At, Bt) do { __builtin_amdgcn_s_setprio(1); _Pragma("unroll") for (int m = 0; m < 4; ++m) _Pragma("unroll") for (int n = 0; n < 2; ++n) _Pragma("unroll") for (int k = 0; k < 2; ++k) \
;         acc[ai][bj][m][n] = __builtin_amdgcn_mfma_f32_16x16x32_bf16(Bt[n][k], At[m][k], acc[ai][bj][m][n], 0, 0, 0); __builtin_amdgcn_s_setprio(0); } while (0)
; #define PG8_WAIT_V(n) asm volatile("s_waitcnt vmcnt(" #n ")" ::: "memory")
; #define PG8_WAIT_L(n) asm volatile("s_waitcnt lgkmcnt(" #n ")" ::: "memory")
; #define PG8_BAR __builtin_amdgcn_s_barrier()
; #define PG8_SCHED __builtin_amdgcn_sched_barrier(0)
; template <class Epi>
; DI void gemm_phase(LAS unsigned char* lds, const Gemm g, const StaticOrder& S, const Epi& E) {
;     ...
;             PG8_BAR; PG8_WAIT_L(0); PG8_MMA(1, 0, At, B0); PG8_BAR; PG8_SCHED;
;             PG8_STAGE(PG8_SB(1, 1), b3 + hstep);
;             PG8_WAIT_V(6); PG8_BAR; PG8_MMA(1, 1, At, B1); PG8_BAR;
;         }
	v_mfma_f32_16x16x32_bf16 v[60:63], v[138:141], v[186:189], v[60:63]
	v_mfma_f32_16x16x32_bf16 v[56:59], v[146:149], v[186:189], v[56:59]
	v_mfma_f32_16x16x32_bf16 v[52:55], v[138:141], v[194:197], v[52:55]
	v_mfma_f32_16x16x32_bf16 v[48:51], v[146:149], v[194:197], v[48:51]
	v_mfma_f32_16x16x32_bf16 v[36:39], v[138:141], v[202:205], v[36:39]
	v_mfma_f32_16x16x32_bf16 v[32:35], v[146:149], v[202:205], v[32:35]
	v_mfma_f32_16x16x32_bf16 v[20:23], v[138:141], v[210:213], v[20:23]
	v_mfma_f32_16x16x32_bf16 v[16:19], v[146:149], v[210:213], v[16:19]
	v_mfma_f32_16x16x32_bf16 v[60:63], v[142:145], v[190:193], v[60:63]
	v_mfma_f32_16x16x32_bf16 v[56:59], v[150:153], v[190:193], v[56:59]
	v_mfma_f32_16x16x32_bf16 v[52:55], v[142:145], v[198:201], v[52:55]
	v_mfma_f32_16x16x32_bf16 v[48:51], v[150:153], v[198:201], v[48:51]
	v_mfma_f32_16x16x32_bf16 v[36:39], v[142:145], v[206:209], v[36:39]
	v_mfma_f32_16x16x32_bf16 v[32:35], v[150:153], v[206:209], v[32:35]
	v_mfma_f32_16x16x32_bf16 v[20:23], v[142:145], v[214:217], v[20:23]
	s_setprio 0
	v_mfma_f32_16x16x32_bf16 v[16:19], v[150:153], v[214:217], v[16:19]
	s_barrier
	s_add_u32 s18, s18, 0x80080
	s_addc_u32 s19, s19, 0
	s_add_i32 s20, s20, s23
	v_lshl_add_u64 v[138:139], s[18:19], 0, v[158:159]
	s_mov_b32 m0, s20
	s_nop 0
	global_load_lds_dwordx4 v[138:139], off
	v_lshl_add_u64 v[138:139], s[18:19], 0, v[128:129]
	s_add_i32 m0, s20, 0x2000
	s_nop 0
	global_load_lds_dwordx4 v[138:139], off
	s_waitcnt vmcnt(6)
	s_setprio 1
	s_barrier
	v_mfma_f32_16x16x32_bf16 v[44:47], v[226:229], v[186:189], v[44:47]
	v_mfma_f32_16x16x32_bf16 v[40:43], v[234:237], v[186:189], v[40:43]
	v_mfma_f32_16x16x32_bf16 v[28:31], v[226:229], v[194:197], v[28:31]
	v_mfma_f32_16x16x32_bf16 v[24:27], v[234:237], v[194:197], v[24:27]
	v_mfma_f32_16x16x32_bf16 v[12:15], v[226:229], v[202:205], v[12:15]
	v_mfma_f32_16x16x32_bf16 v[8:11], v[234:237], v[202:205], v[8:11]
	v_mfma_f32_16x16x32_bf16 v[4:7], v[226:229], v[210:213], v[4:7]
	v_mfma_f32_16x16x32_bf16 v[0:3], v[234:237], v[210:213], v[0:3]
	v_mfma_f32_16x16x32_bf16 v[44:47], v[230:233], v[190:193], v[44:47]
	s_add_i32 s36, s36, 2
	v_mfma_f32_16x16x32_bf16 v[40:43], v[238:241], v[190:193], v[40:43]
	s_add_u32 s16, s16, 0x100
	v_mfma_f32_16x16x32_bf16 v[28:31], v[230:233], v[198:201], v[28:31]
	s_addc_u32 s17, s17, 0
	v_mfma_f32_16x16x32_bf16 v[24:27], v[238:241], v[198:201], v[24:27]
	s_add_u32 s34, s34, 0x100
	v_mfma_f32_16x16x32_bf16 v[12:15], v[230:233], v[206:209], v[12:15]
	s_addc_u32 s35, s35, 0
	v_mfma_f32_16x16x32_bf16 v[8:11], v[238:241], v[206:209], v[8:11]
	s_cmp_gt_u32 s36, 29
	v_mfma_f32_16x16x32_bf16 v[4:7], v[230:233], v[214:217], v[4:7]
	s_setprio 0
	v_mfma_f32_16x16x32_bf16 v[0:3], v[238:241], v[214:217], v[0:3]
	s_barrier
	s_cbranch_scc0 .LBB0_231
; #define PG8_WAIT_V(n) asm volatile("s_waitcnt vmcnt(" #n ")" ::: "memory")
; #define PG8_BAR __builtin_amdgcn_s_barrier()
; template <class Epi>
; DI void gemm_phase(LAS unsigned char* lds, const Gemm g, const StaticOrder& S, const Epi& E) {
;     ...
;         E(acc, cur, wr, wc, fr, fq);
;         if (!has_next) break;
; #pragma unroll
;         for (int a = 0; a < 2; ++a)
; #pragma unroll
;             for (int b = 0; b < 2; ++b)
; #pragma unroll
;                 for (int m = 0; m < 4; ++m)
; #pragma unroll
;                     for (int n = 0; n < 2; ++n) acc[a][b][m][n] = (f32x4){0.f, 0.f, 0.f, 0.f};
;         cur = nxt; cA = nA; cB = nB; ++ui;
;     }
;     PG8_WAIT_V(0);
;     if (wr == 0) PG8_BAR;
;     DI void operator()(const f32x4 (&acc)[2][2][4][2], const Unit& u, int wr, int wc, int fr, int fq) const {
;         const int row0 = u.pm * BM + wr * 64 + fr, col0 = u.pn * BM + wc * 32 + 8 * fq;
; #pragma unroll
;         for (int ai = 0; ai < 2; ++ai)
; #pragma unroll
;             for (int m = 0; m < 4; ++m) { u16* rowp = O + (size_t)(row0 + ai * HALF + m * 16) * ldc + col0;
; #pragma unroll
;                 for (int bj = 0; bj < 2; ++bj) { const f32x4 v0 = acc[ai][bj][m][0], v1 = acc[ai][bj][m][1];
;                     *(u32x4*)(rowp + bj * HALF) = (u32x4){pk(v0[0], v0[1]), pk(v0[2], v0[3]), pk(v1[0], v1[1]), pk(v1[2], v1[3])}; } }
;     }
	v_lshl_add_u32 v144, s33, 8, v134
	v_lshl_or_b32 v138, s31, 8, v136
	v_ashrrev_i32_e32 v139, 31, v138
	v_mov_b64_e32 v[140:141], s[50:51]
	s_movk_i32 s9, 0x3000
	v_cvt_pk_bf16_f32 v68, v68, v69
	v_cvt_pk_bf16_f32 v69, v70, v71
	v_cvt_pk_bf16_f32 v70, v64, v65
	v_add_u32_e32 v64, 0x80, v144
	v_mad_i64_i32 v[142:143], s[4:5], v144, s9, v[140:141]
	v_lshlrev_b64 v[138:139], 1, v[138:139]
	v_cvt_pk_bf16_f32 v108, v108, v109
	v_cvt_pk_bf16_f32 v109, v110, v111
	v_cvt_pk_bf16_f32 v110, v104, v105
	v_or_b32_e32 v104, 16, v144
	v_mad_i64_i32 v[64:65], s[4:5], v64, s9, v[140:141]
	v_cvt_pk_bf16_f32 v44, v44, v45
	v_cvt_pk_bf16_f32 v45, v46, v47
	v_cvt_pk_bf16_f32 v46, v40, v41
	v_add_u32_e32 v40, 0x90, v144
	v_lshl_add_u64 v[142:143], v[142:143], 0, v[138:139]
	v_cvt_pk_bf16_f32 v111, v106, v107
	v_mad_i64_i32 v[104:105], s[4:5], v104, s9, v[140:141]
	v_cvt_pk_bf16_f32 v92, v92, v93
	v_cvt_pk_bf16_f32 v93, v94, v95
	v_cvt_pk_bf16_f32 v94, v88, v89
	v_or_b32_e32 v88, 32, v144
	v_lshl_add_u64 v[64:65], v[64:65], 0, v[138:139]
	v_cvt_pk_bf16_f32 v47, v42, v43
	v_mad_i64_i32 v[40:41], s[4:5], v40, s9, v[140:141]
	v_cvt_pk_bf16_f32 v28, v28, v29
	v_cvt_pk_bf16_f32 v29, v30, v31
	v_cvt_pk_bf16_f32 v30, v24, v25
	v_add_u32_e32 v24, 0xa0, v144
	global_store_dwordx4 v[142:143], v[108:111], off offset:256
	v_cvt_pk_bf16_f32 v95, v90, v91
	v_mad_i64_i32 v[88:89], s[4:5], v88, s9, v[140:141]
	v_lshl_add_u64 v[108:109], v[104:105], 0, v[138:139]
	v_cvt_pk_bf16_f32 v76, v76, v77
	v_cvt_pk_bf16_f32 v77, v78, v79
	v_cvt_pk_bf16_f32 v78, v72, v73
	v_or_b32_e32 v72, 48, v144
	global_store_dwordx4 v[64:65], v[44:47], off offset:256
	v_cvt_pk_bf16_f32 v31, v26, v27
	v_mad_i64_i32 v[24:25], s[4:5], v24, s9, v[140:141]
	v_lshl_add_u64 v[44:45], v[40:41], 0, v[138:139]
	v_cvt_pk_bf16_f32 v12, v12, v13
	v_cvt_pk_bf16_f32 v13, v14, v15
	v_cvt_pk_bf16_f32 v14, v8, v9
	v_add_u32_e32 v8, 0xb0, v144
	global_store_dwordx4 v[108:109], v[92:95], off offset:256
	v_cvt_pk_bf16_f32 v79, v74, v75
	v_mad_i64_i32 v[72:73], s[4:5], v72, s9, v[140:141]
	v_lshl_add_u64 v[92:93], v[88:89], 0, v[138:139]
	global_store_dwordx4 v[44:45], v[28:31], off offset:256
	v_cvt_pk_bf16_f32 v15, v10, v11
	v_mad_i64_i32 v[8:9], s[4:5], v8, s9, v[140:141]
	v_lshl_add_u64 v[28:29], v[24:25], 0, v[138:139]
	v_cvt_pk_bf16_f32 v124, v124, v125
	v_cvt_pk_bf16_f32 v125, v126, v127
	v_cvt_pk_bf16_f32 v126, v120, v121
	v_cvt_pk_bf16_f32 v127, v122, v123
	v_cvt_pk_bf16_f32 v104, v116, v117
	v_cvt_pk_bf16_f32 v105, v118, v119
	v_cvt_pk_bf16_f32 v106, v112, v113
	v_cvt_pk_bf16_f32 v107, v114, v115
	v_cvt_pk_bf16_f32 v88, v100, v101
	v_cvt_pk_bf16_f32 v89, v102, v103
	v_cvt_pk_bf16_f32 v90, v96, v97
	v_cvt_pk_bf16_f32 v91, v98, v99
	global_store_dwordx4 v[92:93], v[76:79], off offset:256
	v_cvt_pk_bf16_f32 v74, v80, v81
	v_cvt_pk_bf16_f32 v75, v82, v83
	v_lshl_add_u64 v[76:77], v[72:73], 0, v[138:139]
	v_cvt_pk_bf16_f32 v72, v84, v85
	v_cvt_pk_bf16_f32 v73, v86, v87
	v_cvt_pk_bf16_f32 v71, v66, v67
	v_cvt_pk_bf16_f32 v60, v60, v61
	v_cvt_pk_bf16_f32 v61, v62, v63
	v_cvt_pk_bf16_f32 v62, v56, v57
	v_cvt_pk_bf16_f32 v63, v58, v59
	v_cvt_pk_bf16_f32 v40, v52, v53
	v_cvt_pk_bf16_f32 v41, v54, v55
	v_cvt_pk_bf16_f32 v42, v48, v49
	v_cvt_pk_bf16_f32 v43, v50, v51
	v_cvt_pk_bf16_f32 v24, v36, v37
	v_cvt_pk_bf16_f32 v25, v38, v39
	v_cvt_pk_bf16_f32 v26, v32, v33
	v_cvt_pk_bf16_f32 v27, v34, v35
	global_store_dwordx4 v[28:29], v[12:15], off offset:256
	v_cvt_pk_bf16_f32 v10, v16, v17
	v_cvt_pk_bf16_f32 v11, v18, v19
	v_lshl_add_u64 v[12:13], v[8:9], 0, v[138:139]
	v_cvt_pk_bf16_f32 v8, v20, v21
	v_cvt_pk_bf16_f32 v9, v22, v23
	v_cvt_pk_bf16_f32 v4, v4, v5
	v_cvt_pk_bf16_f32 v5, v6, v7
	v_cvt_pk_bf16_f32 v6, v0, v1
	v_cvt_pk_bf16_f32 v7, v2, v3
	s_and_b64 vcc, exec, s[6:7]
	s_mov_b32 s31, s8
	s_mov_b32 s33, s10
	s_mov_b64 s[18:19], s[14:15]
	s_mov_b64 s[16:17], s[12:13]
	global_store_dwordx4 v[142:143], v[124:127], off
	global_store_dwordx4 v[108:109], v[104:107], off
	global_store_dwordx4 v[92:93], v[88:91], off
	global_store_dwordx4 v[76:77], v[72:75], off
	global_store_dwordx4 v[76:77], v[68:71], off offset:256
	global_store_dwordx4 v[64:65], v[60:63], off
	global_store_dwordx4 v[44:45], v[40:43], off
	global_store_dwordx4 v[28:29], v[24:27], off
	global_store_dwordx4 v[12:13], v[8:11], off
	global_store_dwordx4 v[12:13], v[4:7], off offset:256
	s_cbranch_vccz .LBB0_228
	s_waitcnt vmcnt(0)
	s_cmpk_gt_u32 s2, 0xff
	s_cbranch_scc1 .LBB0_235
	s_barrier

; #define PG8_STAGE(bufoff, gbase) do { _Pragma("unroll") for (int _i = 0; _i < 2; ++_i) \
;         __builtin_amdgcn_global_load_lds((const unsigned*)((const char*)(gbase) + voff[_i]), (LAS unsigned*)(lds + (bufoff) + ldsw + _i * 8192), 16, 0, 0); } while (0)
; #define PG8_LDA(dst, b, h) do { _Pragma("unroll") for (int m = 0; m < 4; ++m) _Pragma("unroll") for (int k = 0; k < 2; ++k) dst[m][k] = *(const LAS bf16x8*)(lds + PG8_SA(b, h) + aoff + m * 2048 + k * 1024); } while (0)
; #define PG8_LDB(dst, b, h) do { _Pragma("unroll") for (int n = 0; n < 2; ++n) _Pragma("unroll") for (int k = 0; k < 2; ++k) dst[n][k] = *(const LAS bf16x8*)(lds + PG8_SB(b, h) + boff + n * 2048 + k * 1024); } while (0)
; #define PG8_MMA(ai, bj, At, Bt) do { __builtin_amdgcn_s_setprio(1); _Pragma("unroll") for (int m = 0; m < 4; ++m) _Pragma("unroll") for (int n = 0; n < 2; ++n) _Pragma("unroll") for (int k = 0; k < 2; ++k) \
;         acc[ai][bj][m][n] = __builtin_amdgcn_mfma_f32_16x16x32_bf16(Bt[n][k], At[m][k], acc[ai][bj][m][n], 0, 0, 0); __builtin_amdgcn_s_setprio(0); } while (0)
; #define PG8_WAIT_L(n) asm volatile("s_waitcnt lgkmcnt(" #n ")" ::: "memory")
; #define PG8_BAR __builtin_amdgcn_s_barrier()
; #define PG8_SCHED __builtin_amdgcn_sched_barrier(0)
; template <class Epi>
; DI void gemm_phase(LAS unsigned char* lds, const Gemm g, const StaticOrder& S, const Epi& E) {
;     ...
;             PG8_LDB(B0, 0, 0); PG8_SCHED; PG8_LDA(At, 0, 0); PG8_STAGE(PG8_SA(1, 1), a1 + hstep);
;             PG8_WAIT_L(8); PG8_BAR; PG8_WAIT_L(0); PG8_MMA(0, 0, At, B0); PG8_BAR; PG8_SCHED;
;             PG8_LDB(B1, 0, 1); PG8_STAGE(PG8_SB(0, 0), b2);
;             PG8_BAR; PG8_WAIT_L(0); PG8_MMA(0, 1, At, B1); PG8_BAR;
;             PG8_LDA(At, 0, 1); PG8_STAGE(PG8_SA(0, 0), a2);
;             PG8_BAR; PG8_WAIT_L(0); PG8_MMA(1, 0, At, B0); PG8_BAR; PG8_SCHED;
.LBB0_320:
	s_add_u32 s26, s24, 0x100
	s_addc_u32 s27, s25, 0
	s_add_i32 s47, 0, 0x10000
	ds_read_b128 v[128:131], v226
	ds_read_b128 v[132:135], v226 offset:1024
	ds_read_b128 v[136:139], v226 offset:2048
	ds_read_b128 v[140:143], v226 offset:3072
	s_cmp_eq_u32 s46, 28
	s_cselect_b32 s31, s4, s27
	s_cselect_b32 s30, s5, s26
	s_cselect_b32 s29, s9, s45
	s_cselect_b32 s28, s11, s33
	v_lshl_add_u64 v[214:215], s[24:25], 0, v[190:191]
	s_add_i32 m0, s38, 0xc000
	ds_read_b128 v[144:147], v228
	ds_read_b128 v[148:151], v228 offset:1024
	ds_read_b128 v[152:155], v228 offset:2048
	ds_read_b128 v[194:197], v228 offset:3072
	ds_read_b128 v[198:201], v228 offset:4096
	ds_read_b128 v[202:205], v228 offset:5120
	ds_read_b128 v[206:209], v228 offset:6144
	ds_read_b128 v[210:213], v228 offset:7168
	global_load_lds_dwordx4 v[214:215], off
	v_lshl_add_u64 v[214:215], s[24:25], 0, v[192:193]
	s_add_i32 m0, s38, 0xe000
	s_nop 0
	global_load_lds_dwordx4 v[214:215], off
	s_waitcnt lgkmcnt(8)
	s_setprio 1
	s_barrier
	s_waitcnt lgkmcnt(0)
	v_mfma_f32_16x16x32_bf16 v[124:127], v[128:131], v[144:147], v[124:127]
	v_mfma_f32_16x16x32_bf16 v[120:123], v[136:139], v[144:147], v[120:123]
	v_mfma_f32_16x16x32_bf16 v[116:119], v[128:131], v[152:155], v[116:119]
	v_mfma_f32_16x16x32_bf16 v[112:115], v[136:139], v[152:155], v[112:115]
	v_mfma_f32_16x16x32_bf16 v[108:111], v[128:131], v[198:201], v[108:111]
	v_mfma_f32_16x16x32_bf16 v[104:107], v[136:139], v[198:201], v[104:107]
	v_mfma_f32_16x16x32_bf16 v[100:103], v[128:131], v[206:209], v[100:103]
	v_mfma_f32_16x16x32_bf16 v[96:99], v[136:139], v[206:209], v[96:99]
	v_mfma_f32_16x16x32_bf16 v[124:127], v[132:135], v[148:151], v[124:127]
	v_mfma_f32_16x16x32_bf16 v[120:123], v[140:143], v[148:151], v[120:123]
	v_mfma_f32_16x16x32_bf16 v[116:119], v[132:135], v[194:197], v[116:119]
	v_mfma_f32_16x16x32_bf16 v[112:115], v[140:143], v[194:197], v[112:115]
	v_mfma_f32_16x16x32_bf16 v[108:111], v[132:135], v[202:205], v[108:111]
	v_mfma_f32_16x16x32_bf16 v[104:107], v[140:143], v[202:205], v[104:107]
	v_mfma_f32_16x16x32_bf16 v[100:103], v[132:135], v[210:213], v[100:103]
	s_setprio 0
	v_mfma_f32_16x16x32_bf16 v[96:99], v[140:143], v[210:213], v[96:99]
	s_barrier
	s_add_i32 s48, 0, 0x14000
	s_add_i32 s24, s47, s37
	v_lshl_add_u64 v[218:219], s[28:29], 0, v[188:189]
	s_mov_b32 m0, s24
	ds_read_b128 v[214:217], v226 offset:16384
	ds_read_b128 v[230:233], v226 offset:17408
	ds_read_b128 v[234:237], v226 offset:18432
	ds_read_b128 v[238:241], v226 offset:19456
	global_load_lds_dwordx4 v[218:219], off
	v_lshl_add_u64 v[220:221], s[28:29], 0, v[186:187]
	s_add_i32 m0, s24, 0x2000
	s_nop 0
	global_load_lds_dwordx4 v[220:221], off
	s_waitcnt lgkmcnt(0)
	s_setprio 1
	s_barrier
	v_mfma_f32_16x16x32_bf16 v[60:63], v[214:217], v[144:147], v[60:63]
	v_mfma_f32_16x16x32_bf16 v[56:59], v[234:237], v[144:147], v[56:59]
	v_mfma_f32_16x16x32_bf16 v[52:55], v[214:217], v[152:155], v[52:55]
	v_mfma_f32_16x16x32_bf16 v[48:51], v[234:237], v[152:155], v[48:51]
	v_mfma_f32_16x16x32_bf16 v[44:47], v[214:217], v[198:201], v[44:47]
	v_mfma_f32_16x16x32_bf16 v[40:43], v[234:237], v[198:201], v[40:43]
	v_mfma_f32_16x16x32_bf16 v[36:39], v[214:217], v[206:209], v[36:39]
	v_mfma_f32_16x16x32_bf16 v[32:35], v[234:237], v[206:209], v[32:35]
	v_mfma_f32_16x16x32_bf16 v[60:63], v[230:233], v[148:151], v[60:63]
	s_mov_b32 m0, s38
	v_mfma_f32_16x16x32_bf16 v[56:59], v[238:241], v[148:151], v[56:59]
	v_lshl_add_u64 v[242:243], s[30:31], 0, v[188:189]
	v_mfma_f32_16x16x32_bf16 v[52:55], v[230:233], v[194:197], v[52:55]
	v_mfma_f32_16x16x32_bf16 v[48:51], v[238:241], v[194:197], v[48:51]
	v_mfma_f32_16x16x32_bf16 v[44:47], v[230:233], v[202:205], v[44:47]
	v_mfma_f32_16x16x32_bf16 v[40:43], v[238:241], v[202:205], v[40:43]
	v_mfma_f32_16x16x32_bf16 v[36:39], v[230:233], v[210:213], v[36:39]
	s_setprio 0
	v_mfma_f32_16x16x32_bf16 v[32:35], v[238:241], v[210:213], v[32:35]
	s_barrier
	ds_read_b128 v[144:147], v228 offset:16384
	ds_read_b128 v[148:151], v228 offset:17408
	ds_read_b128 v[152:155], v228 offset:18432
	ds_read_b128 v[194:197], v228 offset:19456
	ds_read_b128 v[198:201], v228 offset:20480
	ds_read_b128 v[202:205], v228 offset:21504
	ds_read_b128 v[206:209], v228 offset:22528
	ds_read_b128 v[210:213], v228 offset:23552
	global_load_lds_dwordx4 v[242:243], off
	v_lshl_add_u64 v[244:245], s[30:31], 0, v[186:187]
	s_mov_b32 m0, s39
	s_nop 0
	global_load_lds_dwordx4 v[244:245], off
	s_waitcnt lgkmcnt(0)
	s_setprio 1
	s_barrier
	v_mfma_f32_16x16x32_bf16 v[92:95], v[128:131], v[144:147], v[92:95]
	v_mfma_f32_16x16x32_bf16 v[88:91], v[136:139], v[144:147], v[88:91]
	v_mfma_f32_16x16x32_bf16 v[84:87], v[128:131], v[152:155], v[84:87]
	v_mfma_f32_16x16x32_bf16 v[80:83], v[136:139], v[152:155], v[80:83]
	v_mfma_f32_16x16x32_bf16 v[76:79], v[128:131], v[198:201], v[76:79]
	v_mfma_f32_16x16x32_bf16 v[72:75], v[136:139], v[198:201], v[72:75]
	v_mfma_f32_16x16x32_bf16 v[68:71], v[128:131], v[206:209], v[68:71]
	v_mfma_f32_16x16x32_bf16 v[64:67], v[136:139], v[206:209], v[64:67]
	v_mfma_f32_16x16x32_bf16 v[92:95], v[132:135], v[148:151], v[92:95]
	v_mfma_f32_16x16x32_bf16 v[88:91], v[140:143], v[148:151], v[88:91]
	v_mfma_f32_16x16x32_bf16 v[84:87], v[132:135], v[194:197], v[84:87]
	v_mfma_f32_16x16x32_bf16 v[80:83], v[140:143], v[194:197], v[80:83]
	v_mfma_f32_16x16x32_bf16 v[76:79], v[132:135], v[202:205], v[76:79]
	v_mfma_f32_16x16x32_bf16 v[72:75], v[140:143], v[202:205], v[72:75]
	v_mfma_f32_16x16x32_bf16 v[68:71], v[132:135], v[210:213], v[68:71]
	s_setprio 0
	v_mfma_f32_16x16x32_bf16 v[64:67], v[140:143], v[210:213], v[64:67]
	s_barrier
; #define PG8_STAGE(bufoff, gbase) do { _Pragma("unroll") for (int _i = 0; _i < 2; ++_i) \
;         __builtin_amdgcn_global_load_lds((const unsigned*)((const char*)(gbase) + voff[_i]), (LAS unsigned*)(lds + (bufoff) + ldsw + _i * 8192), 16, 0, 0); } while (0)
; #define PG8_LDA(dst, b, h) do { _Pragma("unroll") for (int m = 0; m < 4; ++m) _Pragma("unroll") for (int k = 0; k < 2; ++k) dst[m][k] = *(const LAS bf16x8*)(lds + PG8_SA(b, h) + aoff + m * 2048 + k * 1024); } while (0)
; #define PG8_LDB(dst, b, h) do { _Pragma("unroll") for (int n = 0; n < 2; ++n) _Pragma("unroll") for (int k = 0; k < 2; ++k) dst[n][k] = *(const LAS bf16x8*)(lds + PG8_SB(b, h) + boff + n * 2048 + k * 1024); } while (0)
; #define PG8_MMA(ai, bj, At, Bt) do { __builtin_amdgcn_s_setprio(1); _Pragma("unroll") for (int m = 0; m < 4; ++m) _Pragma("unroll") for (int n = 0; n < 2; ++n) _Pragma("unroll") for (int k = 0; k < 2; ++k) \
;         acc[ai][bj][m][n] = __builtin_amdgcn_mfma_f32_16x16x32_bf16(Bt[n][k], At[m][k], acc[ai][bj][m][n], 0, 0, 0); __builtin_amdgcn_s_setprio(0); } while (0)
; #define PG8_WAIT_V(n) asm volatile("s_waitcnt vmcnt(" #n ")" ::: "memory")
; #define PG8_WAIT_L(n) asm volatile("s_waitcnt lgkmcnt(" #n ")" ::: "memory")
; #define PG8_BAR __builtin_amdgcn_s_barrier()
; #define PG8_SCHED __builtin_amdgcn_sched_barrier(0)
; template <class Epi>
; DI void gemm_phase(LAS unsigned char* lds, const Gemm g, const StaticOrder& S, const Epi& E) {
;     ...
;             PG8_STAGE(PG8_SB(0, 1), b2 + hstep);
;             PG8_WAIT_V(6); PG8_BAR; PG8_MMA(1, 1, At, B1); PG8_BAR;
;             PG8_LDB(B0, 1, 0); PG8_SCHED; PG8_LDA(At, 1, 0); PG8_STAGE(PG8_SA(0, 1), a2 + hstep);
;             PG8_WAIT_L(8); PG8_BAR; PG8_WAIT_L(0); PG8_MMA(0, 0, At, B0); PG8_BAR; PG8_SCHED;
;             PG8_LDB(B1, 1, 1); PG8_STAGE(PG8_SB(1, 0), b3);
;             PG8_BAR; PG8_WAIT_L(0); PG8_MMA(0, 1, At, B1); PG8_BAR;
;             PG8_LDA(At, 1, 1); PG8_STAGE(PG8_SA(1, 0), a3);
	s_add_u32 s24, s28, 0x80000
	s_addc_u32 s25, s29, 0
	s_add_i32 s47, s48, s37
	v_lshl_add_u64 v[128:129], s[24:25], 0, v[188:189]
	s_mov_b32 m0, s47
	s_nop 0
	global_load_lds_dwordx4 v[128:129], off
	v_lshl_add_u64 v[128:129], s[24:25], 0, v[186:187]
	s_add_i32 m0, s47, 0x2000
	s_nop 0
	global_load_lds_dwordx4 v[128:129], off
	s_waitcnt vmcnt(6)
	s_setprio 1
	s_barrier
	v_mfma_f32_16x16x32_bf16 v[28:31], v[214:217], v[144:147], v[28:31]
	v_mfma_f32_16x16x32_bf16 v[24:27], v[234:237], v[144:147], v[24:27]
	v_mfma_f32_16x16x32_bf16 v[20:23], v[214:217], v[152:155], v[20:23]
	v_mfma_f32_16x16x32_bf16 v[16:19], v[234:237], v[152:155], v[16:19]
	v_mfma_f32_16x16x32_bf16 v[12:15], v[214:217], v[198:201], v[12:15]
	v_mfma_f32_16x16x32_bf16 v[8:11], v[234:237], v[198:201], v[8:11]
	v_mfma_f32_16x16x32_bf16 v[4:7], v[214:217], v[206:209], v[4:7]
	v_mfma_f32_16x16x32_bf16 v[0:3], v[234:237], v[206:209], v[0:3]
	v_mfma_f32_16x16x32_bf16 v[28:31], v[230:233], v[148:151], v[28:31]
	s_add_i32 s47, 0, 0x18000
	v_mfma_f32_16x16x32_bf16 v[24:27], v[238:241], v[148:151], v[24:27]
	v_mfma_f32_16x16x32_bf16 v[20:23], v[230:233], v[194:197], v[20:23]
	v_mfma_f32_16x16x32_bf16 v[16:19], v[238:241], v[194:197], v[16:19]
	v_mfma_f32_16x16x32_bf16 v[12:15], v[230:233], v[202:205], v[12:15]
	v_mfma_f32_16x16x32_bf16 v[8:11], v[238:241], v[202:205], v[8:11]
	v_mfma_f32_16x16x32_bf16 v[4:7], v[230:233], v[210:213], v[4:7]
	s_setprio 0
	v_mfma_f32_16x16x32_bf16 v[0:3], v[238:241], v[210:213], v[0:3]
	s_barrier
	ds_read_b128 v[128:131], v226 offset:32768
	ds_read_b128 v[132:135], v226 offset:33792
	ds_read_b128 v[136:139], v226 offset:34816
	ds_read_b128 v[140:143], v226 offset:35840
	s_add_u32 s24, s30, 0x80000
	s_addc_u32 s25, s31, 0
	s_mov_b32 m0, s40
	v_lshl_add_u64 v[214:215], s[24:25], 0, v[188:189]
	ds_read_b128 v[144:147], v228 offset:32768
	ds_read_b128 v[148:151], v228 offset:33792
	ds_read_b128 v[152:155], v228 offset:34816
	ds_read_b128 v[194:197], v228 offset:35840
	ds_read_b128 v[198:201], v228 offset:36864
	ds_read_b128 v[202:205], v228 offset:37888
	ds_read_b128 v[206:209], v228 offset:38912
	ds_read_b128 v[210:213], v228 offset:39936
	global_load_lds_dwordx4 v[214:215], off
	v_lshl_add_u64 v[214:215], s[24:25], 0, v[186:187]
	s_mov_b32 m0, s41
	s_nop 0
	global_load_lds_dwordx4 v[214:215], off
	s_waitcnt lgkmcnt(8)
	s_setprio 1
	s_barrier
	s_waitcnt lgkmcnt(0)
	v_mfma_f32_16x16x32_bf16 v[124:127], v[128:131], v[144:147], v[124:127]
	v_mfma_f32_16x16x32_bf16 v[120:123], v[136:139], v[144:147], v[120:123]
	v_mfma_f32_16x16x32_bf16 v[116:119], v[128:131], v[152:155], v[116:119]
	v_mfma_f32_16x16x32_bf16 v[112:115], v[136:139], v[152:155], v[112:115]
	v_mfma_f32_16x16x32_bf16 v[108:111], v[128:131], v[198:201], v[108:111]
	v_mfma_f32_16x16x32_bf16 v[104:107], v[136:139], v[198:201], v[104:107]
	v_mfma_f32_16x16x32_bf16 v[100:103], v[128:131], v[206:209], v[100:103]
	v_mfma_f32_16x16x32_bf16 v[96:99], v[136:139], v[206:209], v[96:99]
	v_mfma_f32_16x16x32_bf16 v[124:127], v[132:135], v[148:151], v[124:127]
	v_mfma_f32_16x16x32_bf16 v[120:123], v[140:143], v[148:151], v[120:123]
	v_mfma_f32_16x16x32_bf16 v[116:119], v[132:135], v[194:197], v[116:119]
	v_mfma_f32_16x16x32_bf16 v[112:115], v[140:143], v[194:197], v[112:115]
	v_mfma_f32_16x16x32_bf16 v[108:111], v[132:135], v[202:205], v[108:111]
	v_mfma_f32_16x16x32_bf16 v[104:107], v[140:143], v[202:205], v[104:107]
	v_mfma_f32_16x16x32_bf16 v[100:103], v[132:135], v[210:213], v[100:103]
	s_setprio 0
	v_mfma_f32_16x16x32_bf16 v[96:99], v[140:143], v[210:213], v[96:99]
	s_barrier
	s_add_i32 s30, 0, 0x1c000
	s_add_i32 s24, s47, s37
	v_lshl_add_u64 v[218:219], v[218:219], 0, s[94:95]
	s_mov_b32 m0, s24
	ds_read_b128 v[214:217], v226 offset:49152
	ds_read_b128 v[230:233], v226 offset:50176
	ds_read_b128 v[234:237], v226 offset:51200
	ds_read_b128 v[238:241], v226 offset:52224
	global_load_lds_dwordx4 v[218:219], off
	v_lshl_add_u64 v[218:219], v[220:221], 0, s[94:95]
	s_add_i32 m0, s24, 0x2000
	s_nop 0
	global_load_lds_dwordx4 v[218:219], off
	s_waitcnt lgkmcnt(0)
	s_setprio 1
	s_barrier
	v_mfma_f32_16x16x32_bf16 v[60:63], v[214:217], v[144:147], v[60:63]
	v_mfma_f32_16x16x32_bf16 v[56:59], v[234:237], v[144:147], v[56:59]
	v_mfma_f32_16x16x32_bf16 v[52:55], v[214:217], v[152:155], v[52:55]
	v_mfma_f32_16x16x32_bf16 v[48:51], v[234:237], v[152:155], v[48:51]
	v_mfma_f32_16x16x32_bf16 v[44:47], v[214:217], v[198:201], v[44:47]
	v_mfma_f32_16x16x32_bf16 v[40:43], v[234:237], v[198:201], v[40:43]
	v_mfma_f32_16x16x32_bf16 v[36:39], v[214:217], v[206:209], v[36:39]
	v_mfma_f32_16x16x32_bf16 v[32:35], v[234:237], v[206:209], v[32:35]
	v_mfma_f32_16x16x32_bf16 v[60:63], v[230:233], v[148:151], v[60:63]
	s_mov_b32 m0, s42
	v_mfma_f32_16x16x32_bf16 v[56:59], v[238:241], v[148:151], v[56:59]
	v_lshl_add_u64 v[218:219], v[242:243], 0, s[94:95]
	v_mfma_f32_16x16x32_bf16 v[52:55], v[230:233], v[194:197], v[52:55]
	v_mfma_f32_16x16x32_bf16 v[48:51], v[238:241], v[194:197], v[48:51]
	v_mfma_f32_16x16x32_bf16 v[44:47], v[230:233], v[202:205], v[44:47]
	v_mfma_f32_16x16x32_bf16 v[40:43], v[238:241], v[202:205], v[40:43]
	v_mfma_f32_16x16x32_bf16 v[36:39], v[230:233], v[210:213], v[36:39]
	s_setprio 0
	v_mfma_f32_16x16x32_bf16 v[32:35], v[238:241], v[210:213], v[32:35]
	s_barrier
	ds_read_b128 v[144:147], v228 offset:49152
	ds_read_b128 v[148:151], v228 offset:50176
	ds_read_b128 v[152:155], v228 offset:51200
	ds_read_b128 v[194:197], v228 offset:52224
	ds_read_b128 v[198:201], v228 offset:53248
	ds_read_b128 v[202:205], v228 offset:54272
	ds_read_b128 v[206:209], v228 offset:55296
	ds_read_b128 v[210:213], v228 offset:56320
	global_load_lds_dwordx4 v[218:219], off
	v_lshl_add_u64 v[218:219], v[244:245], 0, s[94:95]
	s_mov_b32 m0, s43
	s_nop 0
	global_load_lds_dwordx4 v[218:219], off
	s_waitcnt lgkmcnt(0)
	s_setprio 1
	s_barrier
; template <class Epi>
; DI void gemm_phase(LAS unsigned char* lds, const Gemm g, const StaticOrder& S, const Epi& E) {
;     ...
;             PG8_BAR; PG8_WAIT_L(0); PG8_MMA(1, 0, At, B0); PG8_BAR; PG8_SCHED;
;             PG8_STAGE(PG8_SB(1, 1), b3 + hstep);
;             PG8_WAIT_V(6); PG8_BAR; PG8_MMA(1, 1, At, B1); PG8_BAR;
;         }
;     template <bool LN, int BJ, int LO, int HI> DI void batch(const f32x4 (&acc)[2][2][4][2], unsigned row0, unsigned col0, const f32x4 (&gv)[2], const f32x4 (&bv)[2]) const {
;         f32x4 r[HI - LO]; float mean[(HI - LO) / 2], rstd[(HI - LO) / 2];
; #pragma unroll
;         for (int i = LO; i < HI; ++i) { const int ai = i >> 3, m = (i >> 1) & 3, n = i & 1; const unsigned row = row0 + ai * HALF + m * 16;
;             if (n == 0) { mean[(i - LO) >> 1] = 0.f; rstd[(i - LO) >> 1] = 1.f;
;                 if (LN) { const float2 st = *(const float2*)(stats + row * 2u); mean[(i - LO) >> 1] = st.x; rstd[(i - LO) >> 1] = st.y; } }
;             r[i - LO] = *(const f32x4*)(src + (row * (unsigned)DM + col0 + BJ * HALF + n * 16)); }
; #pragma unroll
;         for (int i = LO; i < HI; ++i) { const int ai = i >> 3, m = (i >> 1) & 3, n = i & 1; const unsigned row = row0 + ai * HALF + m * 16;
;             *(f32x4*)(Y + (row * (unsigned)DM + col0 + BJ * HALF + n * 16)) = acc[ai][BJ][m][n] + ((r[i - LO] - mean[(i - LO) >> 1]) * rstd[(i - LO) >> 1]) * gv[n] + bv[n]; }
;         __builtin_amdgcn_sched_barrier(0);
;     }
;     template <bool LN, int BJ> DI void load_gb(unsigned col0, f32x4 (&gv)[2], f32x4 (&bv)[2]) const {
; #pragma unroll
;         for (int n = 0; n < 2; ++n) {
;             if (LN) { gv[n] = *(const f32x4*)(gam + col0 + BJ * HALF + n * 16) * ALPHA; bv[n] = *(const f32x4*)(bet + col0 + BJ * HALF + n * 16) * ALPHA; }
;             else { gv[n] = (f32x4){ALPHA, ALPHA, ALPHA, ALPHA}; bv[n] = (f32x4){0.f, 0.f, 0.f, 0.f}; }
;         }
;     }
;     template <bool LN> DI void run(const f32x4 (&acc)[2][2][4][2], const Unit& u, int wr, int wc, int fr, int fq) const {
;         const unsigned row0 = u.pm * BM + wr * 64 + fr, col0 = u.pn * BM + wc * 32 + 4 * fq;
;         f32x4 gv[2], bv[2];
;         load_gb<LN, 0>(col0, gv, bv);
;         batch<LN, 0, 0, 4>(acc, row0, col0, gv, bv);
;         batch<LN, 0, 4, 8>(acc, row0, col0, gv, bv);
;         batch<LN, 0, 8, 12>(acc, row0, col0, gv, bv);
	v_mfma_f32_16x16x32_bf16 v[92:95], v[128:131], v[144:147], v[92:95]
	v_mfma_f32_16x16x32_bf16 v[88:91], v[136:139], v[144:147], v[88:91]
	v_mfma_f32_16x16x32_bf16 v[84:87], v[128:131], v[152:155], v[84:87]
	v_mfma_f32_16x16x32_bf16 v[80:83], v[136:139], v[152:155], v[80:83]
	v_mfma_f32_16x16x32_bf16 v[76:79], v[128:131], v[198:201], v[76:79]
	v_mfma_f32_16x16x32_bf16 v[72:75], v[136:139], v[198:201], v[72:75]
	v_mfma_f32_16x16x32_bf16 v[68:71], v[128:131], v[206:209], v[68:71]
	v_mfma_f32_16x16x32_bf16 v[64:67], v[136:139], v[206:209], v[64:67]
	v_mfma_f32_16x16x32_bf16 v[92:95], v[132:135], v[148:151], v[92:95]
	v_mfma_f32_16x16x32_bf16 v[88:91], v[140:143], v[148:151], v[88:91]
	v_mfma_f32_16x16x32_bf16 v[84:87], v[132:135], v[194:197], v[84:87]
	v_mfma_f32_16x16x32_bf16 v[80:83], v[140:143], v[194:197], v[80:83]
	v_mfma_f32_16x16x32_bf16 v[76:79], v[132:135], v[202:205], v[76:79]
	v_mfma_f32_16x16x32_bf16 v[72:75], v[140:143], v[202:205], v[72:75]
	v_mfma_f32_16x16x32_bf16 v[68:71], v[132:135], v[210:213], v[68:71]
	s_setprio 0
	v_mfma_f32_16x16x32_bf16 v[64:67], v[140:143], v[210:213], v[64:67]
	s_barrier
	s_add_u32 s24, s28, 0x80080
	s_addc_u32 s25, s29, 0
	s_add_i32 s28, s30, s37
	v_lshl_add_u64 v[128:129], s[24:25], 0, v[188:189]
	s_mov_b32 m0, s28
	s_nop 0
	global_load_lds_dwordx4 v[128:129], off
	v_lshl_add_u64 v[128:129], s[24:25], 0, v[186:187]
	s_add_i32 m0, s28, 0x2000
	s_nop 0
	global_load_lds_dwordx4 v[128:129], off
	s_waitcnt vmcnt(6)
	s_setprio 1
	s_barrier
	v_mfma_f32_16x16x32_bf16 v[28:31], v[214:217], v[144:147], v[28:31]
	v_mfma_f32_16x16x32_bf16 v[24:27], v[234:237], v[144:147], v[24:27]
	v_mfma_f32_16x16x32_bf16 v[20:23], v[214:217], v[152:155], v[20:23]
	v_mfma_f32_16x16x32_bf16 v[16:19], v[234:237], v[152:155], v[16:19]
	v_mfma_f32_16x16x32_bf16 v[12:15], v[214:217], v[198:201], v[12:15]
	v_mfma_f32_16x16x32_bf16 v[8:11], v[234:237], v[198:201], v[8:11]
	v_mfma_f32_16x16x32_bf16 v[4:7], v[214:217], v[206:209], v[4:7]
	v_mfma_f32_16x16x32_bf16 v[0:3], v[234:237], v[206:209], v[0:3]
	v_mfma_f32_16x16x32_bf16 v[28:31], v[230:233], v[148:151], v[28:31]
	s_add_i32 s46, s46, 2
	v_mfma_f32_16x16x32_bf16 v[24:27], v[238:241], v[148:151], v[24:27]
	s_add_u32 s33, s33, 0x100
	v_mfma_f32_16x16x32_bf16 v[20:23], v[230:233], v[194:197], v[20:23]
	s_addc_u32 s45, s45, 0
	v_mfma_f32_16x16x32_bf16 v[16:19], v[238:241], v[194:197], v[16:19]
	s_cmp_gt_u32 s46, 29
	v_mfma_f32_16x16x32_bf16 v[12:15], v[230:233], v[202:205], v[12:15]
	s_mov_b64 s[24:25], s[26:27]
	v_mfma_f32_16x16x32_bf16 v[8:11], v[238:241], v[202:205], v[8:11]
	v_mfma_f32_16x16x32_bf16 v[4:7], v[230:233], v[210:213], v[4:7]
	s_setprio 0
	v_mfma_f32_16x16x32_bf16 v[0:3], v[238:241], v[210:213], v[0:3]
	s_barrier
	s_cbranch_scc0 .LBB0_320
	v_lshl_add_u32 v206, s3, 8, v225
	v_lshl_or_b32 v158, s2, 8, v227
	v_lshlrev_b32_e32 v232, 11, v206
	s_andn2_b64 vcc, exec, s[14:15]
	v_or_b32_e32 v231, 16, v158
	v_add_u32_e32 v194, v232, v158
	v_or_b32_e32 v230, 0x80, v158
	v_or_b32_e32 v229, 0x90, v158
	s_cbranch_vccnz .LBB0_323
	v_lshlrev_b64 v[132:133], 2, v[158:159]
	v_lshl_add_u64 v[140:141], s[16:17], 0, v[132:133]
	global_load_dwordx4 v[128:131], v[140:141], off
	v_lshl_add_u64 v[142:143], s[18:19], 0, v[132:133]
	v_readlane_b32 s2, v253, 8
	v_mov_b32_e32 v195, v159
	v_lshlrev_b32_e32 v136, 1, v206
	v_mov_b32_e32 v137, v159
	v_readlane_b32 s3, v253, 9
	v_lshlrev_b64 v[212:213], 2, v[194:195]
	v_add_u32_e32 v146, v232, v231
	v_lshl_add_u64 v[144:145], v[136:137], 2, s[2:3]
	v_lshl_add_u64 v[136:137], s[88:89], 0, v[212:213]
	v_mov_b32_e32 v147, v159
	v_lshl_add_u64 v[146:147], v[146:147], 2, s[88:89]
	v_or_b32_e32 v195, 16, v206
	v_mov_b32_e32 v201, v159
	v_mov_b32_e32 v209, v159
	v_lshl_add_u64 v[212:213], s[90:91], 0, v[212:213]
	s_waitcnt vmcnt(0)
	v_pk_mul_f32 v[152:153], v[130:131], s[78:79] op_sel_hi:[1,0]
	v_pk_mul_f32 v[154:155], v[128:129], s[78:79] op_sel_hi:[1,0]
	global_load_dwordx4 v[132:135], v[142:143], off
	global_load_dwordx4 v[128:131], v[140:141], off offset:64
	global_load_dwordx2 v[204:205], v[144:145], off
	global_load_dwordx4 v[196:199], v[146:147], off
	v_lshlrev_b32_e32 v146, 1, v195
	global_load_dwordx4 v[136:139], v[136:137], off
	v_lshlrev_b32_e32 v195, 11, v195
	v_mov_b32_e32 v147, v159
	v_add_u32_e32 v200, v195, v158
	v_lshl_add_u64 v[146:147], v[146:147], 2, s[2:3]
	v_lshl_add_u64 v[200:201], v[200:201], 2, s[88:89]
	global_load_dwordx2 v[214:215], v[146:147], off
	v_add_u32_e32 v208, v195, v231
	global_load_dwordx4 v[200:203], v[200:201], off
	v_lshl_add_u64 v[208:209], v[208:209], 2, s[88:89]
	global_load_dwordx4 v[208:211], v[208:209], off
	s_waitcnt vmcnt(0)
	v_pk_mul_f32 v[148:149], v[130:131], s[78:79] op_sel_hi:[1,0]
	v_pk_mul_f32 v[150:151], v[128:129], s[78:79] op_sel_hi:[1,0]
	global_load_dwordx4 v[128:131], v[142:143], off offset:64
	v_sub_f32_e32 v137, v137, v204
	v_sub_f32_e32 v136, v136, v204
	v_sub_f32_e32 v139, v139, v204
	v_sub_f32_e32 v138, v138, v204
	v_pk_mul_f32 v[138:139], v[204:205], v[138:139] op_sel:[1,0]
	v_pk_mul_f32 v[136:137], v[204:205], v[136:137] op_sel:[1,0]
	v_pk_fma_f32 v[138:139], v[152:153], v[138:139], v[126:127]
	v_pk_fma_f32 v[136:137], v[154:155], v[136:137], v[124:125]
	v_pk_fma_f32 v[138:139], v[134:135], s[78:79], v[138:139] op_sel_hi:[1,0,1]
	v_pk_fma_f32 v[136:137], v[132:133], s[78:79], v[136:137] op_sel_hi:[1,0,1]
	global_store_dwordx4 v[212:213], v[136:139], off
	s_nop 1
	v_sub_f32_e32 v137, v197, v204
	v_sub_f32_e32 v136, v196, v204
	v_sub_f32_e32 v139, v199, v204
	v_sub_f32_e32 v138, v198, v204
	v_pk_mul_f32 v[138:139], v[204:205], v[138:139] op_sel:[1,0]
	v_pk_mul_f32 v[136:137], v[204:205], v[136:137] op_sel:[1,0]
	v_pk_fma_f32 v[138:139], v[148:149], v[138:139], v[122:123]
	v_pk_fma_f32 v[136:137], v[150:151], v[136:137], v[120:121]
	v_or_b32_e32 v196, 16, v194
	v_mov_b32_e32 v197, v159
	v_lshl_add_u64 v[196:197], v[196:197], 2, s[90:91]
	s_waitcnt vmcnt(0)
;     template <bool LN, int BJ, int LO, int HI> DI void batch(const f32x4 (&acc)[2][2][4][2], unsigned row0, unsigned col0, const f32x4 (&gv)[2], const f32x4 (&bv)[2]) const {
;         f32x4 r[HI - LO]; float mean[(HI - LO) / 2], rstd[(HI - LO) / 2];
; #pragma unroll
;         for (int i = LO; i < HI; ++i) { const int ai = i >> 3, m = (i >> 1) & 3, n = i & 1; const unsigned row = row0 + ai * HALF + m * 16;
;             if (n == 0) { mean[(i - LO) >> 1] = 0.f; rstd[(i - LO) >> 1] = 1.f;
;                 if (LN) { const float2 st = *(const float2*)(stats + row * 2u); mean[(i - LO) >> 1] = st.x; rstd[(i - LO) >> 1] = st.y; } }
;             r[i - LO] = *(const f32x4*)(src + (row * (unsigned)DM + col0 + BJ * HALF + n * 16)); }
; #pragma unroll
;         for (int i = LO; i < HI; ++i) { const int ai = i >> 3, m = (i >> 1) & 3, n = i & 1; const unsigned row = row0 + ai * HALF + m * 16;
;             *(f32x4*)(Y + (row * (unsigned)DM + col0 + BJ * HALF + n * 16)) = acc[ai][BJ][m][n] + ((r[i - LO] - mean[(i - LO) >> 1]) * rstd[(i - LO) >> 1]) * gv[n] + bv[n]; }
;         __builtin_amdgcn_sched_barrier(0);
;     }
;     template <bool LN, int BJ> DI void load_gb(unsigned col0, f32x4 (&gv)[2], f32x4 (&bv)[2]) const {
; #pragma unroll
;         for (int n = 0; n < 2; ++n) {
;             if (LN) { gv[n] = *(const f32x4*)(gam + col0 + BJ * HALF + n * 16) * ALPHA; bv[n] = *(const f32x4*)(bet + col0 + BJ * HALF + n * 16) * ALPHA; }
;             else { gv[n] = (f32x4){ALPHA, ALPHA, ALPHA, ALPHA}; bv[n] = (f32x4){0.f, 0.f, 0.f, 0.f}; }
;         }
;     }
;     template <bool LN> DI void run(const f32x4 (&acc)[2][2][4][2], const Unit& u, int wr, int wc, int fr, int fq) const {
;         const unsigned row0 = u.pm * BM + wr * 64 + fr, col0 = u.pn * BM + wc * 32 + 4 * fq;
;         f32x4 gv[2], bv[2];
;         load_gb<LN, 0>(col0, gv, bv);
;         batch<LN, 0, 0, 4>(acc, row0, col0, gv, bv);
;         batch<LN, 0, 4, 8>(acc, row0, col0, gv, bv);
	v_pk_fma_f32 v[138:139], v[130:131], s[78:79], v[138:139] op_sel_hi:[1,0,1]
	v_pk_fma_f32 v[136:137], v[128:129], s[78:79], v[136:137] op_sel_hi:[1,0,1]
	global_store_dwordx4 v[196:197], v[136:139], off
	v_add_u32_e32 v196, 0x8000, v194
	v_mov_b32_e32 v197, v159
	v_sub_f32_e32 v137, v201, v214
	v_sub_f32_e32 v136, v200, v214
	v_sub_f32_e32 v139, v203, v214
	v_sub_f32_e32 v138, v202, v214
	v_pk_mul_f32 v[138:139], v[214:215], v[138:139] op_sel:[1,0]
	v_pk_mul_f32 v[136:137], v[214:215], v[136:137] op_sel:[1,0]
	v_pk_fma_f32 v[138:139], v[152:153], v[138:139], v[118:119]
	v_pk_fma_f32 v[136:137], v[154:155], v[136:137], v[116:117]
	v_pk_fma_f32 v[138:139], v[134:135], s[78:79], v[138:139] op_sel_hi:[1,0,1]
	v_pk_fma_f32 v[136:137], v[132:133], s[78:79], v[136:137] op_sel_hi:[1,0,1]
	v_lshl_add_u64 v[196:197], v[196:197], 2, s[90:91]
	global_store_dwordx4 v[196:197], v[136:139], off
	v_add_u32_e32 v196, 0x8010, v194
	v_mov_b32_e32 v197, v159
	v_sub_f32_e32 v137, v209, v214
	v_sub_f32_e32 v136, v208, v214
	v_sub_f32_e32 v139, v211, v214
	v_sub_f32_e32 v138, v210, v214
	v_pk_mul_f32 v[138:139], v[214:215], v[138:139] op_sel:[1,0]
	v_pk_mul_f32 v[136:137], v[214:215], v[136:137] op_sel:[1,0]
	v_pk_fma_f32 v[138:139], v[148:149], v[138:139], v[114:115]
	v_pk_fma_f32 v[136:137], v[150:151], v[136:137], v[112:113]
	v_pk_fma_f32 v[138:139], v[130:131], s[78:79], v[138:139] op_sel_hi:[1,0,1]
	v_pk_fma_f32 v[136:137], v[128:129], s[78:79], v[136:137] op_sel_hi:[1,0,1]
	v_lshl_add_u64 v[196:197], v[196:197], 2, s[90:91]
	global_store_dwordx4 v[196:197], v[136:139], off
	s_nop 1
	v_or_b32_e32 v138, 32, v206
	v_lshlrev_b32_e32 v136, 1, v138
	v_mov_b32_e32 v137, v159
	v_lshlrev_b32_e32 v236, 11, v138
	v_lshl_add_u64 v[200:201], v[136:137], 2, s[2:3]
	v_add_u32_e32 v136, v236, v158
	v_lshl_add_u64 v[136:137], v[136:137], 2, s[88:89]
	global_load_dwordx2 v[204:205], v[200:201], off
	v_add_u32_e32 v196, v236, v231
	global_load_dwordx4 v[136:139], v[136:137], off
	v_mov_b32_e32 v197, v159
	v_lshl_add_u64 v[196:197], v[196:197], 2, s[88:89]
	global_load_dwordx4 v[196:199], v[196:197], off
	v_or_b32_e32 v207, 48, v206
	v_lshlrev_b32_e32 v235, 11, v207
	v_lshlrev_b32_e32 v202, 1, v207
	v_mov_b32_e32 v203, v159
	v_add_u32_e32 v208, v235, v158
	v_mov_b32_e32 v209, v159
	v_lshl_add_u64 v[202:203], v[202:203], 2, s[2:3]
	v_lshl_add_u64 v[208:209], v[208:209], 2, s[88:89]
	global_load_dwordx2 v[216:217], v[202:203], off
	v_add_u32_e32 v212, v235, v231
	global_load_dwordx4 v[208:211], v[208:209], off
	v_mov_b32_e32 v213, v159
	v_lshl_add_u64 v[212:213], v[212:213], 2, s[88:89]
	global_load_dwordx4 v[212:215], v[212:213], off
	v_add_u32_e32 v218, 0x10000, v194
	v_mov_b32_e32 v219, v159
	v_lshl_add_u64 v[218:219], v[218:219], 2, s[90:91]
	s_waitcnt vmcnt(0)
	v_sub_f32_e32 v137, v137, v204
	v_sub_f32_e32 v136, v136, v204
	v_sub_f32_e32 v139, v139, v204
	v_sub_f32_e32 v138, v138, v204
	v_pk_mul_f32 v[138:139], v[204:205], v[138:139] op_sel:[1,0]
	v_pk_mul_f32 v[136:137], v[204:205], v[136:137] op_sel:[1,0]
	v_pk_fma_f32 v[138:139], v[152:153], v[138:139], v[110:111]
	v_pk_fma_f32 v[136:137], v[154:155], v[136:137], v[108:109]
	v_pk_fma_f32 v[138:139], v[134:135], s[78:79], v[138:139] op_sel_hi:[1,0,1]
	v_pk_fma_f32 v[136:137], v[132:133], s[78:79], v[136:137] op_sel_hi:[1,0,1]
	global_store_dwordx4 v[218:219], v[136:139], off
	s_nop 1
	v_sub_f32_e32 v137, v197, v204
	v_sub_f32_e32 v136, v196, v204
	v_sub_f32_e32 v139, v199, v204
	v_sub_f32_e32 v138, v198, v204
	v_pk_mul_f32 v[138:139], v[204:205], v[138:139] op_sel:[1,0]
	v_pk_mul_f32 v[136:137], v[204:205], v[136:137] op_sel:[1,0]
	v_pk_fma_f32 v[138:139], v[148:149], v[138:139], v[106:107]
	v_pk_fma_f32 v[136:137], v[150:151], v[136:137], v[104:105]
	v_add_u32_e32 v196, 0x10010, v194
	v_mov_b32_e32 v197, v159
	v_pk_fma_f32 v[138:139], v[130:131], s[78:79], v[138:139] op_sel_hi:[1,0,1]
	v_pk_fma_f32 v[136:137], v[128:129], s[78:79], v[136:137] op_sel_hi:[1,0,1]
	v_lshl_add_u64 v[196:197], v[196:197], 2, s[90:91]
	global_store_dwordx4 v[196:197], v[136:139], off
	v_add_u32_e32 v196, 0x18000, v194
	v_mov_b32_e32 v197, v159
	v_sub_f32_e32 v137, v209, v216
	v_sub_f32_e32 v136, v208, v216
	v_sub_f32_e32 v139, v211, v216
	v_sub_f32_e32 v138, v210, v216
	v_pk_mul_f32 v[138:139], v[216:217], v[138:139] op_sel:[1,0]
	v_pk_mul_f32 v[136:137], v[216:217], v[136:137] op_sel:[1,0]
	v_pk_fma_f32 v[138:139], v[152:153], v[138:139], v[102:103]
	v_pk_fma_f32 v[136:137], v[154:155], v[136:137], v[100:101]
	v_pk_fma_f32 v[138:139], v[134:135], s[78:79], v[138:139] op_sel_hi:[1,0,1]
	v_pk_fma_f32 v[136:137], v[132:133], s[78:79], v[136:137] op_sel_hi:[1,0,1]
	v_lshl_add_u64 v[196:197], v[196:197], 2, s[90:91]
	global_store_dwordx4 v[196:197], v[136:139], off
	v_add_u32_e32 v196, 0x18010, v194
	v_mov_b32_e32 v197, v159
	v_sub_f32_e32 v137, v213, v216
	v_sub_f32_e32 v136, v212, v216
	v_sub_f32_e32 v139, v215, v216
	v_sub_f32_e32 v138, v214, v216
	v_pk_mul_f32 v[138:139], v[216:217], v[138:139] op_sel:[1,0]
	v_pk_mul_f32 v[136:137], v[216:217], v[136:137] op_sel:[1,0]
	v_pk_fma_f32 v[138:139], v[148:149], v[138:139], v[98:99]
	v_pk_fma_f32 v[136:137], v[150:151], v[136:137], v[96:97]
	v_pk_fma_f32 v[138:139], v[130:131], s[78:79], v[138:139] op_sel_hi:[1,0,1]
	v_pk_fma_f32 v[136:137], v[128:129], s[78:79], v[136:137] op_sel_hi:[1,0,1]
	v_lshl_add_u64 v[196:197], v[196:197], 2, s[90:91]
	global_store_dwordx4 v[196:197], v[136:139], off
	s_nop 1
	v_add_u32_e32 v138, 0x80, v206
	v_lshlrev_b32_e32 v136, 1, v138
	v_mov_b32_e32 v137, v159
	v_lshlrev_b32_e32 v233, 11, v138
	v_lshl_add_u64 v[196:197], v[136:137], 2, s[2:3]
	v_add_u32_e32 v136, v233, v158
	v_lshl_add_u64 v[136:137], v[136:137], 2, s[88:89]
	global_load_dwordx2 v[204:205], v[196:197], off
	v_add_u32_e32 v198, v233, v231
	global_load_dwordx4 v[136:139], v[136:137], off
	v_mov_b32_e32 v199, v159
	v_add_u32_e32 v207, 0x90, v206
	v_lshl_add_u64 v[198:199], v[198:199], 2, s[88:89]
	v_lshlrev_b32_e32 v234, 11, v207
	global_load_dwordx4 v[208:211], v[198:199], off
	v_add_u32_e32 v212, v234, v158
	v_mov_b32_e32 v213, v159
	v_lshl_add_u64 v[212:213], v[212:213], 2, s[88:89]
	global_load_dwordx4 v[212:215], v[212:213], off
	v_lshlrev_b32_e32 v198, 1, v207
	v_mov_b32_e32 v199, v159
	v_lshl_add_u64 v[198:199], v[198:199], 2, s[2:3]
	global_load_dwordx2 v[238:239], v[198:199], off
	v_add_u32_e32 v216, v234, v231
	v_mov_b32_e32 v217, v159
	v_lshl_add_u64 v[216:217], v[216:217], 2, s[88:89]
	global_load_dwordx4 v[216:219], v[216:217], off
	v_add_u32_e32 v240, 0x40000, v194
	v_mov_b32_e32 v241, v159
	v_lshl_add_u64 v[240:241], v[240:241], 2, s[90:91]
	s_waitcnt vmcnt(0)
;     template <bool LN, int BJ, int LO, int HI> DI void batch(const f32x4 (&acc)[2][2][4][2], unsigned row0, unsigned col0, const f32x4 (&gv)[2], const f32x4 (&bv)[2]) const {
;         f32x4 r[HI - LO]; float mean[(HI - LO) / 2], rstd[(HI - LO) / 2];
; #pragma unroll
;         for (int i = LO; i < HI; ++i) { const int ai = i >> 3, m = (i >> 1) & 3, n = i & 1; const unsigned row = row0 + ai * HALF + m * 16;
;             if (n == 0) { mean[(i - LO) >> 1] = 0.f; rstd[(i - LO) >> 1] = 1.f;
;                 if (LN) { const float2 st = *(const float2*)(stats + row * 2u); mean[(i - LO) >> 1] = st.x; rstd[(i - LO) >> 1] = st.y; } }
;             r[i - LO] = *(const f32x4*)(src + (row * (unsigned)DM + col0 + BJ * HALF + n * 16)); }
; #pragma unroll
;         for (int i = LO; i < HI; ++i) { const int ai = i >> 3, m = (i >> 1) & 3, n = i & 1; const unsigned row = row0 + ai * HALF + m * 16;
;             *(f32x4*)(Y + (row * (unsigned)DM + col0 + BJ * HALF + n * 16)) = acc[ai][BJ][m][n] + ((r[i - LO] - mean[(i - LO) >> 1]) * rstd[(i - LO) >> 1]) * gv[n] + bv[n]; }
;         __builtin_amdgcn_sched_barrier(0);
;     }
;     template <bool LN, int BJ> DI void load_gb(unsigned col0, f32x4 (&gv)[2], f32x4 (&bv)[2]) const {
; #pragma unroll
;         for (int n = 0; n < 2; ++n) {
;             if (LN) { gv[n] = *(const f32x4*)(gam + col0 + BJ * HALF + n * 16) * ALPHA; bv[n] = *(const f32x4*)(bet + col0 + BJ * HALF + n * 16) * ALPHA; }
;             else { gv[n] = (f32x4){ALPHA, ALPHA, ALPHA, ALPHA}; bv[n] = (f32x4){0.f, 0.f, 0.f, 0.f}; }
;         }
;     }
;     template <bool LN> DI void run(const f32x4 (&acc)[2][2][4][2], const Unit& u, int wr, int wc, int fr, int fq) const {
;         const unsigned row0 = u.pm * BM + wr * 64 + fr, col0 = u.pn * BM + wc * 32 + 4 * fq;
;         f32x4 gv[2], bv[2];
;         load_gb<LN, 0>(col0, gv, bv);
;         batch<LN, 0, 0, 4>(acc, row0, col0, gv, bv);
;         batch<LN, 0, 4, 8>(acc, row0, col0, gv, bv);
	v_sub_f32_e32 v137, v137, v204
	v_sub_f32_e32 v136, v136, v204
	v_sub_f32_e32 v139, v139, v204
	v_sub_f32_e32 v138, v138, v204
	v_pk_mul_f32 v[138:139], v[204:205], v[138:139] op_sel:[1,0]
	v_pk_mul_f32 v[136:137], v[204:205], v[136:137] op_sel:[1,0]
	v_pk_fma_f32 v[138:139], v[152:153], v[138:139], v[94:95]
	v_pk_fma_f32 v[136:137], v[154:155], v[136:137], v[92:93]
	v_pk_fma_f32 v[138:139], v[134:135], s[78:79], v[138:139] op_sel_hi:[1,0,1]
	v_pk_fma_f32 v[136:137], v[132:133], s[78:79], v[136:137] op_sel_hi:[1,0,1]
	global_store_dwordx4 v[240:241], v[136:139], off
	s_nop 1
	v_sub_f32_e32 v137, v209, v204
	v_sub_f32_e32 v136, v208, v204
	v_sub_f32_e32 v139, v211, v204
	v_sub_f32_e32 v138, v210, v204
	v_pk_mul_f32 v[138:139], v[204:205], v[138:139] op_sel:[1,0]
	v_pk_mul_f32 v[136:137], v[204:205], v[136:137] op_sel:[1,0]
	v_pk_fma_f32 v[138:139], v[148:149], v[138:139], v[90:91]
	v_pk_fma_f32 v[136:137], v[150:151], v[136:137], v[88:89]
	v_add_u32_e32 v204, 0x40010, v194
	v_mov_b32_e32 v205, v159
	v_pk_fma_f32 v[138:139], v[130:131], s[78:79], v[138:139] op_sel_hi:[1,0,1]
	v_pk_fma_f32 v[136:137], v[128:129], s[78:79], v[136:137] op_sel_hi:[1,0,1]
	v_lshl_add_u64 v[204:205], v[204:205], 2, s[90:91]
	global_store_dwordx4 v[204:205], v[136:139], off
	v_add_u32_e32 v204, 0x48000, v194
	v_mov_b32_e32 v205, v159
	v_sub_f32_e32 v137, v213, v238
	v_sub_f32_e32 v136, v212, v238
	v_sub_f32_e32 v139, v215, v238
	v_sub_f32_e32 v138, v214, v238
	v_pk_mul_f32 v[138:139], v[238:239], v[138:139] op_sel:[1,0]
	v_pk_mul_f32 v[136:137], v[238:239], v[136:137] op_sel:[1,0]
	v_pk_fma_f32 v[138:139], v[152:153], v[138:139], v[86:87]
	v_pk_fma_f32 v[136:137], v[154:155], v[136:137], v[84:85]
	v_pk_fma_f32 v[138:139], v[134:135], s[78:79], v[138:139] op_sel_hi:[1,0,1]
	v_pk_fma_f32 v[136:137], v[132:133], s[78:79], v[136:137] op_sel_hi:[1,0,1]
	v_lshl_add_u64 v[204:205], v[204:205], 2, s[90:91]
	global_store_dwordx4 v[204:205], v[136:139], off
	v_add_u32_e32 v204, 0x48010, v194
	v_mov_b32_e32 v205, v159
	v_sub_f32_e32 v137, v217, v238
	v_sub_f32_e32 v136, v216, v238
	v_sub_f32_e32 v139, v219, v238
	v_sub_f32_e32 v138, v218, v238
	v_pk_mul_f32 v[138:139], v[238:239], v[138:139] op_sel:[1,0]
	v_pk_mul_f32 v[136:137], v[238:239], v[136:137] op_sel:[1,0]
	v_pk_fma_f32 v[138:139], v[148:149], v[138:139], v[82:83]
	v_pk_fma_f32 v[136:137], v[150:151], v[136:137], v[80:81]
	v_pk_fma_f32 v[138:139], v[130:131], s[78:79], v[138:139] op_sel_hi:[1,0,1]
	v_pk_fma_f32 v[136:137], v[128:129], s[78:79], v[136:137] op_sel_hi:[1,0,1]
	v_lshl_add_u64 v[204:205], v[204:205], 2, s[90:91]
	global_store_dwordx4 v[204:205], v[136:139], off
	s_nop 1
	v_add_u32_e32 v138, 0xa0, v206
	v_lshlrev_b32_e32 v136, 1, v138
	v_mov_b32_e32 v137, v159
	v_lshlrev_b32_e32 v237, 11, v138
	v_lshl_add_u64 v[204:205], v[136:137], 2, s[2:3]
	v_add_u32_e32 v136, v237, v158
	v_lshl_add_u64 v[136:137], v[136:137], 2, s[88:89]
	global_load_dwordx2 v[240:241], v[204:205], off
	v_add_u32_e32 v208, v237, v231
	global_load_dwordx4 v[136:139], v[136:137], off
	v_mov_b32_e32 v209, v159
	v_lshl_add_u64 v[208:209], v[208:209], 2, s[88:89]
	global_load_dwordx4 v[212:215], v[208:209], off
	v_add_u32_e32 v208, 0xb0, v206
	v_lshlrev_b32_e32 v206, 1, v208
	v_mov_b32_e32 v207, v159
	v_lshlrev_b32_e32 v238, 11, v208
	v_lshl_add_u64 v[210:211], v[206:207], 2, s[2:3]
	v_add_u32_e32 v206, v238, v158
	v_lshl_add_u64 v[206:207], v[206:207], 2, s[88:89]
	global_load_dwordx2 v[242:243], v[210:211], off
	v_add_u32_e32 v216, v238, v231
	global_load_dwordx4 v[206:209], v[206:207], off
	v_mov_b32_e32 v217, v159
	v_lshl_add_u64 v[216:217], v[216:217], 2, s[88:89]
	global_load_dwordx4 v[216:219], v[216:217], off
	v_add_u32_e32 v244, 0x50000, v194
	v_mov_b32_e32 v245, v159
	v_lshl_add_u64 v[244:245], v[244:245], 2, s[90:91]
	s_waitcnt vmcnt(0)
	v_sub_f32_e32 v137, v137, v240
	v_sub_f32_e32 v136, v136, v240
	v_sub_f32_e32 v139, v139, v240
	v_sub_f32_e32 v138, v138, v240
	v_pk_mul_f32 v[138:139], v[240:241], v[138:139] op_sel:[1,0]
	v_pk_mul_f32 v[136:137], v[240:241], v[136:137] op_sel:[1,0]
	v_pk_fma_f32 v[138:139], v[152:153], v[138:139], v[78:79]
	v_pk_fma_f32 v[136:137], v[154:155], v[136:137], v[76:77]
	v_pk_fma_f32 v[138:139], v[134:135], s[78:79], v[138:139] op_sel_hi:[1,0,1]
	v_pk_fma_f32 v[136:137], v[132:133], s[78:79], v[136:137] op_sel_hi:[1,0,1]
	global_store_dwordx4 v[244:245], v[136:139], off
	s_nop 1
	v_sub_f32_e32 v137, v213, v240
	v_sub_f32_e32 v136, v212, v240
	v_sub_f32_e32 v139, v215, v240
	v_sub_f32_e32 v138, v214, v240
	v_pk_mul_f32 v[138:139], v[240:241], v[138:139] op_sel:[1,0]
	v_pk_mul_f32 v[136:137], v[240:241], v[136:137] op_sel:[1,0]
	v_pk_fma_f32 v[138:139], v[148:149], v[138:139], v[74:75]
	v_pk_fma_f32 v[136:137], v[150:151], v[136:137], v[72:73]
	v_add_u32_e32 v212, 0x50010, v194
	v_mov_b32_e32 v213, v159
	v_pk_fma_f32 v[138:139], v[130:131], s[78:79], v[138:139] op_sel_hi:[1,0,1]
	v_pk_fma_f32 v[136:137], v[128:129], s[78:79], v[136:137] op_sel_hi:[1,0,1]
	v_lshl_add_u64 v[212:213], v[212:213], 2, s[90:91]
	global_store_dwordx4 v[212:213], v[136:139], off
	s_nop 1
	v_sub_f32_e32 v137, v207, v242
	v_sub_f32_e32 v136, v206, v242
	v_sub_f32_e32 v139, v209, v242
	v_sub_f32_e32 v138, v208, v242
	v_pk_mul_f32 v[136:137], v[242:243], v[136:137] op_sel:[1,0]
	v_pk_mul_f32 v[138:139], v[242:243], v[138:139] op_sel:[1,0]
	v_pk_fma_f32 v[136:137], v[154:155], v[136:137], v[68:69]
	v_pk_fma_f32 v[138:139], v[152:153], v[138:139], v[70:71]
	v_pk_fma_f32 v[132:133], v[132:133], s[78:79], v[136:137] op_sel_hi:[1,0,1]
	v_add_u32_e32 v136, 0x58000, v194
	v_mov_b32_e32 v137, v159
	v_pk_fma_f32 v[134:135], v[134:135], s[78:79], v[138:139] op_sel_hi:[1,0,1]
	v_lshl_add_u64 v[136:137], v[136:137], 2, s[90:91]
	global_store_dwordx4 v[136:137], v[132:135], off
	s_nop 1
	v_sub_f32_e32 v133, v217, v242
	v_sub_f32_e32 v132, v216, v242
	v_sub_f32_e32 v135, v219, v242
	v_sub_f32_e32 v134, v218, v242
	v_pk_mul_f32 v[132:133], v[242:243], v[132:133] op_sel:[1,0]
	v_pk_mul_f32 v[134:135], v[242:243], v[134:135] op_sel:[1,0]
	v_pk_fma_f32 v[132:133], v[150:151], v[132:133], v[64:65]
	v_pk_fma_f32 v[134:135], v[148:149], v[134:135], v[66:67]
	v_pk_fma_f32 v[128:129], v[128:129], s[78:79], v[132:133] op_sel_hi:[1,0,1]
	v_add_u32_e32 v132, 0x58010, v194
	v_mov_b32_e32 v133, v159
	v_pk_fma_f32 v[130:131], v[130:131], s[78:79], v[134:135] op_sel_hi:[1,0,1]
	v_lshl_add_u64 v[132:133], v[132:133], 2, s[90:91]
	global_store_dwordx4 v[132:133], v[128:131], off
	global_load_dwordx4 v[128:131], v[140:141], off offset:512
	v_add_u32_e32 v136, v232, v230
	v_mov_b32_e32 v137, v159
	v_lshl_add_u64 v[136:137], v[136:137], 2, s[88:89]
	s_waitcnt vmcnt(0)
;     template <bool LN, int BJ> DI void load_gb(unsigned col0, f32x4 (&gv)[2], f32x4 (&bv)[2]) const {
; #pragma unroll
;         for (int n = 0; n < 2; ++n) {
;             if (LN) { gv[n] = *(const f32x4*)(gam + col0 + BJ * HALF + n * 16) * ALPHA; bv[n] = *(const f32x4*)(bet + col0 + BJ * HALF + n * 16) * ALPHA; }
;             else { gv[n] = (f32x4){ALPHA, ALPHA, ALPHA, ALPHA}; bv[n] = (f32x4){0.f, 0.f, 0.f, 0.f}; }
;         }
;     }
;     template <bool LN> DI void run(const f32x4 (&acc)[2][2][4][2], const Unit& u, int wr, int wc, int fr, int fq) const {
;         const unsigned row0 = u.pm * BM + wr * 64 + fr, col0 = u.pn * BM + wc * 32 + 4 * fq;
;         f32x4 gv[2], bv[2];
;         load_gb<LN, 0>(col0, gv, bv);
;         batch<LN, 0, 0, 4>(acc, row0, col0, gv, bv);
;         batch<LN, 0, 4, 8>(acc, row0, col0, gv, bv);
	v_pk_mul_f32 v[212:213], v[130:131], s[78:79] op_sel_hi:[1,0]
	v_pk_mul_f32 v[214:215], v[128:129], s[78:79] op_sel_hi:[1,0]
	global_load_dwordx4 v[132:135], v[142:143], off offset:512
	global_load_dwordx4 v[128:131], v[140:141], off offset:576
	s_waitcnt vmcnt(0)
	v_pk_mul_f32 v[206:207], v[130:131], s[78:79] op_sel_hi:[1,0]
	v_pk_mul_f32 v[208:209], v[128:129], s[78:79] op_sel_hi:[1,0]
	global_load_dwordx4 v[128:131], v[142:143], off offset:576
	global_load_dwordx2 v[220:221], v[144:145], off
	global_load_dwordx4 v[240:243], v[136:137], off
	v_add_u32_e32 v136, v232, v229
	v_mov_b32_e32 v137, v159
	v_lshl_add_u64 v[136:137], v[136:137], 2, s[88:89]
	global_load_dwordx4 v[244:247], v[136:137], off
	global_load_dwordx2 v[218:219], v[146:147], off
	v_add_u32_e32 v136, v195, v230
	v_mov_b32_e32 v137, v159
	v_lshl_add_u64 v[136:137], v[136:137], 2, s[88:89]
	global_load_dwordx4 v[248:251], v[136:137], off
	v_add_u32_e32 v136, v195, v229
	v_mov_b32_e32 v137, v159
	v_lshl_add_u64 v[136:137], v[136:137], 2, s[88:89]
	global_load_dwordx4 v[152:155], v[136:137], off
	global_load_dwordx2 v[216:217], v[200:201], off
	v_add_u32_e32 v136, v236, v230
	v_mov_b32_e32 v137, v159
	v_lshl_add_u64 v[136:137], v[136:137], 2, s[88:89]
	global_load_dwordx4 v[148:151], v[136:137], off
	v_add_u32_e32 v136, v236, v229
	v_mov_b32_e32 v137, v159
	v_lshl_add_u64 v[136:137], v[136:137], 2, s[88:89]
	global_load_dwordx4 v[144:147], v[136:137], off
	global_load_dwordx2 v[200:201], v[202:203], off
	v_add_u32_e32 v136, v235, v230
	v_mov_b32_e32 v137, v159
	v_lshl_add_u64 v[136:137], v[136:137], 2, s[88:89]
	global_load_dwordx4 v[140:143], v[136:137], off
	v_add_u32_e32 v136, v235, v229
	v_mov_b32_e32 v137, v159
	v_lshl_add_u64 v[136:137], v[136:137], 2, s[88:89]
	global_load_dwordx4 v[136:139], v[136:137], off
	v_add_u32_e32 v202, 0x80, v194
	v_mov_b32_e32 v203, v159
	v_lshl_add_u64 v[202:203], v[202:203], 2, s[90:91]
	s_waitcnt vmcnt(0)
	v_sub_f32_e32 v241, v241, v220
	v_sub_f32_e32 v240, v240, v220
	v_sub_f32_e32 v243, v243, v220
	v_sub_f32_e32 v242, v242, v220
	v_pk_mul_f32 v[242:243], v[220:221], v[242:243] op_sel:[1,0]
	v_pk_mul_f32 v[240:241], v[220:221], v[240:241] op_sel:[1,0]
	v_pk_fma_f32 v[242:243], v[212:213], v[242:243], v[62:63]
	v_pk_fma_f32 v[240:241], v[214:215], v[240:241], v[60:61]
	v_pk_fma_f32 v[242:243], v[134:135], s[78:79], v[242:243] op_sel_hi:[1,0,1]
	v_pk_fma_f32 v[240:241], v[132:133], s[78:79], v[240:241] op_sel_hi:[1,0,1]
	global_store_dwordx4 v[202:203], v[240:243], off
	v_sub_f32_e32 v203, v245, v220
	v_sub_f32_e32 v202, v244, v220
	v_sub_f32_e32 v241, v247, v220
	v_sub_f32_e32 v240, v246, v220
	v_pk_mul_f32 v[202:203], v[220:221], v[202:203] op_sel:[1,0]
	v_pk_mul_f32 v[240:241], v[220:221], v[240:241] op_sel:[1,0]
	v_pk_fma_f32 v[202:203], v[208:209], v[202:203], v[56:57]
	v_pk_fma_f32 v[220:221], v[206:207], v[240:241], v[58:59]
	v_pk_fma_f32 v[240:241], v[128:129], s[78:79], v[202:203] op_sel_hi:[1,0,1]
	v_add_u32_e32 v202, 0x90, v194
	v_mov_b32_e32 v203, v159
	v_pk_fma_f32 v[242:243], v[130:131], s[78:79], v[220:221] op_sel_hi:[1,0,1]
	v_lshl_add_u64 v[202:203], v[202:203], 2, s[90:91]
	global_store_dwordx4 v[202:203], v[240:243], off
	v_sub_f32_e32 v203, v249, v218
	v_sub_f32_e32 v202, v248, v218
	v_sub_f32_e32 v221, v251, v218
	v_sub_f32_e32 v220, v250, v218
	v_pk_mul_f32 v[202:203], v[218:219], v[202:203] op_sel:[1,0]
	v_pk_mul_f32 v[220:221], v[218:219], v[220:221] op_sel:[1,0]
	v_pk_fma_f32 v[202:203], v[214:215], v[202:203], v[52:53]
	v_pk_fma_f32 v[220:221], v[212:213], v[220:221], v[54:55]
	v_pk_fma_f32 v[240:241], v[132:133], s[78:79], v[202:203] op_sel_hi:[1,0,1]
	v_add_u32_e32 v202, 0x8080, v194
	v_mov_b32_e32 v203, v159
	v_sub_f32_e32 v153, v153, v218
	v_sub_f32_e32 v152, v152, v218
	v_sub_f32_e32 v155, v155, v218
	v_sub_f32_e32 v154, v154, v218
	v_pk_fma_f32 v[242:243], v[134:135], s[78:79], v[220:221] op_sel_hi:[1,0,1]
	v_lshl_add_u64 v[202:203], v[202:203], 2, s[90:91]
	v_pk_mul_f32 v[154:155], v[218:219], v[154:155] op_sel:[1,0]
	v_pk_mul_f32 v[152:153], v[218:219], v[152:153] op_sel:[1,0]
	global_store_dwordx4 v[202:203], v[240:243], off
	v_pk_fma_f32 v[152:153], v[208:209], v[152:153], v[48:49]
	v_pk_fma_f32 v[154:155], v[206:207], v[154:155], v[50:51]
	v_add_u32_e32 v202, 0x8090, v194
	v_mov_b32_e32 v203, v159
	v_sub_f32_e32 v149, v149, v216
	v_sub_f32_e32 v148, v148, v216
	v_sub_f32_e32 v151, v151, v216
	v_sub_f32_e32 v150, v150, v216
	v_pk_fma_f32 v[154:155], v[130:131], s[78:79], v[154:155] op_sel_hi:[1,0,1]
	v_pk_fma_f32 v[152:153], v[128:129], s[78:79], v[152:153] op_sel_hi:[1,0,1]
	v_lshl_add_u64 v[202:203], v[202:203], 2, s[90:91]
	v_pk_mul_f32 v[150:151], v[216:217], v[150:151] op_sel:[1,0]
	v_pk_mul_f32 v[148:149], v[216:217], v[148:149] op_sel:[1,0]
	global_store_dwordx4 v[202:203], v[152:155], off
	v_pk_fma_f32 v[148:149], v[214:215], v[148:149], v[44:45]
	v_pk_fma_f32 v[150:151], v[212:213], v[150:151], v[46:47]
	v_add_u32_e32 v152, 0x10080, v194
	v_mov_b32_e32 v153, v159
	v_sub_f32_e32 v145, v145, v216
	v_sub_f32_e32 v144, v144, v216
	v_sub_f32_e32 v147, v147, v216
	v_sub_f32_e32 v146, v146, v216
	v_pk_fma_f32 v[150:151], v[134:135], s[78:79], v[150:151] op_sel_hi:[1,0,1]
	v_pk_fma_f32 v[148:149], v[132:133], s[78:79], v[148:149] op_sel_hi:[1,0,1]
	v_lshl_add_u64 v[152:153], v[152:153], 2, s[90:91]
	v_pk_mul_f32 v[146:147], v[216:217], v[146:147] op_sel:[1,0]
	v_pk_mul_f32 v[144:145], v[216:217], v[144:145] op_sel:[1,0]
	global_store_dwordx4 v[152:153], v[148:151], off
	v_pk_fma_f32 v[144:145], v[208:209], v[144:145], v[40:41]
	v_pk_fma_f32 v[146:147], v[206:207], v[146:147], v[42:43]
;     template <bool LN, int BJ, int LO, int HI> DI void batch(const f32x4 (&acc)[2][2][4][2], unsigned row0, unsigned col0, const f32x4 (&gv)[2], const f32x4 (&bv)[2]) const {
;     ...
;         for (int i = LO; i < HI; ++i) { const int ai = i >> 3, m = (i >> 1) & 3, n = i & 1; const unsigned row = row0 + ai * HALF + m * 16;
;             if (n == 0) { mean[(i - LO) >> 1] = 0.f; rstd[(i - LO) >> 1] = 1.f;
;                 if (LN) { const float2 st = *(const float2*)(stats + row * 2u); mean[(i - LO) >> 1] = st.x; rstd[(i - LO) >> 1] = st.y; } }
;             r[i - LO] = *(const f32x4*)(src + (row * (unsigned)DM + col0 + BJ * HALF + n * 16)); }
; #pragma unroll
;         for (int i = LO; i < HI; ++i) { const int ai = i >> 3, m = (i >> 1) & 3, n = i & 1; const unsigned row = row0 + ai * HALF + m * 16;
;             *(f32x4*)(Y + (row * (unsigned)DM + col0 + BJ * HALF + n * 16)) = acc[ai][BJ][m][n] + ((r[i - LO] - mean[(i - LO) >> 1]) * rstd[(i - LO) >> 1]) * gv[n] + bv[n]; }
	v_add_u32_e32 v148, 0x10090, v194
	v_mov_b32_e32 v149, v159
	v_sub_f32_e32 v141, v141, v200
	v_sub_f32_e32 v140, v140, v200
	v_sub_f32_e32 v143, v143, v200
	v_sub_f32_e32 v142, v142, v200
	v_pk_fma_f32 v[146:147], v[130:131], s[78:79], v[146:147] op_sel_hi:[1,0,1]
	v_pk_fma_f32 v[144:145], v[128:129], s[78:79], v[144:145] op_sel_hi:[1,0,1]
	v_lshl_add_u64 v[148:149], v[148:149], 2, s[90:91]
	v_pk_mul_f32 v[142:143], v[200:201], v[142:143] op_sel:[1,0]
	v_pk_mul_f32 v[140:141], v[200:201], v[140:141] op_sel:[1,0]
	global_store_dwordx4 v[148:149], v[144:147], off
	v_pk_fma_f32 v[140:141], v[214:215], v[140:141], v[36:37]
	v_pk_fma_f32 v[142:143], v[212:213], v[142:143], v[38:39]
	v_add_u32_e32 v144, 0x18080, v194
	v_mov_b32_e32 v145, v159
	v_sub_f32_e32 v137, v137, v200
	v_sub_f32_e32 v136, v136, v200
	v_sub_f32_e32 v139, v139, v200
	v_sub_f32_e32 v138, v138, v200
	v_pk_fma_f32 v[142:143], v[134:135], s[78:79], v[142:143] op_sel_hi:[1,0,1]
	v_pk_fma_f32 v[140:141], v[132:133], s[78:79], v[140:141] op_sel_hi:[1,0,1]
	v_lshl_add_u64 v[144:145], v[144:145], 2, s[90:91]
	v_pk_mul_f32 v[138:139], v[200:201], v[138:139] op_sel:[1,0]
	v_pk_mul_f32 v[136:137], v[200:201], v[136:137] op_sel:[1,0]
	global_store_dwordx4 v[144:145], v[140:143], off
	v_pk_fma_f32 v[136:137], v[208:209], v[136:137], v[32:33]
	v_pk_fma_f32 v[138:139], v[206:207], v[138:139], v[34:35]
	v_add_u32_e32 v140, 0x18090, v194
	v_mov_b32_e32 v141, v159
	v_pk_fma_f32 v[138:139], v[130:131], s[78:79], v[138:139] op_sel_hi:[1,0,1]
	v_pk_fma_f32 v[136:137], v[128:129], s[78:79], v[136:137] op_sel_hi:[1,0,1]
	v_lshl_add_u64 v[140:141], v[140:141], 2, s[90:91]
	global_store_dwordx4 v[140:141], v[136:139], off
	s_nop 1
	v_add_u32_e32 v136, v233, v230
	v_mov_b32_e32 v137, v159
	v_lshl_add_u64 v[136:137], v[136:137], 2, s[88:89]
	global_load_dwordx2 v[220:221], v[196:197], off
	global_load_dwordx4 v[216:219], v[136:137], off
	v_add_u32_e32 v136, v233, v229
	v_mov_b32_e32 v137, v159
	v_lshl_add_u64 v[136:137], v[136:137], 2, s[88:89]
	global_load_dwordx4 v[240:243], v[136:137], off
	global_load_dwordx2 v[200:201], v[198:199], off
	v_add_u32_e32 v136, v234, v230
	v_mov_b32_e32 v137, v159
	v_lshl_add_u64 v[136:137], v[136:137], 2, s[88:89]
	global_load_dwordx4 v[244:247], v[136:137], off
	v_add_u32_e32 v136, v234, v229
	v_mov_b32_e32 v137, v159
	v_lshl_add_u64 v[136:137], v[136:137], 2, s[88:89]
	global_load_dwordx4 v[152:155], v[136:137], off
	global_load_dwordx2 v[198:199], v[204:205], off
	v_add_u32_e32 v136, v237, v230
	v_mov_b32_e32 v137, v159
	v_lshl_add_u64 v[136:137], v[136:137], 2, s[88:89]
	global_load_dwordx4 v[148:151], v[136:137], off
	v_add_u32_e32 v136, v237, v229
	v_mov_b32_e32 v137, v159
	v_lshl_add_u64 v[136:137], v[136:137], 2, s[88:89]
	global_load_dwordx4 v[144:147], v[136:137], off
	global_load_dwordx2 v[196:197], v[210:211], off
	v_add_u32_e32 v136, v238, v230
	v_mov_b32_e32 v137, v159
	v_lshl_add_u64 v[136:137], v[136:137], 2, s[88:89]
	global_load_dwordx4 v[140:143], v[136:137], off
	v_add_u32_e32 v136, v238, v229
	v_mov_b32_e32 v137, v159
	v_lshl_add_u64 v[136:137], v[136:137], 2, s[88:89]
	global_load_dwordx4 v[136:139], v[136:137], off
	v_add_u32_e32 v210, 0x40080, v194
	v_mov_b32_e32 v211, v159
	v_lshl_add_u64 v[210:211], v[210:211], 2, s[90:91]
	s_waitcnt vmcnt(0)
;     template <bool LN, int BJ, int LO, int HI> DI void batch(const f32x4 (&acc)[2][2][4][2], unsigned row0, unsigned col0, const f32x4 (&gv)[2], const f32x4 (&bv)[2]) const {
;     ...
;         for (int i = LO; i < HI; ++i) { const int ai = i >> 3, m = (i >> 1) & 3, n = i & 1; const unsigned row = row0 + ai * HALF + m * 16;
;             if (n == 0) { mean[(i - LO) >> 1] = 0.f; rstd[(i - LO) >> 1] = 1.f;
;                 if (LN) { const float2 st = *(const float2*)(stats + row * 2u); mean[(i - LO) >> 1] = st.x; rstd[(i - LO) >> 1] = st.y; } }
;             r[i - LO] = *(const f32x4*)(src + (row * (unsigned)DM + col0 + BJ * HALF + n * 16)); }
; #pragma unroll
;         for (int i = LO; i < HI; ++i) { const int ai = i >> 3, m = (i >> 1) & 3, n = i & 1; const unsigned row = row0 + ai * HALF + m * 16;
;             *(f32x4*)(Y + (row * (unsigned)DM + col0 + BJ * HALF + n * 16)) = acc[ai][BJ][m][n] + ((r[i - LO] - mean[(i - LO) >> 1]) * rstd[(i - LO) >> 1]) * gv[n] + bv[n]; }
	v_sub_f32_e32 v203, v217, v220
	v_sub_f32_e32 v202, v216, v220
	v_sub_f32_e32 v205, v219, v220
	v_sub_f32_e32 v204, v218, v220
	v_pk_mul_f32 v[204:205], v[220:221], v[204:205] op_sel:[1,0]
	v_pk_mul_f32 v[202:203], v[220:221], v[202:203] op_sel:[1,0]
	v_pk_fma_f32 v[204:205], v[212:213], v[204:205], v[30:31]
	v_pk_fma_f32 v[202:203], v[214:215], v[202:203], v[28:29]
	v_pk_fma_f32 v[204:205], v[134:135], s[78:79], v[204:205] op_sel_hi:[1,0,1]
	v_pk_fma_f32 v[202:203], v[132:133], s[78:79], v[202:203] op_sel_hi:[1,0,1]
	global_store_dwordx4 v[210:211], v[202:205], off
	v_add_u32_e32 v210, 0x40090, v194
	v_mov_b32_e32 v211, v159
	v_sub_f32_e32 v203, v241, v220
	v_sub_f32_e32 v202, v240, v220
	v_sub_f32_e32 v205, v243, v220
	v_sub_f32_e32 v204, v242, v220
	v_pk_mul_f32 v[204:205], v[220:221], v[204:205] op_sel:[1,0]
	v_pk_mul_f32 v[202:203], v[220:221], v[202:203] op_sel:[1,0]
	v_pk_fma_f32 v[204:205], v[206:207], v[204:205], v[26:27]
	v_pk_fma_f32 v[202:203], v[208:209], v[202:203], v[24:25]
	v_pk_fma_f32 v[204:205], v[130:131], s[78:79], v[204:205] op_sel_hi:[1,0,1]
	v_pk_fma_f32 v[202:203], v[128:129], s[78:79], v[202:203] op_sel_hi:[1,0,1]
	v_lshl_add_u64 v[210:211], v[210:211], 2, s[90:91]
	global_store_dwordx4 v[210:211], v[202:205], off
	v_sub_f32_e32 v149, v149, v198
	v_sub_f32_e32 v148, v148, v198
	v_sub_f32_e32 v203, v245, v200
	v_sub_f32_e32 v202, v244, v200
	v_sub_f32_e32 v141, v141, v196
	v_sub_f32_e32 v140, v140, v196
	v_sub_f32_e32 v205, v247, v200
	v_sub_f32_e32 v204, v246, v200
	v_pk_mul_f32 v[202:203], v[200:201], v[202:203] op_sel:[1,0]
	v_sub_f32_e32 v151, v151, v198
	v_sub_f32_e32 v150, v150, v198
	v_pk_mul_f32 v[148:149], v[198:199], v[148:149] op_sel:[1,0]
	v_sub_f32_e32 v143, v143, v196
	v_sub_f32_e32 v142, v142, v196
	v_pk_mul_f32 v[140:141], v[196:197], v[140:141] op_sel:[1,0]
	v_pk_mul_f32 v[204:205], v[200:201], v[204:205] op_sel:[1,0]
	v_pk_fma_f32 v[202:203], v[214:215], v[202:203], v[20:21]
	v_sub_f32_e32 v153, v153, v200
	v_sub_f32_e32 v152, v152, v200
	v_sub_f32_e32 v155, v155, v200
	v_sub_f32_e32 v154, v154, v200
	v_pk_mul_f32 v[150:151], v[198:199], v[150:151] op_sel:[1,0]
	v_pk_fma_f32 v[148:149], v[214:215], v[148:149], v[12:13]
	v_pk_mul_f32 v[142:143], v[196:197], v[142:143] op_sel:[1,0]
	v_pk_fma_f32 v[140:141], v[214:215], v[140:141], v[4:5]
	v_pk_fma_f32 v[204:205], v[212:213], v[204:205], v[22:23]
	v_pk_fma_f32 v[202:203], v[132:133], s[78:79], v[202:203] op_sel_hi:[1,0,1]
	v_pk_mul_f32 v[154:155], v[200:201], v[154:155] op_sel:[1,0]
	v_pk_mul_f32 v[152:153], v[200:201], v[152:153] op_sel:[1,0]
	v_pk_fma_f32 v[150:151], v[212:213], v[150:151], v[14:15]
	v_pk_fma_f32 v[148:149], v[132:133], s[78:79], v[148:149] op_sel_hi:[1,0,1]
	v_pk_fma_f32 v[142:143], v[212:213], v[142:143], v[6:7]
	v_pk_fma_f32 v[132:133], v[132:133], s[78:79], v[140:141] op_sel_hi:[1,0,1]
	v_add_u32_e32 v140, 0x58080, v194
	v_mov_b32_e32 v141, v159
	v_pk_fma_f32 v[204:205], v[134:135], s[78:79], v[204:205] op_sel_hi:[1,0,1]
	v_pk_fma_f32 v[152:153], v[208:209], v[152:153], v[16:17]
	v_pk_fma_f32 v[154:155], v[206:207], v[154:155], v[18:19]
	v_add_u32_e32 v200, 0x48090, v194
	v_mov_b32_e32 v201, v159
	v_pk_fma_f32 v[150:151], v[134:135], s[78:79], v[150:151] op_sel_hi:[1,0,1]
	v_pk_fma_f32 v[134:135], v[134:135], s[78:79], v[142:143] op_sel_hi:[1,0,1]
	v_lshl_add_u64 v[140:141], v[140:141], 2, s[90:91]
	v_pk_fma_f32 v[154:155], v[130:131], s[78:79], v[154:155] op_sel_hi:[1,0,1]
	v_pk_fma_f32 v[152:153], v[128:129], s[78:79], v[152:153] op_sel_hi:[1,0,1]
	v_lshl_add_u64 v[200:201], v[200:201], 2, s[90:91]
	v_sub_f32_e32 v145, v145, v198
	v_sub_f32_e32 v144, v144, v198
	global_store_dwordx4 v[140:141], v[132:135], off
	global_store_dwordx4 v[200:201], v[152:155], off
	v_sub_f32_e32 v147, v147, v198
	v_sub_f32_e32 v133, v137, v196
	v_sub_f32_e32 v132, v136, v196
	v_add_u32_e32 v152, 0x50080, v194
	v_mov_b32_e32 v153, v159
	v_sub_f32_e32 v146, v146, v198
	v_pk_mul_f32 v[144:145], v[198:199], v[144:145] op_sel:[1,0]
	v_sub_f32_e32 v135, v139, v196
	v_sub_f32_e32 v134, v138, v196
	v_pk_mul_f32 v[132:133], v[196:197], v[132:133] op_sel:[1,0]
	v_lshl_add_u64 v[152:153], v[152:153], 2, s[90:91]
	v_pk_mul_f32 v[146:147], v[198:199], v[146:147] op_sel:[1,0]
	v_pk_fma_f32 v[144:145], v[208:209], v[144:145], v[8:9]
	v_pk_mul_f32 v[134:135], v[196:197], v[134:135] op_sel:[1,0]
	v_pk_fma_f32 v[132:133], v[208:209], v[132:133], v[0:1]
	v_add_u32_e32 v210, 0x48080, v194
	v_mov_b32_e32 v211, v159
	global_store_dwordx4 v[152:153], v[148:151], off
	v_pk_fma_f32 v[146:147], v[206:207], v[146:147], v[10:11]
	v_pk_fma_f32 v[144:145], v[128:129], s[78:79], v[144:145] op_sel_hi:[1,0,1]
	v_add_u32_e32 v148, 0x50090, v194
	v_mov_b32_e32 v149, v159
	v_pk_fma_f32 v[134:135], v[206:207], v[134:135], v[2:3]
	v_pk_fma_f32 v[128:129], v[128:129], s[78:79], v[132:133] op_sel_hi:[1,0,1]
	v_add_u32_e32 v132, 0x58090, v194
	v_mov_b32_e32 v133, v159
	v_lshl_add_u64 v[210:211], v[210:211], 2, s[90:91]
	v_pk_fma_f32 v[146:147], v[130:131], s[78:79], v[146:147] op_sel_hi:[1,0,1]
	v_lshl_add_u64 v[148:149], v[148:149], 2, s[90:91]
	v_pk_fma_f32 v[130:131], v[130:131], s[78:79], v[134:135] op_sel_hi:[1,0,1]
	v_lshl_add_u64 v[132:133], v[132:133], 2, s[90:91]
	global_store_dwordx4 v[210:211], v[202:205], off
	global_store_dwordx4 v[148:149], v[144:147], off
	global_store_dwordx4 v[132:133], v[128:131], off
	s_mov_b64 s[24:25], 0
	s_branch .LBB0_324
